# GEMM loops: the two K-half MFMAs of each accumulator issued back to back (accumulate chain), on top of the saddr DMA version
# speedup vs baseline: 1.0113x; 1.0079x over previous
; #define PG8_STAGE(bufoff, gbase, voff) do { _Pragma("unroll") for (int _i = 0; _i < 2; ++_i) \
;         __builtin_amdgcn_global_load_lds((const unsigned*)((const char*)(gbase) + (voff)[_i]), (LAS unsigned*)(lds + (bufoff) + ldsw + _i * 8192), 16, 0, 0); } while (0)
; #define PG8_LDA(dst, b, h) do { _Pragma("unroll") for (int m = 0; m < 4; ++m) _Pragma("unroll") for (int k = 0; k < 2; ++k) dst[m][k] = *(const LAS bf16x8*)(lds + PG8_SA(b, h) + aoff + m * 2048 + k * 1024); } while (0)
; #define PG8_LDB(dst, b, h) do { _Pragma("unroll") for (int n = 0; n < 2; ++n) _Pragma("unroll") for (int k = 0; k < 2; ++k) dst[n][k] = *(const LAS bf16x8*)(lds + PG8_SB(b, h) + boff + n * 2048 + k * 1024); } while (0)
; #define PG8_MMA(ai, bj, At, Bt) do { __builtin_amdgcn_s_setprio(1); _Pragma("unroll") for (int m = 0; m < 4; ++m) _Pragma("unroll") for (int n = 0; n < 2; ++n) _Pragma("unroll") for (int k = 0; k < 2; ++k) \
;         acc[ai][bj][m][n] = __builtin_amdgcn_mfma_f32_16x16x32_bf16(Bt[n][k], At[m][k], acc[ai][bj][m][n], 0, 0, 0); __builtin_amdgcn_s_setprio(0); } while (0)
; #define PG8_WAIT_V(n) asm volatile("s_waitcnt vmcnt(" #n ")" ::: "memory")
; #define PG8_WAIT_L(n) asm volatile("s_waitcnt lgkmcnt(" #n ")" ::: "memory")
; #define PG8_BAR __builtin_amdgcn_s_barrier()
; #define PG8_SCHED __builtin_amdgcn_sched_barrier(0)
;     ...
;             const bool last = (t == nt - 2);
;             const char* a1 = PG8_ATILE(cA, cA2, t + 1);
;             const char* a2 = last ? nA : PG8_ATILE(cA, cA2, t + 2); const char* b2 = last ? nB : cB + (size_t)(t + 2) * 128;
;             const char* a3 = last ? nA + kA1 : PG8_ATILE(cA, cA2, t + 3); const char* b3 = b2 + kB1;
;             if constexpr (SP2) {
;             PG8_LDB(B0, 0, 0); PG8_LDB(B1, 0, 1); PG8_SCHED; PG8_LDA(At, 0, 0); PG8_STAGE(PG8_SA(1, 1), a1 + hA, voffA);
;             PG8_WAIT_V(8); PG8_WAIT_L(0); PG8_BAR; PG8_MMA(0, 0, At, B0); PG8_MMA(0, 1, At, B1); PG8_BAR; PG8_SCHED;
;             PG8_LDA(At, 0, 1); PG8_STAGE(PG8_SB(0, 0), b2, voffB); PG8_STAGE(PG8_SB(0, 1), b2 + hB, voffB); PG8_STAGE(PG8_SA(0, 0), a2, voffA);
;             PG8_WAIT_V(8); PG8_WAIT_L(0); PG8_BAR; PG8_MMA(1, 0, At, B0); PG8_MMA(1, 1, At, B1); PG8_BAR; PG8_SCHED;
.LBB0_96:
	s_and_b64 s[2:3], exec, s[80:81]
	s_cselect_b32 s73, s27, s13
	s_cselect_b32 s72, s26, s9
	s_add_i32 s17, 0, 0x10000
	s_add_i32 s36, 0, 0x14000
	v_add_u32_e32 v132, s17, v182
	v_add_u32_e32 v180, s36, v182
	ds_read_b128 v[16:19], v132
	ds_read_b128 v[24:27], v132 offset:1024
	ds_read_b128 v[120:123], v132 offset:2048
	ds_read_b128 v[132:135], v132 offset:3072
	ds_read_b128 v[140:143], v180
	ds_read_b128 v[148:151], v180 offset:1024
	ds_read_b128 v[176:179], v180 offset:2048
	ds_read_b128 v[184:187], v180 offset:3072
	s_add_u32 s2, s78, 0x10000
	s_addc_u32 s3, s79, 0
	v_lshl_add_u64 v[180:181], s[2:3], 0, v[152:153]
	s_add_i32 m0, s94, 0xc000
	ds_read_b128 v[188:191], v183
	ds_read_b128 v[192:195], v183 offset:1024
	ds_read_b128 v[196:199], v183 offset:2048
	ds_read_b128 v[200:203], v183 offset:3072
	ds_read_b128 v[208:211], v183 offset:4096
	ds_read_b128 v[214:217], v183 offset:5120
	ds_read_b128 v[230:233], v183 offset:6144
	ds_read_b128 v[234:237], v183 offset:7168
	global_load_lds_dwordx4 v[180:181], off
	v_lshl_add_u64 v[180:181], s[2:3], 0, v[154:155]
	s_add_i32 m0, s94, 0xe000
	s_nop 0
	global_load_lds_dwordx4 v[180:181], off
	s_waitcnt vmcnt(8)
	s_waitcnt lgkmcnt(0)
	s_barrier
	s_setprio 1
	s_waitcnt lgkmcnt(0)
	v_mfma_f32_16x16x32_bf16 v[144:147], v[16:19], v[188:191], v[144:147]
	v_mfma_f32_16x16x32_bf16 v[144:147], v[24:27], v[192:195], v[144:147]
	v_mfma_f32_16x16x32_bf16 v[136:139], v[120:123], v[188:191], v[136:139]
	v_mfma_f32_16x16x32_bf16 v[136:139], v[132:135], v[192:195], v[136:139]
	v_mfma_f32_16x16x32_bf16 v[116:119], v[16:19], v[196:199], v[116:119]
	v_mfma_f32_16x16x32_bf16 v[116:119], v[24:27], v[200:203], v[116:119]
	v_mfma_f32_16x16x32_bf16 v[112:115], v[120:123], v[196:199], v[112:115]
	v_mfma_f32_16x16x32_bf16 v[112:115], v[132:135], v[200:203], v[112:115]
	v_mfma_f32_16x16x32_bf16 v[100:103], v[16:19], v[208:211], v[100:103]
	v_mfma_f32_16x16x32_bf16 v[100:103], v[24:27], v[214:217], v[100:103]
	v_mfma_f32_16x16x32_bf16 v[96:99], v[120:123], v[208:211], v[96:99]
	v_mfma_f32_16x16x32_bf16 v[96:99], v[132:135], v[214:217], v[96:99]
	v_mfma_f32_16x16x32_bf16 v[84:87], v[16:19], v[230:233], v[84:87]
	v_mfma_f32_16x16x32_bf16 v[84:87], v[24:27], v[234:237], v[84:87]
	v_mfma_f32_16x16x32_bf16 v[80:83], v[120:123], v[230:233], v[80:83]
	v_mfma_f32_16x16x32_bf16 v[80:83], v[132:135], v[234:237], v[80:83]
	s_setprio 0
	s_setprio 1
	v_mfma_f32_16x16x32_bf16 v[128:131], v[140:143], v[188:191], v[128:131]
	v_mfma_f32_16x16x32_bf16 v[128:131], v[148:151], v[192:195], v[128:131]
	v_mfma_f32_16x16x32_bf16 v[124:127], v[176:179], v[188:191], v[124:127]
	v_mfma_f32_16x16x32_bf16 v[124:127], v[184:187], v[192:195], v[124:127]
	v_mfma_f32_16x16x32_bf16 v[108:111], v[140:143], v[196:199], v[108:111]
	v_mfma_f32_16x16x32_bf16 v[108:111], v[148:151], v[200:203], v[108:111]
	v_mfma_f32_16x16x32_bf16 v[104:107], v[176:179], v[196:199], v[104:107]
	v_mfma_f32_16x16x32_bf16 v[104:107], v[184:187], v[200:203], v[104:107]
	v_mfma_f32_16x16x32_bf16 v[92:95], v[140:143], v[208:211], v[92:95]
	v_mfma_f32_16x16x32_bf16 v[92:95], v[148:151], v[214:217], v[92:95]
	v_mfma_f32_16x16x32_bf16 v[88:91], v[176:179], v[208:211], v[88:91]
	v_mfma_f32_16x16x32_bf16 v[88:91], v[184:187], v[214:217], v[88:91]
	v_mfma_f32_16x16x32_bf16 v[76:79], v[140:143], v[230:233], v[76:79]
	v_mfma_f32_16x16x32_bf16 v[76:79], v[148:151], v[234:237], v[76:79]
	v_mfma_f32_16x16x32_bf16 v[72:75], v[176:179], v[230:233], v[72:75]
	v_mfma_f32_16x16x32_bf16 v[72:75], v[184:187], v[234:237], v[72:75]
	s_setprio 0
	s_barrier
	s_add_i32 s2, s17, s93
	v_lshl_add_u64 v[180:181], s[72:73], 0, v[156:157]
	s_mov_b32 m0, s2
	ds_read_b128 v[188:191], v183 offset:16384
	ds_read_b128 v[192:195], v183 offset:17408
	ds_read_b128 v[196:199], v183 offset:18432
	ds_read_b128 v[200:203], v183 offset:19456
	ds_read_b128 v[208:211], v183 offset:20480
	ds_read_b128 v[214:217], v183 offset:21504
	ds_read_b128 v[230:233], v183 offset:22528
	ds_read_b128 v[234:237], v183 offset:23552
	global_load_lds_dwordx4 v[180:181], off
	s_add_i32 m0, s2, 0x2000
	s_add_u32 s2, s72, 0x18000
	v_lshl_add_u64 v[204:205], s[72:73], 0, v[168:169]
	s_addc_u32 s3, s73, 0
	s_add_i32 s17, s36, s93
	global_load_lds_dwordx4 v[204:205], off
	v_lshl_add_u64 v[206:207], s[2:3], 0, v[156:157]
	s_mov_b32 m0, s17
	s_nop 0
	global_load_lds_dwordx4 v[206:207], off
	v_lshl_add_u64 v[206:207], s[2:3], 0, v[168:169]
	s_add_i32 m0, s17, 0x2000
	s_nop 0
	global_load_lds_dwordx4 v[206:207], off
	v_lshl_add_u64 v[206:207], s[76:77], 0, v[152:153]
	s_mov_b32 m0, s94
	s_nop 0
	global_load_lds_dwordx4 v[206:207], off
	v_lshl_add_u64 v[206:207], s[76:77], 0, v[154:155]
	s_mov_b32 m0, s95
	s_nop 0
	global_load_lds_dwordx4 v[206:207], off
	s_waitcnt vmcnt(8)
	s_waitcnt lgkmcnt(0)
	s_barrier
; #define PG8_STAGE(bufoff, gbase, voff) do { _Pragma("unroll") for (int _i = 0; _i < 2; ++_i) \
;         __builtin_amdgcn_global_load_lds((const unsigned*)((const char*)(gbase) + (voff)[_i]), (LAS unsigned*)(lds + (bufoff) + ldsw + _i * 8192), 16, 0, 0); } while (0)
; #define PG8_LDA(dst, b, h) do { _Pragma("unroll") for (int m = 0; m < 4; ++m) _Pragma("unroll") for (int k = 0; k < 2; ++k) dst[m][k] = *(const LAS bf16x8*)(lds + PG8_SA(b, h) + aoff + m * 2048 + k * 1024); } while (0)
; #define PG8_LDB(dst, b, h) do { _Pragma("unroll") for (int n = 0; n < 2; ++n) _Pragma("unroll") for (int k = 0; k < 2; ++k) dst[n][k] = *(const LAS bf16x8*)(lds + PG8_SB(b, h) + boff + n * 2048 + k * 1024); } while (0)
; #define PG8_MMA(ai, bj, At, Bt) do { __builtin_amdgcn_s_setprio(1); _Pragma("unroll") for (int m = 0; m < 4; ++m) _Pragma("unroll") for (int n = 0; n < 2; ++n) _Pragma("unroll") for (int k = 0; k < 2; ++k) \
;         acc[ai][bj][m][n] = __builtin_amdgcn_mfma_f32_16x16x32_bf16(Bt[n][k], At[m][k], acc[ai][bj][m][n], 0, 0, 0); __builtin_amdgcn_s_setprio(0); } while (0)
; #define PG8_WAIT_V(n) asm volatile("s_waitcnt vmcnt(" #n ")" ::: "memory")
; #define PG8_WAIT_L(n) asm volatile("s_waitcnt lgkmcnt(" #n ")" ::: "memory")
; #define PG8_BAR __builtin_amdgcn_s_barrier()
; #define PG8_SCHED __builtin_amdgcn_sched_barrier(0)
;     ...
;             PG8_WAIT_V(8); PG8_WAIT_L(0); PG8_BAR; PG8_MMA(1, 0, At, B0); PG8_MMA(1, 1, At, B1); PG8_BAR; PG8_SCHED;
;             PG8_LDB(B0, 1, 0); PG8_LDB(B1, 1, 1); PG8_SCHED; PG8_LDA(At, 1, 0); PG8_STAGE(PG8_SA(0, 1), a2 + hA, voffA);
;             PG8_WAIT_V(8); PG8_WAIT_L(0); PG8_BAR; PG8_MMA(0, 0, At, B0); PG8_MMA(0, 1, At, B1); PG8_BAR; PG8_SCHED;
	s_setprio 1
	s_waitcnt lgkmcnt(0)
	v_mfma_f32_16x16x32_bf16 v[68:71], v[16:19], v[188:191], v[68:71]
	v_mfma_f32_16x16x32_bf16 v[68:71], v[24:27], v[192:195], v[68:71]
	v_mfma_f32_16x16x32_bf16 v[64:67], v[120:123], v[188:191], v[64:67]
	v_mfma_f32_16x16x32_bf16 v[64:67], v[132:135], v[192:195], v[64:67]
	v_mfma_f32_16x16x32_bf16 v[52:55], v[16:19], v[196:199], v[52:55]
	v_mfma_f32_16x16x32_bf16 v[52:55], v[24:27], v[200:203], v[52:55]
	v_mfma_f32_16x16x32_bf16 v[48:51], v[120:123], v[196:199], v[48:51]
	v_mfma_f32_16x16x32_bf16 v[48:51], v[132:135], v[200:203], v[48:51]
	v_mfma_f32_16x16x32_bf16 v[36:39], v[16:19], v[208:211], v[36:39]
	v_mfma_f32_16x16x32_bf16 v[36:39], v[24:27], v[214:217], v[36:39]
	v_mfma_f32_16x16x32_bf16 v[32:35], v[120:123], v[208:211], v[32:35]
	v_mfma_f32_16x16x32_bf16 v[32:35], v[132:135], v[214:217], v[32:35]
	v_mfma_f32_16x16x32_bf16 v[12:15], v[16:19], v[230:233], v[12:15]
	v_mfma_f32_16x16x32_bf16 v[12:15], v[24:27], v[234:237], v[12:15]
	v_mfma_f32_16x16x32_bf16 v[8:11], v[120:123], v[230:233], v[8:11]
	v_mfma_f32_16x16x32_bf16 v[8:11], v[132:135], v[234:237], v[8:11]
	s_setprio 0
	s_setprio 1
	v_mfma_f32_16x16x32_bf16 v[44:47], v[140:143], v[196:199], v[44:47]
	v_mfma_f32_16x16x32_bf16 v[44:47], v[148:151], v[200:203], v[44:47]
	v_mfma_f32_16x16x32_bf16 v[40:43], v[176:179], v[196:199], v[40:43]
	v_mfma_f32_16x16x32_bf16 v[40:43], v[184:187], v[200:203], v[40:43]
	v_mfma_f32_16x16x32_bf16 v[28:31], v[140:143], v[208:211], v[28:31]
	v_mfma_f32_16x16x32_bf16 v[28:31], v[148:151], v[214:217], v[28:31]
	v_mfma_f32_16x16x32_bf16 v[20:23], v[176:179], v[208:211], v[20:23]
	v_mfma_f32_16x16x32_bf16 v[20:23], v[184:187], v[214:217], v[20:23]
	v_mfma_f32_16x16x32_bf16 v[4:7], v[140:143], v[230:233], v[4:7]
	v_mfma_f32_16x16x32_bf16 v[4:7], v[148:151], v[234:237], v[4:7]
	v_mfma_f32_16x16x32_bf16 v[0:3], v[176:179], v[230:233], v[0:3]
	v_mfma_f32_16x16x32_bf16 v[0:3], v[184:187], v[234:237], v[0:3]
	v_mfma_f32_16x16x32_bf16 v[16:19], v[140:143], v[188:191], v[60:63]
	v_mfma_f32_16x16x32_bf16 v[16:19], v[148:151], v[192:195], v[16:19]
	v_mfma_f32_16x16x32_bf16 v[24:27], v[176:179], v[188:191], v[56:59]
	v_mfma_f32_16x16x32_bf16 v[24:27], v[184:187], v[192:195], v[24:27]
	s_setprio 0
	s_barrier
	s_add_i32 s17, 0, 0x18000
	s_add_i32 s36, 0, 0x1c000
	v_add_u32_e32 v132, s17, v182
	v_add_u32_e32 v184, s36, v182
	ds_read_b128 v[56:59], v132
	ds_read_b128 v[60:63], v132 offset:1024
	ds_read_b128 v[120:123], v132 offset:2048
	ds_read_b128 v[132:135], v132 offset:3072
	ds_read_b128 v[140:143], v184
	ds_read_b128 v[148:151], v184 offset:1024
	ds_read_b128 v[176:179], v184 offset:2048
	ds_read_b128 v[184:187], v184 offset:3072
	s_add_u32 s2, s76, 0x10000
	s_addc_u32 s3, s77, 0
	s_mov_b32 m0, s44
	v_lshl_add_u64 v[206:207], s[2:3], 0, v[152:153]
	ds_read_b128 v[188:191], v183 offset:32768
	ds_read_b128 v[192:195], v183 offset:33792
	ds_read_b128 v[196:199], v183 offset:34816
	ds_read_b128 v[200:203], v183 offset:35840
	ds_read_b128 v[208:211], v183 offset:36864
	ds_read_b128 v[214:217], v183 offset:37888
	ds_read_b128 v[230:233], v183 offset:38912
	ds_read_b128 v[234:237], v183 offset:39936
	global_load_lds_dwordx4 v[206:207], off
	v_lshl_add_u64 v[206:207], s[2:3], 0, v[154:155]
	s_mov_b32 m0, s45
	s_nop 0
	global_load_lds_dwordx4 v[206:207], off
	s_waitcnt vmcnt(8)
	s_waitcnt lgkmcnt(0)
	s_barrier
	s_setprio 1
	s_waitcnt lgkmcnt(0)
	v_mfma_f32_16x16x32_bf16 v[144:147], v[56:59], v[188:191], v[144:147]
	v_mfma_f32_16x16x32_bf16 v[144:147], v[60:63], v[192:195], v[144:147]
	v_mfma_f32_16x16x32_bf16 v[136:139], v[120:123], v[188:191], v[136:139]
	v_mfma_f32_16x16x32_bf16 v[136:139], v[132:135], v[192:195], v[136:139]
	v_mfma_f32_16x16x32_bf16 v[116:119], v[56:59], v[196:199], v[116:119]
	v_mfma_f32_16x16x32_bf16 v[116:119], v[60:63], v[200:203], v[116:119]
	v_mfma_f32_16x16x32_bf16 v[112:115], v[120:123], v[196:199], v[112:115]
	v_mfma_f32_16x16x32_bf16 v[112:115], v[132:135], v[200:203], v[112:115]
	v_mfma_f32_16x16x32_bf16 v[100:103], v[56:59], v[208:211], v[100:103]
	v_mfma_f32_16x16x32_bf16 v[100:103], v[60:63], v[214:217], v[100:103]
	v_mfma_f32_16x16x32_bf16 v[96:99], v[120:123], v[208:211], v[96:99]
	v_mfma_f32_16x16x32_bf16 v[96:99], v[132:135], v[214:217], v[96:99]
	v_mfma_f32_16x16x32_bf16 v[84:87], v[56:59], v[230:233], v[84:87]
	v_mfma_f32_16x16x32_bf16 v[84:87], v[60:63], v[234:237], v[84:87]
	v_mfma_f32_16x16x32_bf16 v[80:83], v[120:123], v[230:233], v[80:83]
	v_mfma_f32_16x16x32_bf16 v[80:83], v[132:135], v[234:237], v[80:83]
	s_setprio 0
	s_setprio 1
	v_mfma_f32_16x16x32_bf16 v[128:131], v[140:143], v[188:191], v[128:131]
	v_mfma_f32_16x16x32_bf16 v[128:131], v[148:151], v[192:195], v[128:131]
	v_mfma_f32_16x16x32_bf16 v[124:127], v[176:179], v[188:191], v[124:127]
	v_mfma_f32_16x16x32_bf16 v[124:127], v[184:187], v[192:195], v[124:127]
	v_mfma_f32_16x16x32_bf16 v[108:111], v[140:143], v[196:199], v[108:111]
	v_mfma_f32_16x16x32_bf16 v[108:111], v[148:151], v[200:203], v[108:111]
	v_mfma_f32_16x16x32_bf16 v[104:107], v[176:179], v[196:199], v[104:107]
	v_mfma_f32_16x16x32_bf16 v[104:107], v[184:187], v[200:203], v[104:107]
	v_mfma_f32_16x16x32_bf16 v[92:95], v[140:143], v[208:211], v[92:95]
	v_mfma_f32_16x16x32_bf16 v[92:95], v[148:151], v[214:217], v[92:95]
	v_mfma_f32_16x16x32_bf16 v[88:91], v[176:179], v[208:211], v[88:91]
	v_mfma_f32_16x16x32_bf16 v[88:91], v[184:187], v[214:217], v[88:91]
	v_mfma_f32_16x16x32_bf16 v[76:79], v[140:143], v[230:233], v[76:79]
	v_mfma_f32_16x16x32_bf16 v[76:79], v[148:151], v[234:237], v[76:79]
	v_mfma_f32_16x16x32_bf16 v[72:75], v[176:179], v[230:233], v[72:75]
	v_mfma_f32_16x16x32_bf16 v[72:75], v[184:187], v[234:237], v[72:75]
	s_setprio 0
	s_barrier
; #define PG8_STAGE(bufoff, gbase, voff) do { _Pragma("unroll") for (int _i = 0; _i < 2; ++_i) \
;         __builtin_amdgcn_global_load_lds((const unsigned*)((const char*)(gbase) + (voff)[_i]), (LAS unsigned*)(lds + (bufoff) + ldsw + _i * 8192), 16, 0, 0); } while (0)
; #define PG8_LDA(dst, b, h) do { _Pragma("unroll") for (int m = 0; m < 4; ++m) _Pragma("unroll") for (int k = 0; k < 2; ++k) dst[m][k] = *(const LAS bf16x8*)(lds + PG8_SA(b, h) + aoff + m * 2048 + k * 1024); } while (0)
; #define PG8_MMA(ai, bj, At, Bt) do { __builtin_amdgcn_s_setprio(1); _Pragma("unroll") for (int m = 0; m < 4; ++m) _Pragma("unroll") for (int n = 0; n < 2; ++n) _Pragma("unroll") for (int k = 0; k < 2; ++k) \
;         acc[ai][bj][m][n] = __builtin_amdgcn_mfma_f32_16x16x32_bf16(Bt[n][k], At[m][k], acc[ai][bj][m][n], 0, 0, 0); __builtin_amdgcn_s_setprio(0); } while (0)
; #define PG8_WAIT_V(n) asm volatile("s_waitcnt vmcnt(" #n ")" ::: "memory")
; #define PG8_WAIT_L(n) asm volatile("s_waitcnt lgkmcnt(" #n ")" ::: "memory")
; #define PG8_BAR __builtin_amdgcn_s_barrier()
; #define PG8_SCHED __builtin_amdgcn_sched_barrier(0)
;     ...
;         for (int t = 0; t < nt; t += 2) {
;     ...
;             PG8_LDA(At, 1, 1); PG8_STAGE(PG8_SB(1, 0), b3, voffB); PG8_STAGE(PG8_SB(1, 1), b3 + hB, voffB); PG8_STAGE(PG8_SA(1, 0), a3, voffA);
;             PG8_WAIT_V(8); PG8_WAIT_L(0); PG8_BAR; PG8_MMA(1, 0, At, B0); PG8_MMA(1, 1, At, B1); PG8_BAR; PG8_SCHED;
	s_add_i32 s2, s17, s93
	v_lshl_add_u64 v[180:181], v[180:181], 0, s[38:39]
	s_mov_b32 m0, s2
	ds_read_b128 v[188:191], v183 offset:49152
	ds_read_b128 v[192:195], v183 offset:50176
	ds_read_b128 v[196:199], v183 offset:51200
	ds_read_b128 v[200:203], v183 offset:52224
	ds_read_b128 v[208:211], v183 offset:53248
	ds_read_b128 v[214:217], v183 offset:54272
	ds_read_b128 v[230:233], v183 offset:55296
	ds_read_b128 v[234:237], v183 offset:56320
	global_load_lds_dwordx4 v[180:181], off
	s_add_i32 m0, s2, 0x2000
	s_add_u32 s2, s72, 0x18080
	v_lshl_add_u64 v[180:181], v[204:205], 0, s[38:39]
	s_addc_u32 s3, s73, 0
	s_add_i32 s17, s36, s93
	global_load_lds_dwordx4 v[180:181], off
	v_lshl_add_u64 v[180:181], s[2:3], 0, v[156:157]
	s_mov_b32 m0, s17
	s_nop 0
	global_load_lds_dwordx4 v[180:181], off
	v_lshl_add_u64 v[180:181], s[2:3], 0, v[168:169]
	s_add_i32 m0, s17, 0x2000
	s_nop 0
	global_load_lds_dwordx4 v[180:181], off
	v_lshl_add_u64 v[180:181], s[74:75], 0, v[152:153]
	s_mov_b32 m0, s51
	s_nop 0
	global_load_lds_dwordx4 v[180:181], off
	v_lshl_add_u64 v[180:181], s[74:75], 0, v[154:155]
	s_mov_b32 m0, s50
	s_nop 0
	global_load_lds_dwordx4 v[180:181], off
	s_waitcnt vmcnt(8)
	s_waitcnt lgkmcnt(0)
	s_barrier
	s_setprio 1
	s_waitcnt lgkmcnt(0)
	v_mfma_f32_16x16x32_bf16 v[68:71], v[56:59], v[188:191], v[68:71]
	v_mfma_f32_16x16x32_bf16 v[68:71], v[60:63], v[192:195], v[68:71]
	v_mfma_f32_16x16x32_bf16 v[64:67], v[120:123], v[188:191], v[64:67]
	v_mfma_f32_16x16x32_bf16 v[64:67], v[132:135], v[192:195], v[64:67]
	v_mfma_f32_16x16x32_bf16 v[52:55], v[56:59], v[196:199], v[52:55]
	v_mfma_f32_16x16x32_bf16 v[52:55], v[60:63], v[200:203], v[52:55]
	v_mfma_f32_16x16x32_bf16 v[48:51], v[120:123], v[196:199], v[48:51]
	v_mfma_f32_16x16x32_bf16 v[48:51], v[132:135], v[200:203], v[48:51]
	v_mfma_f32_16x16x32_bf16 v[36:39], v[56:59], v[208:211], v[36:39]
	v_mfma_f32_16x16x32_bf16 v[36:39], v[60:63], v[214:217], v[36:39]
	v_mfma_f32_16x16x32_bf16 v[32:35], v[120:123], v[208:211], v[32:35]
	v_mfma_f32_16x16x32_bf16 v[32:35], v[132:135], v[214:217], v[32:35]
	v_mfma_f32_16x16x32_bf16 v[12:15], v[56:59], v[230:233], v[12:15]
	v_mfma_f32_16x16x32_bf16 v[12:15], v[60:63], v[234:237], v[12:15]
	v_mfma_f32_16x16x32_bf16 v[8:11], v[120:123], v[230:233], v[8:11]
	v_mfma_f32_16x16x32_bf16 v[8:11], v[132:135], v[234:237], v[8:11]
	s_setprio 0
	s_setprio 1
	v_mfma_f32_16x16x32_bf16 v[16:19], v[140:143], v[188:191], v[16:19]
	v_mfma_f32_16x16x32_bf16 v[60:63], v[148:151], v[192:195], v[16:19]
	v_mfma_f32_16x16x32_bf16 v[16:19], v[176:179], v[188:191], v[24:27]
	v_mfma_f32_16x16x32_bf16 v[56:59], v[184:187], v[192:195], v[16:19]
	v_mfma_f32_16x16x32_bf16 v[16:19], v[140:143], v[196:199], v[44:47]
	v_mfma_f32_16x16x32_bf16 v[44:47], v[148:151], v[200:203], v[16:19]
	v_mfma_f32_16x16x32_bf16 v[16:19], v[176:179], v[196:199], v[40:43]
	v_mfma_f32_16x16x32_bf16 v[40:43], v[184:187], v[200:203], v[16:19]
	v_mfma_f32_16x16x32_bf16 v[16:19], v[140:143], v[208:211], v[28:31]
	v_mfma_f32_16x16x32_bf16 v[28:31], v[148:151], v[214:217], v[16:19]
	v_mfma_f32_16x16x32_bf16 v[16:19], v[176:179], v[208:211], v[20:23]
	v_mfma_f32_16x16x32_bf16 v[4:7], v[140:143], v[230:233], v[4:7]
	v_mfma_f32_16x16x32_bf16 v[0:3], v[176:179], v[230:233], v[0:3]
	v_mfma_f32_16x16x32_bf16 v[20:23], v[184:187], v[214:217], v[16:19]
	v_mfma_f32_16x16x32_bf16 v[4:7], v[148:151], v[234:237], v[4:7]
	v_mfma_f32_16x16x32_bf16 v[0:3], v[184:187], v[234:237], v[0:3]
	s_setprio 0
	s_barrier
	s_add_u32 s90, s90, 0x100
	s_addc_u32 s91, s91, 0
	s_add_u32 s9, s9, 0x100
	s_addc_u32 s13, s13, 0
	s_cmp_gt_u32 s15, 3
	s_mov_b32 s72, s15
	s_cbranch_scc1 .LBB0_103

; #define PG8_STAGE(bufoff, gbase, voff) do { _Pragma("unroll") for (int _i = 0; _i < 2; ++_i) \
;         __builtin_amdgcn_global_load_lds((const unsigned*)((const char*)(gbase) + (voff)[_i]), (LAS unsigned*)(lds + (bufoff) + ldsw + _i * 8192), 16, 0, 0); } while (0)
; #define PG8_LDA(dst, b, h) do { _Pragma("unroll") for (int m = 0; m < 4; ++m) _Pragma("unroll") for (int k = 0; k < 2; ++k) dst[m][k] = *(const LAS bf16x8*)(lds + PG8_SA(b, h) + aoff + m * 2048 + k * 1024); } while (0)
; #define PG8_LDB(dst, b, h) do { _Pragma("unroll") for (int n = 0; n < 2; ++n) _Pragma("unroll") for (int k = 0; k < 2; ++k) dst[n][k] = *(const LAS bf16x8*)(lds + PG8_SB(b, h) + boff + n * 2048 + k * 1024); } while (0)
; #define PG8_MMA(ai, bj, At, Bt) do { __builtin_amdgcn_s_setprio(1); _Pragma("unroll") for (int m = 0; m < 4; ++m) _Pragma("unroll") for (int n = 0; n < 2; ++n) _Pragma("unroll") for (int k = 0; k < 2; ++k) \
;         acc[ai][bj][m][n] = __builtin_amdgcn_mfma_f32_16x16x32_bf16(Bt[n][k], At[m][k], acc[ai][bj][m][n], 0, 0, 0); __builtin_amdgcn_s_setprio(0); } while (0)
; #define PG8_WAIT_V(n) asm volatile("s_waitcnt vmcnt(" #n ")" ::: "memory")
; #define PG8_WAIT_L(n) asm volatile("s_waitcnt lgkmcnt(" #n ")" ::: "memory")
; #define PG8_BAR __builtin_amdgcn_s_barrier()
; #define PG8_SCHED __builtin_amdgcn_sched_barrier(0)
;     ...
;             const bool last = (t == nt - 2);
;             const char* a1 = PG8_ATILE(cA, cA2, t + 1);
;             const char* a2 = last ? nA : PG8_ATILE(cA, cA2, t + 2); const char* b2 = last ? nB : cB + (size_t)(t + 2) * 128;
;             const char* a3 = last ? nA + kA1 : PG8_ATILE(cA, cA2, t + 3); const char* b3 = b2 + kB1;
;             if constexpr (SP2) {
;             PG8_LDB(B0, 0, 0); PG8_LDB(B1, 0, 1); PG8_SCHED; PG8_LDA(At, 0, 0); PG8_STAGE(PG8_SA(1, 1), a1 + hA, voffA);
;             PG8_WAIT_V(8); PG8_WAIT_L(0); PG8_BAR; PG8_MMA(0, 0, At, B0); PG8_MMA(0, 1, At, B1); PG8_BAR; PG8_SCHED;
;             PG8_LDA(At, 0, 1); PG8_STAGE(PG8_SB(0, 0), b2, voffB); PG8_STAGE(PG8_SB(0, 1), b2 + hB, voffB); PG8_STAGE(PG8_SA(0, 0), a2, voffA);
;             PG8_WAIT_V(8); PG8_WAIT_L(0); PG8_BAR; PG8_MMA(1, 0, At, B0); PG8_MMA(1, 1, At, B1); PG8_BAR; PG8_SCHED;
.LBB0_119:
	s_add_u32 s2, s52, s94
	s_addc_u32 s3, s53, s95
	s_add_u32 s76, s2, 0x100
	s_addc_u32 s77, s3, 0
	s_add_u32 s74, s80, s94
	s_addc_u32 s75, s81, s95
	s_add_u32 s2, s2, 0x180
	s_addc_u32 s3, s3, 0
	s_add_i32 vcc_hi, 0, 0x10000
	s_add_i32 s12, 0, 0x14000
	v_add_u32_e32 v155, vcc_hi, v153
	ds_read_b128 v[168:171], v155
	ds_read_b128 v[172:175], v155 offset:1024
	ds_read_b128 v[176:179], v155 offset:2048
	ds_read_b128 v[180:183], v155 offset:3072
	v_add_u32_e32 v155, s12, v153
	ds_read_b128 v[184:187], v155
	ds_read_b128 v[188:191], v155 offset:1024
	ds_read_b128 v[192:195], v155 offset:2048
	ds_read_b128 v[196:199], v155 offset:3072
	s_cmpk_eq_i32 s94, 0x300
	s_cselect_b32 s73, s97, s3
	s_cselect_b32 s72, s96, s2
	s_cselect_b32 s75, s82, s75
	s_cselect_b32 s74, s91, s74
	s_cselect_b32 s77, s83, s77
	s_cselect_b32 s76, s89, s76
	v_lshl_add_u64 v[204:205], v[142:143], 0, s[94:95]
	s_add_i32 m0, s1, 0xc000
	ds_read_b128 v[208:211], v154
	ds_read_b128 v[214:217], v154 offset:1024
	ds_read_b128 v[230:233], v154 offset:2048
	ds_read_b128 v[234:237], v154 offset:3072
	ds_read_b128 v[238:241], v154 offset:4096
	ds_read_b128 v[242:245], v154 offset:5120
	ds_read_b128 v[246:249], v154 offset:6144
	ds_read_b128 v[200:203], v154 offset:7168
	global_load_lds_dwordx4 v[204:205], off
	v_lshl_add_u64 v[204:205], v[144:145], 0, s[94:95]
	s_add_i32 m0, s1, 0xe000
	s_nop 0
	global_load_lds_dwordx4 v[204:205], off
	s_waitcnt vmcnt(8)
	s_waitcnt lgkmcnt(0)
	s_barrier
	s_setprio 1
	s_waitcnt lgkmcnt(0)
	v_mfma_f32_16x16x32_bf16 v[124:127], v[168:171], v[208:211], v[124:127]
	v_mfma_f32_16x16x32_bf16 v[124:127], v[172:175], v[214:217], v[124:127]
	v_mfma_f32_16x16x32_bf16 v[120:123], v[176:179], v[208:211], v[120:123]
	v_mfma_f32_16x16x32_bf16 v[120:123], v[180:183], v[214:217], v[120:123]
	v_mfma_f32_16x16x32_bf16 v[116:119], v[168:171], v[230:233], v[116:119]
	v_mfma_f32_16x16x32_bf16 v[116:119], v[172:175], v[234:237], v[116:119]
	v_mfma_f32_16x16x32_bf16 v[112:115], v[176:179], v[230:233], v[112:115]
	v_mfma_f32_16x16x32_bf16 v[112:115], v[180:183], v[234:237], v[112:115]
	v_mfma_f32_16x16x32_bf16 v[108:111], v[168:171], v[238:241], v[108:111]
	v_mfma_f32_16x16x32_bf16 v[108:111], v[172:175], v[242:245], v[108:111]
	v_mfma_f32_16x16x32_bf16 v[100:103], v[176:179], v[238:241], v[100:103]
	v_mfma_f32_16x16x32_bf16 v[100:103], v[180:183], v[242:245], v[100:103]
	v_mfma_f32_16x16x32_bf16 v[92:95], v[168:171], v[246:249], v[92:95]
	v_mfma_f32_16x16x32_bf16 v[92:95], v[172:175], v[200:203], v[92:95]
	v_mfma_f32_16x16x32_bf16 v[84:87], v[176:179], v[246:249], v[84:87]
	v_mfma_f32_16x16x32_bf16 v[84:87], v[180:183], v[200:203], v[84:87]
	s_setprio 0
	s_setprio 1
	v_mfma_f32_16x16x32_bf16 v[104:107], v[184:187], v[208:211], v[104:107]
	v_mfma_f32_16x16x32_bf16 v[104:107], v[188:191], v[214:217], v[104:107]
	v_mfma_f32_16x16x32_bf16 v[96:99], v[192:195], v[208:211], v[96:99]
	v_mfma_f32_16x16x32_bf16 v[96:99], v[196:199], v[214:217], v[96:99]
	v_mfma_f32_16x16x32_bf16 v[88:91], v[184:187], v[230:233], v[88:91]
	v_mfma_f32_16x16x32_bf16 v[88:91], v[188:191], v[234:237], v[88:91]
	v_mfma_f32_16x16x32_bf16 v[80:83], v[192:195], v[230:233], v[80:83]
	v_mfma_f32_16x16x32_bf16 v[80:83], v[196:199], v[234:237], v[80:83]
	v_mfma_f32_16x16x32_bf16 v[76:79], v[184:187], v[238:241], v[76:79]
	v_mfma_f32_16x16x32_bf16 v[76:79], v[188:191], v[242:245], v[76:79]
	v_mfma_f32_16x16x32_bf16 v[72:75], v[192:195], v[238:241], v[72:75]
	v_mfma_f32_16x16x32_bf16 v[72:75], v[196:199], v[242:245], v[72:75]
	v_mfma_f32_16x16x32_bf16 v[68:71], v[184:187], v[246:249], v[68:71]
	v_mfma_f32_16x16x32_bf16 v[68:71], v[188:191], v[200:203], v[68:71]
	v_mfma_f32_16x16x32_bf16 v[64:67], v[192:195], v[246:249], v[64:67]
	v_mfma_f32_16x16x32_bf16 v[64:67], v[196:199], v[200:203], v[64:67]
	s_setprio 0
	s_barrier
	s_add_i32 s2, vcc_hi, s0
	v_lshl_add_u64 v[204:205], s[74:75], 0, v[130:131]
	s_mov_b32 m0, s2
	ds_read_b128 v[200:203], v154 offset:16384
	ds_read_b128 v[208:211], v154 offset:17408
	ds_read_b128 v[214:217], v154 offset:18432
	ds_read_b128 v[230:233], v154 offset:19456
	ds_read_b128 v[234:237], v154 offset:20480
	ds_read_b128 v[238:241], v154 offset:21504
	ds_read_b128 v[242:245], v154 offset:22528
	ds_read_b128 v[246:249], v154 offset:23552
	global_load_lds_dwordx4 v[204:205], off
	s_add_i32 m0, s2, 0x2000
	s_add_u32 s2, s74, 0x20000
	v_lshl_add_u64 v[206:207], s[74:75], 0, v[134:135]
	s_addc_u32 s3, s75, 0
	s_add_i32 s12, s12, s0
	global_load_lds_dwordx4 v[206:207], off
	v_lshl_add_u64 v[250:251], s[2:3], 0, v[130:131]
	s_mov_b32 m0, s12
	s_nop 0
	global_load_lds_dwordx4 v[250:251], off
	v_lshl_add_u64 v[250:251], s[2:3], 0, v[134:135]
	s_add_i32 m0, s12, 0x2000
	s_nop 0
	global_load_lds_dwordx4 v[250:251], off
	v_lshl_add_u64 v[250:251], s[76:77], 0, v[128:129]
	s_mov_b32 m0, s1
	s_nop 0
	global_load_lds_dwordx4 v[250:251], off
	v_lshl_add_u64 v[250:251], s[76:77], 0, v[132:133]
	s_mov_b32 m0, s4
	s_nop 0
	global_load_lds_dwordx4 v[250:251], off
	s_waitcnt vmcnt(8)
	s_waitcnt lgkmcnt(0)
	s_barrier
; #define PG8_STAGE(bufoff, gbase, voff) do { _Pragma("unroll") for (int _i = 0; _i < 2; ++_i) \
;         __builtin_amdgcn_global_load_lds((const unsigned*)((const char*)(gbase) + (voff)[_i]), (LAS unsigned*)(lds + (bufoff) + ldsw + _i * 8192), 16, 0, 0); } while (0)
; #define PG8_LDA(dst, b, h) do { _Pragma("unroll") for (int m = 0; m < 4; ++m) _Pragma("unroll") for (int k = 0; k < 2; ++k) dst[m][k] = *(const LAS bf16x8*)(lds + PG8_SA(b, h) + aoff + m * 2048 + k * 1024); } while (0)
; #define PG8_LDB(dst, b, h) do { _Pragma("unroll") for (int n = 0; n < 2; ++n) _Pragma("unroll") for (int k = 0; k < 2; ++k) dst[n][k] = *(const LAS bf16x8*)(lds + PG8_SB(b, h) + boff + n * 2048 + k * 1024); } while (0)
; #define PG8_MMA(ai, bj, At, Bt) do { __builtin_amdgcn_s_setprio(1); _Pragma("unroll") for (int m = 0; m < 4; ++m) _Pragma("unroll") for (int n = 0; n < 2; ++n) _Pragma("unroll") for (int k = 0; k < 2; ++k) \
;         acc[ai][bj][m][n] = __builtin_amdgcn_mfma_f32_16x16x32_bf16(Bt[n][k], At[m][k], acc[ai][bj][m][n], 0, 0, 0); __builtin_amdgcn_s_setprio(0); } while (0)
; #define PG8_WAIT_V(n) asm volatile("s_waitcnt vmcnt(" #n ")" ::: "memory")
; #define PG8_WAIT_L(n) asm volatile("s_waitcnt lgkmcnt(" #n ")" ::: "memory")
; #define PG8_BAR __builtin_amdgcn_s_barrier()
; #define PG8_SCHED __builtin_amdgcn_sched_barrier(0)
;     ...
;             PG8_WAIT_V(8); PG8_WAIT_L(0); PG8_BAR; PG8_MMA(1, 0, At, B0); PG8_MMA(1, 1, At, B1); PG8_BAR; PG8_SCHED;
;             PG8_LDB(B0, 1, 0); PG8_LDB(B1, 1, 1); PG8_SCHED; PG8_LDA(At, 1, 0); PG8_STAGE(PG8_SA(0, 1), a2 + hA, voffA);
;             PG8_WAIT_V(8); PG8_WAIT_L(0); PG8_BAR; PG8_MMA(0, 0, At, B0); PG8_MMA(0, 1, At, B1); PG8_BAR; PG8_SCHED;
	s_setprio 1
	s_waitcnt lgkmcnt(0)
	v_mfma_f32_16x16x32_bf16 v[60:63], v[168:171], v[200:203], v[60:63]
	v_mfma_f32_16x16x32_bf16 v[60:63], v[172:175], v[208:211], v[60:63]
	v_mfma_f32_16x16x32_bf16 v[56:59], v[176:179], v[200:203], v[56:59]
	v_mfma_f32_16x16x32_bf16 v[56:59], v[180:183], v[208:211], v[56:59]
	v_mfma_f32_16x16x32_bf16 v[52:55], v[168:171], v[214:217], v[52:55]
	v_mfma_f32_16x16x32_bf16 v[52:55], v[172:175], v[230:233], v[52:55]
	v_mfma_f32_16x16x32_bf16 v[48:51], v[176:179], v[214:217], v[48:51]
	v_mfma_f32_16x16x32_bf16 v[48:51], v[180:183], v[230:233], v[48:51]
	v_mfma_f32_16x16x32_bf16 v[44:47], v[168:171], v[234:237], v[44:47]
	v_mfma_f32_16x16x32_bf16 v[44:47], v[172:175], v[238:241], v[44:47]
	v_mfma_f32_16x16x32_bf16 v[36:39], v[176:179], v[234:237], v[36:39]
	v_mfma_f32_16x16x32_bf16 v[36:39], v[180:183], v[238:241], v[36:39]
	v_mfma_f32_16x16x32_bf16 v[28:31], v[168:171], v[242:245], v[28:31]
	v_mfma_f32_16x16x32_bf16 v[28:31], v[172:175], v[246:249], v[28:31]
	v_mfma_f32_16x16x32_bf16 v[20:23], v[176:179], v[242:245], v[20:23]
	v_mfma_f32_16x16x32_bf16 v[20:23], v[180:183], v[246:249], v[20:23]
	s_setprio 0
	s_setprio 1
	v_mfma_f32_16x16x32_bf16 v[40:43], v[184:187], v[200:203], v[40:43]
	v_mfma_f32_16x16x32_bf16 v[40:43], v[188:191], v[208:211], v[40:43]
	v_mfma_f32_16x16x32_bf16 v[32:35], v[192:195], v[200:203], v[32:35]
	v_mfma_f32_16x16x32_bf16 v[32:35], v[196:199], v[208:211], v[32:35]
	v_mfma_f32_16x16x32_bf16 v[24:27], v[184:187], v[214:217], v[24:27]
	v_mfma_f32_16x16x32_bf16 v[24:27], v[188:191], v[230:233], v[24:27]
	v_mfma_f32_16x16x32_bf16 v[16:19], v[192:195], v[214:217], v[16:19]
	v_mfma_f32_16x16x32_bf16 v[16:19], v[196:199], v[230:233], v[16:19]
	v_mfma_f32_16x16x32_bf16 v[12:15], v[184:187], v[234:237], v[12:15]
	v_mfma_f32_16x16x32_bf16 v[12:15], v[188:191], v[238:241], v[12:15]
	v_mfma_f32_16x16x32_bf16 v[8:11], v[192:195], v[234:237], v[8:11]
	v_mfma_f32_16x16x32_bf16 v[8:11], v[196:199], v[238:241], v[8:11]
	v_mfma_f32_16x16x32_bf16 v[4:7], v[184:187], v[242:245], v[4:7]
	v_mfma_f32_16x16x32_bf16 v[4:7], v[188:191], v[246:249], v[4:7]
	v_mfma_f32_16x16x32_bf16 v[0:3], v[192:195], v[242:245], v[0:3]
	v_mfma_f32_16x16x32_bf16 v[0:3], v[196:199], v[246:249], v[0:3]
	s_setprio 0
	s_barrier
	s_add_i32 s12, 0, 0x18000
	v_add_u32_e32 v155, s12, v153
	s_add_i32 s13, 0, 0x1c000
	ds_read_b128 v[168:171], v155
	ds_read_b128 v[172:175], v155 offset:1024
	ds_read_b128 v[176:179], v155 offset:2048
	ds_read_b128 v[180:183], v155 offset:3072
	v_add_u32_e32 v155, s13, v153
	ds_read_b128 v[184:187], v155
	ds_read_b128 v[188:191], v155 offset:1024
	ds_read_b128 v[192:195], v155 offset:2048
	ds_read_b128 v[196:199], v155 offset:3072
	s_add_u32 s2, s76, 0x20000
	s_addc_u32 s3, s77, 0
	s_mov_b32 m0, s5
	v_lshl_add_u64 v[250:251], s[2:3], 0, v[128:129]
	ds_read_b128 v[200:203], v154 offset:32768
	ds_read_b128 v[208:211], v154 offset:33792
	ds_read_b128 v[214:217], v154 offset:34816
	ds_read_b128 v[230:233], v154 offset:35840
	ds_read_b128 v[234:237], v154 offset:36864
	ds_read_b128 v[238:241], v154 offset:37888
	ds_read_b128 v[242:245], v154 offset:38912
	ds_read_b128 v[246:249], v154 offset:39936
	global_load_lds_dwordx4 v[250:251], off
	v_lshl_add_u64 v[250:251], s[2:3], 0, v[132:133]
	s_mov_b32 m0, s6
	s_nop 0
	global_load_lds_dwordx4 v[250:251], off
	s_waitcnt vmcnt(8)
	s_waitcnt lgkmcnt(0)
	s_barrier
	s_setprio 1
	s_waitcnt lgkmcnt(0)
	v_mfma_f32_16x16x32_bf16 v[124:127], v[168:171], v[200:203], v[124:127]
	v_mfma_f32_16x16x32_bf16 v[124:127], v[172:175], v[208:211], v[124:127]
	v_mfma_f32_16x16x32_bf16 v[120:123], v[176:179], v[200:203], v[120:123]
	v_mfma_f32_16x16x32_bf16 v[120:123], v[180:183], v[208:211], v[120:123]
	v_mfma_f32_16x16x32_bf16 v[116:119], v[168:171], v[214:217], v[116:119]
	v_mfma_f32_16x16x32_bf16 v[116:119], v[172:175], v[230:233], v[116:119]
	v_mfma_f32_16x16x32_bf16 v[112:115], v[176:179], v[214:217], v[112:115]
	v_mfma_f32_16x16x32_bf16 v[112:115], v[180:183], v[230:233], v[112:115]
	v_mfma_f32_16x16x32_bf16 v[108:111], v[168:171], v[234:237], v[108:111]
	v_mfma_f32_16x16x32_bf16 v[108:111], v[172:175], v[238:241], v[108:111]
	v_mfma_f32_16x16x32_bf16 v[100:103], v[176:179], v[234:237], v[100:103]
	v_mfma_f32_16x16x32_bf16 v[100:103], v[180:183], v[238:241], v[100:103]
	v_mfma_f32_16x16x32_bf16 v[92:95], v[168:171], v[242:245], v[92:95]
	v_mfma_f32_16x16x32_bf16 v[92:95], v[172:175], v[246:249], v[92:95]
	v_mfma_f32_16x16x32_bf16 v[84:87], v[176:179], v[242:245], v[84:87]
	v_mfma_f32_16x16x32_bf16 v[84:87], v[180:183], v[246:249], v[84:87]
	s_setprio 0
	s_setprio 1
	v_mfma_f32_16x16x32_bf16 v[104:107], v[184:187], v[200:203], v[104:107]
	v_mfma_f32_16x16x32_bf16 v[104:107], v[188:191], v[208:211], v[104:107]
	v_mfma_f32_16x16x32_bf16 v[96:99], v[192:195], v[200:203], v[96:99]
	v_mfma_f32_16x16x32_bf16 v[96:99], v[196:199], v[208:211], v[96:99]
	v_mfma_f32_16x16x32_bf16 v[88:91], v[184:187], v[214:217], v[88:91]
	v_mfma_f32_16x16x32_bf16 v[88:91], v[188:191], v[230:233], v[88:91]
	v_mfma_f32_16x16x32_bf16 v[80:83], v[192:195], v[214:217], v[80:83]
	v_mfma_f32_16x16x32_bf16 v[80:83], v[196:199], v[230:233], v[80:83]
	v_mfma_f32_16x16x32_bf16 v[76:79], v[184:187], v[234:237], v[76:79]
	v_mfma_f32_16x16x32_bf16 v[76:79], v[188:191], v[238:241], v[76:79]
	v_mfma_f32_16x16x32_bf16 v[72:75], v[192:195], v[234:237], v[72:75]
	v_mfma_f32_16x16x32_bf16 v[72:75], v[196:199], v[238:241], v[72:75]
	v_mfma_f32_16x16x32_bf16 v[68:71], v[184:187], v[242:245], v[68:71]
	v_mfma_f32_16x16x32_bf16 v[68:71], v[188:191], v[246:249], v[68:71]
	v_mfma_f32_16x16x32_bf16 v[64:67], v[192:195], v[242:245], v[64:67]
	v_mfma_f32_16x16x32_bf16 v[64:67], v[196:199], v[246:249], v[64:67]
	s_setprio 0
	s_barrier
; #define PG8_STAGE(bufoff, gbase, voff) do { _Pragma("unroll") for (int _i = 0; _i < 2; ++_i) \
;         __builtin_amdgcn_global_load_lds((const unsigned*)((const char*)(gbase) + (voff)[_i]), (LAS unsigned*)(lds + (bufoff) + ldsw + _i * 8192), 16, 0, 0); } while (0)
; #define PG8_LDA(dst, b, h) do { _Pragma("unroll") for (int m = 0; m < 4; ++m) _Pragma("unroll") for (int k = 0; k < 2; ++k) dst[m][k] = *(const LAS bf16x8*)(lds + PG8_SA(b, h) + aoff + m * 2048 + k * 1024); } while (0)
; #define PG8_MMA(ai, bj, At, Bt) do { __builtin_amdgcn_s_setprio(1); _Pragma("unroll") for (int m = 0; m < 4; ++m) _Pragma("unroll") for (int n = 0; n < 2; ++n) _Pragma("unroll") for (int k = 0; k < 2; ++k) \
;         acc[ai][bj][m][n] = __builtin_amdgcn_mfma_f32_16x16x32_bf16(Bt[n][k], At[m][k], acc[ai][bj][m][n], 0, 0, 0); __builtin_amdgcn_s_setprio(0); } while (0)
; #define PG8_WAIT_V(n) asm volatile("s_waitcnt vmcnt(" #n ")" ::: "memory")
; #define PG8_WAIT_L(n) asm volatile("s_waitcnt lgkmcnt(" #n ")" ::: "memory")
; #define PG8_BAR __builtin_amdgcn_s_barrier()
; #define PG8_SCHED __builtin_amdgcn_sched_barrier(0)
;     ...
;         for (int t = 0; t < nt; t += 2) {
;     ...
;             PG8_LDA(At, 1, 1); PG8_STAGE(PG8_SB(1, 0), b3, voffB); PG8_STAGE(PG8_SB(1, 1), b3 + hB, voffB); PG8_STAGE(PG8_SA(1, 0), a3, voffA);
;             PG8_WAIT_V(8); PG8_WAIT_L(0); PG8_BAR; PG8_MMA(1, 0, At, B0); PG8_MMA(1, 1, At, B1); PG8_BAR; PG8_SCHED;
	s_add_i32 s2, s12, s0
	v_lshl_add_u64 v[204:205], v[204:205], 0, s[38:39]
	s_mov_b32 m0, s2
	ds_read_b128 v[200:203], v154 offset:49152
	ds_read_b128 v[208:211], v154 offset:50176
	ds_read_b128 v[214:217], v154 offset:51200
	ds_read_b128 v[230:233], v154 offset:52224
	ds_read_b128 v[234:237], v154 offset:53248
	ds_read_b128 v[238:241], v154 offset:54272
	ds_read_b128 v[242:245], v154 offset:55296
	ds_read_b128 v[246:249], v154 offset:56320
	global_load_lds_dwordx4 v[204:205], off
	s_add_i32 m0, s2, 0x2000
	s_add_u32 s2, s74, 0x20080
	v_lshl_add_u64 v[204:205], v[206:207], 0, s[38:39]
	s_addc_u32 s3, s75, 0
	s_add_i32 s12, s13, s0
	global_load_lds_dwordx4 v[204:205], off
	v_lshl_add_u64 v[204:205], s[2:3], 0, v[130:131]
	s_mov_b32 m0, s12
	s_nop 0
	global_load_lds_dwordx4 v[204:205], off
	v_lshl_add_u64 v[204:205], s[2:3], 0, v[134:135]
	s_add_i32 m0, s12, 0x2000
	s_nop 0
	global_load_lds_dwordx4 v[204:205], off
	v_lshl_add_u64 v[204:205], s[72:73], 0, v[128:129]
	s_mov_b32 m0, s8
	s_nop 0
	global_load_lds_dwordx4 v[204:205], off
	v_lshl_add_u64 v[204:205], s[72:73], 0, v[132:133]
	s_mov_b32 m0, s9
	s_nop 0
	global_load_lds_dwordx4 v[204:205], off
	s_waitcnt vmcnt(8)
	s_waitcnt lgkmcnt(0)
	s_barrier
	s_setprio 1
	s_waitcnt lgkmcnt(0)
	v_mfma_f32_16x16x32_bf16 v[60:63], v[168:171], v[200:203], v[60:63]
	v_mfma_f32_16x16x32_bf16 v[60:63], v[172:175], v[208:211], v[60:63]
	v_mfma_f32_16x16x32_bf16 v[56:59], v[176:179], v[200:203], v[56:59]
	v_mfma_f32_16x16x32_bf16 v[56:59], v[180:183], v[208:211], v[56:59]
	v_mfma_f32_16x16x32_bf16 v[52:55], v[168:171], v[214:217], v[52:55]
	v_mfma_f32_16x16x32_bf16 v[52:55], v[172:175], v[230:233], v[52:55]
	v_mfma_f32_16x16x32_bf16 v[48:51], v[176:179], v[214:217], v[48:51]
	v_mfma_f32_16x16x32_bf16 v[48:51], v[180:183], v[230:233], v[48:51]
	v_mfma_f32_16x16x32_bf16 v[44:47], v[168:171], v[234:237], v[44:47]
	v_mfma_f32_16x16x32_bf16 v[44:47], v[172:175], v[238:241], v[44:47]
	v_mfma_f32_16x16x32_bf16 v[36:39], v[176:179], v[234:237], v[36:39]
	v_mfma_f32_16x16x32_bf16 v[36:39], v[180:183], v[238:241], v[36:39]
	v_mfma_f32_16x16x32_bf16 v[28:31], v[168:171], v[242:245], v[28:31]
	v_mfma_f32_16x16x32_bf16 v[28:31], v[172:175], v[246:249], v[28:31]
	v_mfma_f32_16x16x32_bf16 v[20:23], v[176:179], v[242:245], v[20:23]
	v_mfma_f32_16x16x32_bf16 v[20:23], v[180:183], v[246:249], v[20:23]
	s_setprio 0
	s_setprio 1
	v_mfma_f32_16x16x32_bf16 v[40:43], v[184:187], v[200:203], v[40:43]
	v_mfma_f32_16x16x32_bf16 v[40:43], v[188:191], v[208:211], v[40:43]
	v_mfma_f32_16x16x32_bf16 v[32:35], v[192:195], v[200:203], v[32:35]
	v_mfma_f32_16x16x32_bf16 v[32:35], v[196:199], v[208:211], v[32:35]
	v_mfma_f32_16x16x32_bf16 v[24:27], v[184:187], v[214:217], v[24:27]
	v_mfma_f32_16x16x32_bf16 v[24:27], v[188:191], v[230:233], v[24:27]
	v_mfma_f32_16x16x32_bf16 v[16:19], v[192:195], v[214:217], v[16:19]
	v_mfma_f32_16x16x32_bf16 v[16:19], v[196:199], v[230:233], v[16:19]
	v_mfma_f32_16x16x32_bf16 v[12:15], v[184:187], v[234:237], v[12:15]
	v_mfma_f32_16x16x32_bf16 v[12:15], v[188:191], v[238:241], v[12:15]
	v_mfma_f32_16x16x32_bf16 v[8:11], v[192:195], v[234:237], v[8:11]
	v_mfma_f32_16x16x32_bf16 v[8:11], v[196:199], v[238:241], v[8:11]
	v_mfma_f32_16x16x32_bf16 v[4:7], v[184:187], v[242:245], v[4:7]
	v_mfma_f32_16x16x32_bf16 v[4:7], v[188:191], v[246:249], v[4:7]
	v_mfma_f32_16x16x32_bf16 v[0:3], v[192:195], v[242:245], v[0:3]
	v_mfma_f32_16x16x32_bf16 v[0:3], v[196:199], v[246:249], v[0:3]
	s_setprio 0
	s_barrier
	s_add_i32 vcc_lo, vcc_lo, 2
	s_add_u32 s94, s94, 0x100
	s_addc_u32 s95, s95, 0
	s_cmp_gt_u32 vcc_lo, 5
	s_cbranch_scc0 .LBB0_119
	s_and_b64 vcc, exec, s[30:31]
	s_cbranch_vccz .LBB0_122
	s_barrier

; #define PG8_STAGE(bufoff, gbase, voff) do { _Pragma("unroll") for (int _i = 0; _i < 2; ++_i) \
;         __builtin_amdgcn_global_load_lds((const unsigned*)((const char*)(gbase) + (voff)[_i]), (LAS unsigned*)(lds + (bufoff) + ldsw + _i * 8192), 16, 0, 0); } while (0)
; #define PG8_LDA(dst, b, h) do { _Pragma("unroll") for (int m = 0; m < 4; ++m) _Pragma("unroll") for (int k = 0; k < 2; ++k) dst[m][k] = *(const LAS bf16x8*)(lds + PG8_SA(b, h) + aoff + m * 2048 + k * 1024); } while (0)
; #define PG8_LDB(dst, b, h) do { _Pragma("unroll") for (int n = 0; n < 2; ++n) _Pragma("unroll") for (int k = 0; k < 2; ++k) dst[n][k] = *(const LAS bf16x8*)(lds + PG8_SB(b, h) + boff + n * 2048 + k * 1024); } while (0)
; #define PG8_MMA(ai, bj, At, Bt) do { __builtin_amdgcn_s_setprio(1); _Pragma("unroll") for (int m = 0; m < 4; ++m) _Pragma("unroll") for (int n = 0; n < 2; ++n) _Pragma("unroll") for (int k = 0; k < 2; ++k) \
;         acc[ai][bj][m][n] = __builtin_amdgcn_mfma_f32_16x16x32_bf16(Bt[n][k], At[m][k], acc[ai][bj][m][n], 0, 0, 0); __builtin_amdgcn_s_setprio(0); } while (0)
; #define PG8_WAIT_V(n) asm volatile("s_waitcnt vmcnt(" #n ")" ::: "memory")
; #define PG8_WAIT_L(n) asm volatile("s_waitcnt lgkmcnt(" #n ")" ::: "memory")
; #define PG8_BAR __builtin_amdgcn_s_barrier()
; #define PG8_SCHED __builtin_amdgcn_sched_barrier(0)
;     ...
;             const bool last = (t == nt - 2);
;             const char* a1 = PG8_ATILE(cA, cA2, t + 1);
;             const char* a2 = last ? nA : PG8_ATILE(cA, cA2, t + 2); const char* b2 = last ? nB : cB + (size_t)(t + 2) * 128;
;             const char* a3 = last ? nA + kA1 : PG8_ATILE(cA, cA2, t + 3); const char* b3 = b2 + kB1;
;             if constexpr (SP2) {
;             PG8_LDB(B0, 0, 0); PG8_LDB(B1, 0, 1); PG8_SCHED; PG8_LDA(At, 0, 0); PG8_STAGE(PG8_SA(1, 1), a1 + hA, voffA);
;             PG8_WAIT_V(8); PG8_WAIT_L(0); PG8_BAR; PG8_MMA(0, 0, At, B0); PG8_MMA(0, 1, At, B1); PG8_BAR; PG8_SCHED;
;             PG8_LDA(At, 0, 1); PG8_STAGE(PG8_SB(0, 0), b2, voffB); PG8_STAGE(PG8_SB(0, 1), b2 + hB, voffB); PG8_STAGE(PG8_SA(0, 0), a2, voffA);
;             PG8_WAIT_V(8); PG8_WAIT_L(0); PG8_BAR; PG8_MMA(1, 0, At, B0); PG8_MMA(1, 1, At, B1); PG8_BAR; PG8_SCHED;
.LBB0_155:
	s_add_u32 s29, s34, s44
	s_addc_u32 s36, s35, s45
	s_add_u32 s54, s29, 0x800000
	s_addc_u32 s55, s36, 0
	s_add_u32 s29, s29, 0xc00000
	s_addc_u32 s36, s36, 0
	s_add_i32 s82, 0, 0x10000
	s_add_i32 s83, 0, 0x14000
	v_add_u32_e32 v168, s82, v180
	v_add_u32_e32 v183, s83, v180
	ds_read_b128 v[120:123], v168
	ds_read_b128 v[132:135], v168 offset:1024
	ds_read_b128 v[140:143], v168 offset:2048
	ds_read_b128 v[168:171], v168 offset:3072
	ds_read_b128 v[172:175], v183
	ds_read_b128 v[176:179], v183 offset:1024
	ds_read_b128 v[184:187], v183 offset:2048
	ds_read_b128 v[188:191], v183 offset:3072
	s_cmp_eq_u32 s44, 0x3800000
	s_cselect_b32 s53, s8, s36
	s_cselect_b32 s52, s7, s29
	s_cselect_b32 s73, s5, s17
	s_cselect_b32 s72, s6, s9
	s_cselect_b32 s75, s1, s55
	s_cselect_b32 s74, s4, s54
	v_lshl_add_u64 v[204:205], v[110:111], 0, s[44:45]
	s_add_i32 m0, s78, 0xc000
	ds_read_b128 v[192:195], v182
	ds_read_b128 v[196:199], v182 offset:1024
	ds_read_b128 v[200:203], v182 offset:2048
	ds_read_b128 v[208:211], v182 offset:3072
	ds_read_b128 v[214:217], v182 offset:4096
	ds_read_b128 v[230:233], v182 offset:5120
	ds_read_b128 v[234:237], v182 offset:6144
	ds_read_b128 v[238:241], v182 offset:7168
	global_load_lds_dwordx4 v[204:205], off
	v_lshl_add_u64 v[204:205], v[108:109], 0, s[44:45]
	s_add_i32 m0, s78, 0xe000
	s_nop 0
	global_load_lds_dwordx4 v[204:205], off
	s_waitcnt vmcnt(8)
	s_waitcnt lgkmcnt(0)
	s_barrier
	s_setprio 1
	s_waitcnt lgkmcnt(0)
	v_mfma_f32_16x16x32_bf16 v[136:139], v[120:123], v[192:195], v[136:139]
	v_mfma_f32_16x16x32_bf16 v[136:139], v[132:135], v[196:199], v[136:139]
	v_mfma_f32_16x16x32_bf16 v[128:131], v[140:143], v[192:195], v[128:131]
	v_mfma_f32_16x16x32_bf16 v[128:131], v[168:171], v[196:199], v[128:131]
	v_mfma_f32_16x16x32_bf16 v[112:115], v[120:123], v[200:203], v[112:115]
	v_mfma_f32_16x16x32_bf16 v[112:115], v[132:135], v[208:211], v[112:115]
	v_mfma_f32_16x16x32_bf16 v[104:107], v[140:143], v[200:203], v[104:107]
	v_mfma_f32_16x16x32_bf16 v[104:107], v[168:171], v[208:211], v[104:107]
	v_mfma_f32_16x16x32_bf16 v[92:95], v[120:123], v[214:217], v[92:95]
	v_mfma_f32_16x16x32_bf16 v[92:95], v[132:135], v[230:233], v[92:95]
	v_mfma_f32_16x16x32_bf16 v[88:91], v[140:143], v[214:217], v[88:91]
	v_mfma_f32_16x16x32_bf16 v[88:91], v[168:171], v[230:233], v[88:91]
	v_mfma_f32_16x16x32_bf16 v[76:79], v[120:123], v[234:237], v[76:79]
	v_mfma_f32_16x16x32_bf16 v[76:79], v[132:135], v[238:241], v[76:79]
	v_mfma_f32_16x16x32_bf16 v[72:75], v[140:143], v[234:237], v[72:75]
	v_mfma_f32_16x16x32_bf16 v[72:75], v[168:171], v[238:241], v[72:75]
	s_setprio 0
	s_setprio 1
	v_mfma_f32_16x16x32_bf16 v[124:127], v[172:175], v[192:195], v[124:127]
	v_mfma_f32_16x16x32_bf16 v[124:127], v[176:179], v[196:199], v[124:127]
	v_mfma_f32_16x16x32_bf16 v[116:119], v[184:187], v[192:195], v[116:119]
	v_mfma_f32_16x16x32_bf16 v[116:119], v[188:191], v[196:199], v[116:119]
	v_mfma_f32_16x16x32_bf16 v[100:103], v[172:175], v[200:203], v[100:103]
	v_mfma_f32_16x16x32_bf16 v[100:103], v[176:179], v[208:211], v[100:103]
	v_mfma_f32_16x16x32_bf16 v[96:99], v[184:187], v[200:203], v[96:99]
	v_mfma_f32_16x16x32_bf16 v[96:99], v[188:191], v[208:211], v[96:99]
	v_mfma_f32_16x16x32_bf16 v[84:87], v[172:175], v[214:217], v[84:87]
	v_mfma_f32_16x16x32_bf16 v[84:87], v[176:179], v[230:233], v[84:87]
	v_mfma_f32_16x16x32_bf16 v[80:83], v[184:187], v[214:217], v[80:83]
	v_mfma_f32_16x16x32_bf16 v[80:83], v[188:191], v[230:233], v[80:83]
	v_mfma_f32_16x16x32_bf16 v[68:71], v[172:175], v[234:237], v[68:71]
	v_mfma_f32_16x16x32_bf16 v[68:71], v[176:179], v[238:241], v[68:71]
	v_mfma_f32_16x16x32_bf16 v[64:67], v[184:187], v[234:237], v[64:67]
	v_mfma_f32_16x16x32_bf16 v[64:67], v[188:191], v[238:241], v[64:67]
	s_setprio 0
	s_barrier
	s_add_i32 s29, s82, s77
	v_lshl_add_u64 v[204:205], s[72:73], 0, v[146:147]
	s_mov_b32 m0, s29
	ds_read_b128 v[192:195], v182 offset:16384
	ds_read_b128 v[196:199], v182 offset:17408
	ds_read_b128 v[200:203], v182 offset:18432
	ds_read_b128 v[208:211], v182 offset:19456
	ds_read_b128 v[214:217], v182 offset:20480
	ds_read_b128 v[230:233], v182 offset:21504
	ds_read_b128 v[234:237], v182 offset:22528
	ds_read_b128 v[238:241], v182 offset:23552
	global_load_lds_dwordx4 v[204:205], off
	s_add_i32 m0, s29, 0x2000
	s_add_u32 s54, s72, 0x40000
	v_lshl_add_u64 v[206:207], s[72:73], 0, v[150:151]
	s_addc_u32 s55, s73, 0
	s_add_i32 s29, s83, s77
	global_load_lds_dwordx4 v[206:207], off
	v_lshl_add_u64 v[242:243], s[54:55], 0, v[146:147]
	s_mov_b32 m0, s29
	s_nop 0
	global_load_lds_dwordx4 v[242:243], off
	v_lshl_add_u64 v[242:243], s[54:55], 0, v[150:151]
	s_add_i32 m0, s29, 0x2000
	s_nop 0
	global_load_lds_dwordx4 v[242:243], off
	v_lshl_add_u64 v[242:243], s[74:75], 0, v[144:145]
	s_mov_b32 m0, s78
	s_nop 0
	global_load_lds_dwordx4 v[242:243], off
	v_lshl_add_u64 v[242:243], s[74:75], 0, v[148:149]
	s_mov_b32 m0, s79
	s_nop 0
	global_load_lds_dwordx4 v[242:243], off
	s_waitcnt vmcnt(8)
	s_waitcnt lgkmcnt(0)
	s_barrier
; #define PG8_STAGE(bufoff, gbase, voff) do { _Pragma("unroll") for (int _i = 0; _i < 2; ++_i) \
;         __builtin_amdgcn_global_load_lds((const unsigned*)((const char*)(gbase) + (voff)[_i]), (LAS unsigned*)(lds + (bufoff) + ldsw + _i * 8192), 16, 0, 0); } while (0)
; #define PG8_LDA(dst, b, h) do { _Pragma("unroll") for (int m = 0; m < 4; ++m) _Pragma("unroll") for (int k = 0; k < 2; ++k) dst[m][k] = *(const LAS bf16x8*)(lds + PG8_SA(b, h) + aoff + m * 2048 + k * 1024); } while (0)
; #define PG8_LDB(dst, b, h) do { _Pragma("unroll") for (int n = 0; n < 2; ++n) _Pragma("unroll") for (int k = 0; k < 2; ++k) dst[n][k] = *(const LAS bf16x8*)(lds + PG8_SB(b, h) + boff + n * 2048 + k * 1024); } while (0)
; #define PG8_MMA(ai, bj, At, Bt) do { __builtin_amdgcn_s_setprio(1); _Pragma("unroll") for (int m = 0; m < 4; ++m) _Pragma("unroll") for (int n = 0; n < 2; ++n) _Pragma("unroll") for (int k = 0; k < 2; ++k) \
;         acc[ai][bj][m][n] = __builtin_amdgcn_mfma_f32_16x16x32_bf16(Bt[n][k], At[m][k], acc[ai][bj][m][n], 0, 0, 0); __builtin_amdgcn_s_setprio(0); } while (0)
; #define PG8_WAIT_V(n) asm volatile("s_waitcnt vmcnt(" #n ")" ::: "memory")
; #define PG8_WAIT_L(n) asm volatile("s_waitcnt lgkmcnt(" #n ")" ::: "memory")
; #define PG8_BAR __builtin_amdgcn_s_barrier()
; #define PG8_SCHED __builtin_amdgcn_sched_barrier(0)
;     ...
;             PG8_WAIT_V(8); PG8_WAIT_L(0); PG8_BAR; PG8_MMA(1, 0, At, B0); PG8_MMA(1, 1, At, B1); PG8_BAR; PG8_SCHED;
;             PG8_LDB(B0, 1, 0); PG8_LDB(B1, 1, 1); PG8_SCHED; PG8_LDA(At, 1, 0); PG8_STAGE(PG8_SA(0, 1), a2 + hA, voffA);
;             PG8_WAIT_V(8); PG8_WAIT_L(0); PG8_BAR; PG8_MMA(0, 0, At, B0); PG8_MMA(0, 1, At, B1); PG8_BAR; PG8_SCHED;
	s_setprio 1
	s_waitcnt lgkmcnt(0)
	v_mfma_f32_16x16x32_bf16 v[60:63], v[120:123], v[192:195], v[60:63]
	v_mfma_f32_16x16x32_bf16 v[60:63], v[132:135], v[196:199], v[60:63]
	v_mfma_f32_16x16x32_bf16 v[56:59], v[140:143], v[192:195], v[56:59]
	v_mfma_f32_16x16x32_bf16 v[56:59], v[168:171], v[196:199], v[56:59]
	v_mfma_f32_16x16x32_bf16 v[44:47], v[120:123], v[200:203], v[44:47]
	v_mfma_f32_16x16x32_bf16 v[44:47], v[132:135], v[208:211], v[44:47]
	v_mfma_f32_16x16x32_bf16 v[40:43], v[140:143], v[200:203], v[40:43]
	v_mfma_f32_16x16x32_bf16 v[40:43], v[168:171], v[208:211], v[40:43]
	v_mfma_f32_16x16x32_bf16 v[28:31], v[120:123], v[214:217], v[28:31]
	v_mfma_f32_16x16x32_bf16 v[28:31], v[132:135], v[230:233], v[28:31]
	v_mfma_f32_16x16x32_bf16 v[24:27], v[140:143], v[214:217], v[24:27]
	v_mfma_f32_16x16x32_bf16 v[24:27], v[168:171], v[230:233], v[24:27]
	v_mfma_f32_16x16x32_bf16 v[12:15], v[120:123], v[234:237], v[12:15]
	v_mfma_f32_16x16x32_bf16 v[12:15], v[132:135], v[238:241], v[12:15]
	v_mfma_f32_16x16x32_bf16 v[8:11], v[140:143], v[234:237], v[8:11]
	v_mfma_f32_16x16x32_bf16 v[8:11], v[168:171], v[238:241], v[8:11]
	s_setprio 0
	s_setprio 1
	v_mfma_f32_16x16x32_bf16 v[52:55], v[172:175], v[192:195], v[52:55]
	v_mfma_f32_16x16x32_bf16 v[52:55], v[176:179], v[196:199], v[52:55]
	v_mfma_f32_16x16x32_bf16 v[48:51], v[184:187], v[192:195], v[48:51]
	v_mfma_f32_16x16x32_bf16 v[48:51], v[188:191], v[196:199], v[48:51]
	v_mfma_f32_16x16x32_bf16 v[36:39], v[172:175], v[200:203], v[36:39]
	v_mfma_f32_16x16x32_bf16 v[36:39], v[176:179], v[208:211], v[36:39]
	v_mfma_f32_16x16x32_bf16 v[32:35], v[184:187], v[200:203], v[32:35]
	v_mfma_f32_16x16x32_bf16 v[32:35], v[188:191], v[208:211], v[32:35]
	v_mfma_f32_16x16x32_bf16 v[20:23], v[172:175], v[214:217], v[20:23]
	v_mfma_f32_16x16x32_bf16 v[20:23], v[176:179], v[230:233], v[20:23]
	v_mfma_f32_16x16x32_bf16 v[16:19], v[184:187], v[214:217], v[16:19]
	v_mfma_f32_16x16x32_bf16 v[16:19], v[188:191], v[230:233], v[16:19]
	v_mfma_f32_16x16x32_bf16 v[4:7], v[172:175], v[234:237], v[4:7]
	v_mfma_f32_16x16x32_bf16 v[4:7], v[176:179], v[238:241], v[4:7]
	v_mfma_f32_16x16x32_bf16 v[0:3], v[184:187], v[234:237], v[0:3]
	v_mfma_f32_16x16x32_bf16 v[0:3], v[188:191], v[238:241], v[0:3]
	s_setprio 0
	s_barrier
	s_add_i32 s29, 0, 0x18000
	s_add_i32 s36, 0, 0x1c000
	v_add_u32_e32 v168, s29, v180
	v_add_u32_e32 v183, s36, v180
	ds_read_b128 v[120:123], v168
	ds_read_b128 v[132:135], v168 offset:1024
	ds_read_b128 v[140:143], v168 offset:2048
	ds_read_b128 v[168:171], v168 offset:3072
	ds_read_b128 v[172:175], v183
	ds_read_b128 v[176:179], v183 offset:1024
	ds_read_b128 v[184:187], v183 offset:2048
	ds_read_b128 v[188:191], v183 offset:3072
	s_add_u32 s54, s74, 0x1000
	s_addc_u32 s55, s75, 0
	s_mov_b32 m0, s80
	v_lshl_add_u64 v[242:243], s[54:55], 0, v[144:145]
	ds_read_b128 v[192:195], v182 offset:32768
	ds_read_b128 v[196:199], v182 offset:33792
	ds_read_b128 v[200:203], v182 offset:34816
	ds_read_b128 v[208:211], v182 offset:35840
	ds_read_b128 v[214:217], v182 offset:36864
	ds_read_b128 v[230:233], v182 offset:37888
	ds_read_b128 v[234:237], v182 offset:38912
	ds_read_b128 v[238:241], v182 offset:39936
	global_load_lds_dwordx4 v[242:243], off
	v_lshl_add_u64 v[242:243], s[54:55], 0, v[148:149]
	s_mov_b32 m0, s81
	s_nop 0
	global_load_lds_dwordx4 v[242:243], off
	s_waitcnt vmcnt(8)
	s_waitcnt lgkmcnt(0)
	s_barrier
	s_setprio 1
	s_waitcnt lgkmcnt(0)
	v_mfma_f32_16x16x32_bf16 v[136:139], v[120:123], v[192:195], v[136:139]
	v_mfma_f32_16x16x32_bf16 v[136:139], v[132:135], v[196:199], v[136:139]
	v_mfma_f32_16x16x32_bf16 v[128:131], v[140:143], v[192:195], v[128:131]
	v_mfma_f32_16x16x32_bf16 v[128:131], v[168:171], v[196:199], v[128:131]
	v_mfma_f32_16x16x32_bf16 v[112:115], v[120:123], v[200:203], v[112:115]
	v_mfma_f32_16x16x32_bf16 v[112:115], v[132:135], v[208:211], v[112:115]
	v_mfma_f32_16x16x32_bf16 v[104:107], v[140:143], v[200:203], v[104:107]
	v_mfma_f32_16x16x32_bf16 v[104:107], v[168:171], v[208:211], v[104:107]
	v_mfma_f32_16x16x32_bf16 v[92:95], v[120:123], v[214:217], v[92:95]
	v_mfma_f32_16x16x32_bf16 v[92:95], v[132:135], v[230:233], v[92:95]
	v_mfma_f32_16x16x32_bf16 v[88:91], v[140:143], v[214:217], v[88:91]
	v_mfma_f32_16x16x32_bf16 v[88:91], v[168:171], v[230:233], v[88:91]
	v_mfma_f32_16x16x32_bf16 v[76:79], v[120:123], v[234:237], v[76:79]
	v_mfma_f32_16x16x32_bf16 v[76:79], v[132:135], v[238:241], v[76:79]
	v_mfma_f32_16x16x32_bf16 v[72:75], v[140:143], v[234:237], v[72:75]
	v_mfma_f32_16x16x32_bf16 v[72:75], v[168:171], v[238:241], v[72:75]
	s_setprio 0
	s_setprio 1
	v_mfma_f32_16x16x32_bf16 v[124:127], v[172:175], v[192:195], v[124:127]
	v_mfma_f32_16x16x32_bf16 v[124:127], v[176:179], v[196:199], v[124:127]
	v_mfma_f32_16x16x32_bf16 v[116:119], v[184:187], v[192:195], v[116:119]
	v_mfma_f32_16x16x32_bf16 v[116:119], v[188:191], v[196:199], v[116:119]
	v_mfma_f32_16x16x32_bf16 v[100:103], v[172:175], v[200:203], v[100:103]
	v_mfma_f32_16x16x32_bf16 v[100:103], v[176:179], v[208:211], v[100:103]
	v_mfma_f32_16x16x32_bf16 v[96:99], v[184:187], v[200:203], v[96:99]
	v_mfma_f32_16x16x32_bf16 v[96:99], v[188:191], v[208:211], v[96:99]
	v_mfma_f32_16x16x32_bf16 v[84:87], v[172:175], v[214:217], v[84:87]
	v_mfma_f32_16x16x32_bf16 v[84:87], v[176:179], v[230:233], v[84:87]
	v_mfma_f32_16x16x32_bf16 v[80:83], v[184:187], v[214:217], v[80:83]
	v_mfma_f32_16x16x32_bf16 v[80:83], v[188:191], v[230:233], v[80:83]
	v_mfma_f32_16x16x32_bf16 v[68:71], v[172:175], v[234:237], v[68:71]
	v_mfma_f32_16x16x32_bf16 v[68:71], v[176:179], v[238:241], v[68:71]
	v_mfma_f32_16x16x32_bf16 v[64:67], v[184:187], v[234:237], v[64:67]
	v_mfma_f32_16x16x32_bf16 v[64:67], v[188:191], v[238:241], v[64:67]
	s_setprio 0
	s_barrier
; #define PG8_STAGE(bufoff, gbase, voff) do { _Pragma("unroll") for (int _i = 0; _i < 2; ++_i) \
;         __builtin_amdgcn_global_load_lds((const unsigned*)((const char*)(gbase) + (voff)[_i]), (LAS unsigned*)(lds + (bufoff) + ldsw + _i * 8192), 16, 0, 0); } while (0)
; #define PG8_LDA(dst, b, h) do { _Pragma("unroll") for (int m = 0; m < 4; ++m) _Pragma("unroll") for (int k = 0; k < 2; ++k) dst[m][k] = *(const LAS bf16x8*)(lds + PG8_SA(b, h) + aoff + m * 2048 + k * 1024); } while (0)
; #define PG8_MMA(ai, bj, At, Bt) do { __builtin_amdgcn_s_setprio(1); _Pragma("unroll") for (int m = 0; m < 4; ++m) _Pragma("unroll") for (int n = 0; n < 2; ++n) _Pragma("unroll") for (int k = 0; k < 2; ++k) \
;         acc[ai][bj][m][n] = __builtin_amdgcn_mfma_f32_16x16x32_bf16(Bt[n][k], At[m][k], acc[ai][bj][m][n], 0, 0, 0); __builtin_amdgcn_s_setprio(0); } while (0)
; #define PG8_WAIT_V(n) asm volatile("s_waitcnt vmcnt(" #n ")" ::: "memory")
; #define PG8_WAIT_L(n) asm volatile("s_waitcnt lgkmcnt(" #n ")" ::: "memory")
; #define PG8_BAR __builtin_amdgcn_s_barrier()
; #define PG8_SCHED __builtin_amdgcn_sched_barrier(0)
;     ...
;         for (int t = 0; t < nt; t += 2) {
;     ...
;             PG8_LDA(At, 1, 1); PG8_STAGE(PG8_SB(1, 0), b3, voffB); PG8_STAGE(PG8_SB(1, 1), b3 + hB, voffB); PG8_STAGE(PG8_SA(1, 0), a3, voffA);
;             PG8_WAIT_V(8); PG8_WAIT_L(0); PG8_BAR; PG8_MMA(1, 0, At, B0); PG8_MMA(1, 1, At, B1); PG8_BAR; PG8_SCHED;
	s_add_i32 s29, s29, s77
	v_lshl_add_u64 v[204:205], v[204:205], 0, s[38:39]
	s_mov_b32 m0, s29
	ds_read_b128 v[192:195], v182 offset:49152
	ds_read_b128 v[196:199], v182 offset:50176
	ds_read_b128 v[200:203], v182 offset:51200
	ds_read_b128 v[208:211], v182 offset:52224
	ds_read_b128 v[214:217], v182 offset:53248
	ds_read_b128 v[230:233], v182 offset:54272
	ds_read_b128 v[234:237], v182 offset:55296
	ds_read_b128 v[238:241], v182 offset:56320
	global_load_lds_dwordx4 v[204:205], off
	s_add_i32 m0, s29, 0x2000
	s_add_u32 s54, s72, 0x40080
	v_lshl_add_u64 v[204:205], v[206:207], 0, s[38:39]
	s_addc_u32 s55, s73, 0
	s_add_i32 s29, s36, s77
	global_load_lds_dwordx4 v[204:205], off
	v_lshl_add_u64 v[204:205], s[54:55], 0, v[146:147]
	s_mov_b32 m0, s29
	s_nop 0
	global_load_lds_dwordx4 v[204:205], off
	v_lshl_add_u64 v[204:205], s[54:55], 0, v[150:151]
	s_add_i32 m0, s29, 0x2000
	s_nop 0
	global_load_lds_dwordx4 v[204:205], off
	v_lshl_add_u64 v[204:205], s[52:53], 0, v[144:145]
	s_mov_b32 m0, s89
	s_nop 0
	global_load_lds_dwordx4 v[204:205], off
	v_lshl_add_u64 v[204:205], s[52:53], 0, v[148:149]
	s_mov_b32 m0, s90
	s_nop 0
	global_load_lds_dwordx4 v[204:205], off
	s_waitcnt vmcnt(8)
	s_waitcnt lgkmcnt(0)
	s_barrier
	s_setprio 1
	s_waitcnt lgkmcnt(0)
	v_mfma_f32_16x16x32_bf16 v[60:63], v[120:123], v[192:195], v[60:63]
	v_mfma_f32_16x16x32_bf16 v[60:63], v[132:135], v[196:199], v[60:63]
	v_mfma_f32_16x16x32_bf16 v[56:59], v[140:143], v[192:195], v[56:59]
	v_mfma_f32_16x16x32_bf16 v[56:59], v[168:171], v[196:199], v[56:59]
	v_mfma_f32_16x16x32_bf16 v[44:47], v[120:123], v[200:203], v[44:47]
	v_mfma_f32_16x16x32_bf16 v[44:47], v[132:135], v[208:211], v[44:47]
	v_mfma_f32_16x16x32_bf16 v[40:43], v[140:143], v[200:203], v[40:43]
	v_mfma_f32_16x16x32_bf16 v[40:43], v[168:171], v[208:211], v[40:43]
	v_mfma_f32_16x16x32_bf16 v[28:31], v[120:123], v[214:217], v[28:31]
	v_mfma_f32_16x16x32_bf16 v[28:31], v[132:135], v[230:233], v[28:31]
	v_mfma_f32_16x16x32_bf16 v[24:27], v[140:143], v[214:217], v[24:27]
	v_mfma_f32_16x16x32_bf16 v[24:27], v[168:171], v[230:233], v[24:27]
	v_mfma_f32_16x16x32_bf16 v[12:15], v[120:123], v[234:237], v[12:15]
	v_mfma_f32_16x16x32_bf16 v[12:15], v[132:135], v[238:241], v[12:15]
	v_mfma_f32_16x16x32_bf16 v[8:11], v[140:143], v[234:237], v[8:11]
	v_mfma_f32_16x16x32_bf16 v[8:11], v[168:171], v[238:241], v[8:11]
	s_setprio 0
	s_setprio 1
	v_mfma_f32_16x16x32_bf16 v[52:55], v[172:175], v[192:195], v[52:55]
	v_mfma_f32_16x16x32_bf16 v[52:55], v[176:179], v[196:199], v[52:55]
	v_mfma_f32_16x16x32_bf16 v[48:51], v[184:187], v[192:195], v[48:51]
	v_mfma_f32_16x16x32_bf16 v[48:51], v[188:191], v[196:199], v[48:51]
	v_mfma_f32_16x16x32_bf16 v[36:39], v[172:175], v[200:203], v[36:39]
	v_mfma_f32_16x16x32_bf16 v[36:39], v[176:179], v[208:211], v[36:39]
	v_mfma_f32_16x16x32_bf16 v[32:35], v[184:187], v[200:203], v[32:35]
	v_mfma_f32_16x16x32_bf16 v[32:35], v[188:191], v[208:211], v[32:35]
	v_mfma_f32_16x16x32_bf16 v[20:23], v[172:175], v[214:217], v[20:23]
	v_mfma_f32_16x16x32_bf16 v[20:23], v[176:179], v[230:233], v[20:23]
	v_mfma_f32_16x16x32_bf16 v[16:19], v[184:187], v[214:217], v[16:19]
	v_mfma_f32_16x16x32_bf16 v[16:19], v[188:191], v[230:233], v[16:19]
	v_mfma_f32_16x16x32_bf16 v[4:7], v[172:175], v[234:237], v[4:7]
	v_mfma_f32_16x16x32_bf16 v[4:7], v[176:179], v[238:241], v[4:7]
	v_mfma_f32_16x16x32_bf16 v[0:3], v[184:187], v[234:237], v[0:3]
	v_mfma_f32_16x16x32_bf16 v[0:3], v[188:191], v[238:241], v[0:3]
	s_setprio 0
	s_barrier
	s_add_i32 s27, s27, 2
	s_add_u32 s9, s9, 0x100
	s_addc_u32 s17, s17, 0
	s_add_u32 s44, s44, 0x800000
	s_addc_u32 s45, s45, 0
	s_cmp_gt_u32 s27, 13
	s_cbranch_scc0 .LBB0_155
	s_and_b64 vcc, exec, s[14:15]
	s_cbranch_vccz .LBB0_158
	s_barrier

; #define PG8_STAGE(bufoff, gbase, voff) do { _Pragma("unroll") for (int _i = 0; _i < 2; ++_i) \
;         __builtin_amdgcn_global_load_lds((const unsigned*)((const char*)(gbase) + (voff)[_i]), (LAS unsigned*)(lds + (bufoff) + ldsw + _i * 8192), 16, 0, 0); } while (0)
; #define PG8_LDA(dst, b, h) do { _Pragma("unroll") for (int m = 0; m < 4; ++m) _Pragma("unroll") for (int k = 0; k < 2; ++k) dst[m][k] = *(const LAS bf16x8*)(lds + PG8_SA(b, h) + aoff + m * 2048 + k * 1024); } while (0)
; #define PG8_LDB(dst, b, h) do { _Pragma("unroll") for (int n = 0; n < 2; ++n) _Pragma("unroll") for (int k = 0; k < 2; ++k) dst[n][k] = *(const LAS bf16x8*)(lds + PG8_SB(b, h) + boff + n * 2048 + k * 1024); } while (0)
; #define PG8_MMA(ai, bj, At, Bt) do { __builtin_amdgcn_s_setprio(1); _Pragma("unroll") for (int m = 0; m < 4; ++m) _Pragma("unroll") for (int n = 0; n < 2; ++n) _Pragma("unroll") for (int k = 0; k < 2; ++k) \
;         acc[ai][bj][m][n] = __builtin_amdgcn_mfma_f32_16x16x32_bf16(Bt[n][k], At[m][k], acc[ai][bj][m][n], 0, 0, 0); __builtin_amdgcn_s_setprio(0); } while (0)
; #define PG8_WAIT_V(n) asm volatile("s_waitcnt vmcnt(" #n ")" ::: "memory")
; #define PG8_WAIT_L(n) asm volatile("s_waitcnt lgkmcnt(" #n ")" ::: "memory")
; #define PG8_BAR __builtin_amdgcn_s_barrier()
; #define PG8_SCHED __builtin_amdgcn_sched_barrier(0)
;     ...
;             const bool last = (t == nt - 2);
;             const char* a1 = PG8_ATILE(cA, cA2, t + 1);
;             const char* a2 = last ? nA : PG8_ATILE(cA, cA2, t + 2); const char* b2 = last ? nB : cB + (size_t)(t + 2) * 128;
;             const char* a3 = last ? nA + kA1 : PG8_ATILE(cA, cA2, t + 3); const char* b3 = b2 + kB1;
;             if constexpr (SP2) {
;             PG8_LDB(B0, 0, 0); PG8_LDB(B1, 0, 1); PG8_SCHED; PG8_LDA(At, 0, 0); PG8_STAGE(PG8_SA(1, 1), a1 + hA, voffA);
;             PG8_WAIT_V(8); PG8_WAIT_L(0); PG8_BAR; PG8_MMA(0, 0, At, B0); PG8_MMA(0, 1, At, B1); PG8_BAR; PG8_SCHED;
;             PG8_LDA(At, 0, 1); PG8_STAGE(PG8_SB(0, 0), b2, voffB); PG8_STAGE(PG8_SB(0, 1), b2 + hB, voffB); PG8_STAGE(PG8_SA(0, 0), a2, voffA);
;             PG8_WAIT_V(8); PG8_WAIT_L(0); PG8_BAR; PG8_MMA(1, 0, At, B0); PG8_MMA(1, 1, At, B1); PG8_BAR; PG8_SCHED;
.LBB0_191:
	s_add_u32 s72, s44, s52
	s_addc_u32 s73, s45, s53
	s_add_u32 s76, s72, 0x100
	s_addc_u32 s77, s73, 0
	s_add_u32 s74, s80, s52
	s_addc_u32 s75, s81, s53
	s_add_u32 s72, s72, 0x180
	s_addc_u32 s73, s73, 0
	s_add_i32 s83, 0, 0x10000
	s_add_i32 s89, 0, 0x14000
	v_add_u32_e32 v146, s83, v150
	ds_read_b128 v[100:103], v146
	ds_read_b128 v[168:171], v146 offset:1024
	ds_read_b128 v[172:175], v146 offset:2048
	ds_read_b128 v[176:179], v146 offset:3072
	v_add_u32_e32 v146, s89, v150
	ds_read_b128 v[180:183], v146
	ds_read_b128 v[184:187], v146 offset:1024
	ds_read_b128 v[188:191], v146 offset:2048
	ds_read_b128 v[192:195], v146 offset:3072
	s_cmpk_eq_i32 s52, 0x700
	s_cselect_b32 s73, s79, s73
	s_cselect_b32 s72, s78, s72
	s_cselect_b32 s75, s17, s75
	s_cselect_b32 s74, s55, s74
	s_cselect_b32 s77, s27, s77
	s_cselect_b32 s76, s54, s76
	v_lshl_add_u64 v[146:147], v[96:97], 0, s[52:53]
	s_add_i32 m0, s6, 0xc000
	ds_read_b128 v[196:199], v154
	ds_read_b128 v[200:203], v154 offset:1024
	ds_read_b128 v[208:211], v154 offset:2048
	ds_read_b128 v[214:217], v154 offset:3072
	ds_read_b128 v[230:233], v154 offset:4096
	ds_read_b128 v[234:237], v154 offset:5120
	ds_read_b128 v[238:241], v154 offset:6144
	ds_read_b128 v[242:245], v154 offset:7168
	global_load_lds_dwordx4 v[146:147], off
	v_lshl_add_u64 v[146:147], v[98:99], 0, s[52:53]
	s_add_i32 m0, s6, 0xe000
	s_nop 0
	global_load_lds_dwordx4 v[146:147], off
	s_waitcnt vmcnt(8)
	s_waitcnt lgkmcnt(0)
	s_barrier
	s_setprio 1
	s_waitcnt lgkmcnt(0)
	v_mfma_f32_16x16x32_bf16 v[132:135], v[100:103], v[196:199], v[132:135]
	v_mfma_f32_16x16x32_bf16 v[132:135], v[168:171], v[200:203], v[132:135]
	v_mfma_f32_16x16x32_bf16 v[128:131], v[172:175], v[196:199], v[128:131]
	v_mfma_f32_16x16x32_bf16 v[128:131], v[176:179], v[200:203], v[128:131]
	v_mfma_f32_16x16x32_bf16 v[124:127], v[100:103], v[208:211], v[124:127]
	v_mfma_f32_16x16x32_bf16 v[124:127], v[168:171], v[214:217], v[124:127]
	v_mfma_f32_16x16x32_bf16 v[120:123], v[172:175], v[208:211], v[120:123]
	v_mfma_f32_16x16x32_bf16 v[120:123], v[176:179], v[214:217], v[120:123]
	v_mfma_f32_16x16x32_bf16 v[116:119], v[100:103], v[230:233], v[116:119]
	v_mfma_f32_16x16x32_bf16 v[116:119], v[168:171], v[234:237], v[116:119]
	v_mfma_f32_16x16x32_bf16 v[112:115], v[172:175], v[230:233], v[112:115]
	v_mfma_f32_16x16x32_bf16 v[112:115], v[176:179], v[234:237], v[112:115]
	v_mfma_f32_16x16x32_bf16 v[108:111], v[100:103], v[238:241], v[108:111]
	v_mfma_f32_16x16x32_bf16 v[108:111], v[168:171], v[242:245], v[108:111]
	v_mfma_f32_16x16x32_bf16 v[104:107], v[172:175], v[238:241], v[104:107]
	v_mfma_f32_16x16x32_bf16 v[104:107], v[176:179], v[242:245], v[104:107]
	s_setprio 0
	s_setprio 1
	v_mfma_f32_16x16x32_bf16 v[68:71], v[180:183], v[196:199], v[68:71]
	v_mfma_f32_16x16x32_bf16 v[68:71], v[184:187], v[200:203], v[68:71]
	v_mfma_f32_16x16x32_bf16 v[56:59], v[188:191], v[196:199], v[56:59]
	v_mfma_f32_16x16x32_bf16 v[56:59], v[192:195], v[200:203], v[56:59]
	v_mfma_f32_16x16x32_bf16 v[52:55], v[180:183], v[208:211], v[52:55]
	v_mfma_f32_16x16x32_bf16 v[52:55], v[184:187], v[214:217], v[52:55]
	v_mfma_f32_16x16x32_bf16 v[48:51], v[188:191], v[208:211], v[48:51]
	v_mfma_f32_16x16x32_bf16 v[48:51], v[192:195], v[214:217], v[48:51]
	v_mfma_f32_16x16x32_bf16 v[44:47], v[180:183], v[230:233], v[44:47]
	v_mfma_f32_16x16x32_bf16 v[44:47], v[184:187], v[234:237], v[44:47]
	v_mfma_f32_16x16x32_bf16 v[40:43], v[188:191], v[230:233], v[40:43]
	v_mfma_f32_16x16x32_bf16 v[40:43], v[192:195], v[234:237], v[40:43]
	v_mfma_f32_16x16x32_bf16 v[36:39], v[180:183], v[238:241], v[36:39]
	v_mfma_f32_16x16x32_bf16 v[36:39], v[184:187], v[242:245], v[36:39]
	v_mfma_f32_16x16x32_bf16 v[32:35], v[188:191], v[238:241], v[32:35]
	v_mfma_f32_16x16x32_bf16 v[32:35], v[192:195], v[242:245], v[32:35]
	s_setprio 0
	s_barrier
	s_add_i32 s83, s83, s5
	v_lshl_add_u64 v[146:147], s[74:75], 0, v[156:157]
	s_mov_b32 m0, s83
	ds_read_b128 v[196:199], v154 offset:16384
	ds_read_b128 v[200:203], v154 offset:17408
	ds_read_b128 v[208:211], v154 offset:18432
	ds_read_b128 v[214:217], v154 offset:19456
	ds_read_b128 v[230:233], v154 offset:20480
	ds_read_b128 v[234:237], v154 offset:21504
	ds_read_b128 v[238:241], v154 offset:22528
	ds_read_b128 v[242:245], v154 offset:23552
	global_load_lds_dwordx4 v[146:147], off
	s_add_i32 m0, s83, 0x2000
	s_add_u32 s90, s74, 0x40000
	v_lshl_add_u64 v[204:205], s[74:75], 0, v[140:141]
	s_addc_u32 s91, s75, 0
	s_add_i32 s83, s89, s5
	global_load_lds_dwordx4 v[204:205], off
	v_lshl_add_u64 v[206:207], s[90:91], 0, v[156:157]
	s_mov_b32 m0, s83
	s_nop 0
	global_load_lds_dwordx4 v[206:207], off
	v_lshl_add_u64 v[206:207], s[90:91], 0, v[140:141]
	s_add_i32 m0, s83, 0x2000
	s_nop 0
	global_load_lds_dwordx4 v[206:207], off
	v_lshl_add_u64 v[206:207], s[76:77], 0, v[136:137]
	s_mov_b32 m0, s6
	s_nop 0
	global_load_lds_dwordx4 v[206:207], off
	v_lshl_add_u64 v[206:207], s[76:77], 0, v[138:139]
	s_mov_b32 m0, s7
	s_nop 0
	global_load_lds_dwordx4 v[206:207], off
	s_waitcnt vmcnt(8)
	s_waitcnt lgkmcnt(0)
	s_barrier
; #define PG8_STAGE(bufoff, gbase, voff) do { _Pragma("unroll") for (int _i = 0; _i < 2; ++_i) \
;         __builtin_amdgcn_global_load_lds((const unsigned*)((const char*)(gbase) + (voff)[_i]), (LAS unsigned*)(lds + (bufoff) + ldsw + _i * 8192), 16, 0, 0); } while (0)
; #define PG8_LDA(dst, b, h) do { _Pragma("unroll") for (int m = 0; m < 4; ++m) _Pragma("unroll") for (int k = 0; k < 2; ++k) dst[m][k] = *(const LAS bf16x8*)(lds + PG8_SA(b, h) + aoff + m * 2048 + k * 1024); } while (0)
; #define PG8_LDB(dst, b, h) do { _Pragma("unroll") for (int n = 0; n < 2; ++n) _Pragma("unroll") for (int k = 0; k < 2; ++k) dst[n][k] = *(const LAS bf16x8*)(lds + PG8_SB(b, h) + boff + n * 2048 + k * 1024); } while (0)
; #define PG8_MMA(ai, bj, At, Bt) do { __builtin_amdgcn_s_setprio(1); _Pragma("unroll") for (int m = 0; m < 4; ++m) _Pragma("unroll") for (int n = 0; n < 2; ++n) _Pragma("unroll") for (int k = 0; k < 2; ++k) \
;         acc[ai][bj][m][n] = __builtin_amdgcn_mfma_f32_16x16x32_bf16(Bt[n][k], At[m][k], acc[ai][bj][m][n], 0, 0, 0); __builtin_amdgcn_s_setprio(0); } while (0)
; #define PG8_WAIT_V(n) asm volatile("s_waitcnt vmcnt(" #n ")" ::: "memory")
; #define PG8_WAIT_L(n) asm volatile("s_waitcnt lgkmcnt(" #n ")" ::: "memory")
; #define PG8_BAR __builtin_amdgcn_s_barrier()
; #define PG8_SCHED __builtin_amdgcn_sched_barrier(0)
;     ...
;             PG8_WAIT_V(8); PG8_WAIT_L(0); PG8_BAR; PG8_MMA(1, 0, At, B0); PG8_MMA(1, 1, At, B1); PG8_BAR; PG8_SCHED;
;             PG8_LDB(B0, 1, 0); PG8_LDB(B1, 1, 1); PG8_SCHED; PG8_LDA(At, 1, 0); PG8_STAGE(PG8_SA(0, 1), a2 + hA, voffA);
;             PG8_WAIT_V(8); PG8_WAIT_L(0); PG8_BAR; PG8_MMA(0, 0, At, B0); PG8_MMA(0, 1, At, B1); PG8_BAR; PG8_SCHED;
	s_setprio 1
	s_waitcnt lgkmcnt(0)
	v_mfma_f32_16x16x32_bf16 v[92:95], v[100:103], v[196:199], v[92:95]
	v_mfma_f32_16x16x32_bf16 v[92:95], v[168:171], v[200:203], v[92:95]
	v_mfma_f32_16x16x32_bf16 v[88:91], v[172:175], v[196:199], v[88:91]
	v_mfma_f32_16x16x32_bf16 v[88:91], v[176:179], v[200:203], v[88:91]
	v_mfma_f32_16x16x32_bf16 v[84:87], v[100:103], v[208:211], v[84:87]
	v_mfma_f32_16x16x32_bf16 v[84:87], v[168:171], v[214:217], v[84:87]
	v_mfma_f32_16x16x32_bf16 v[80:83], v[172:175], v[208:211], v[80:83]
	v_mfma_f32_16x16x32_bf16 v[80:83], v[176:179], v[214:217], v[80:83]
	v_mfma_f32_16x16x32_bf16 v[76:79], v[100:103], v[230:233], v[76:79]
	v_mfma_f32_16x16x32_bf16 v[76:79], v[168:171], v[234:237], v[76:79]
	v_mfma_f32_16x16x32_bf16 v[72:75], v[172:175], v[230:233], v[72:75]
	v_mfma_f32_16x16x32_bf16 v[72:75], v[176:179], v[234:237], v[72:75]
	v_mfma_f32_16x16x32_bf16 v[64:67], v[100:103], v[238:241], v[64:67]
	v_mfma_f32_16x16x32_bf16 v[64:67], v[168:171], v[242:245], v[64:67]
	v_mfma_f32_16x16x32_bf16 v[60:63], v[172:175], v[238:241], v[60:63]
	v_mfma_f32_16x16x32_bf16 v[60:63], v[176:179], v[242:245], v[60:63]
	s_setprio 0
	s_setprio 1
	v_mfma_f32_16x16x32_bf16 v[28:31], v[180:183], v[196:199], v[28:31]
	v_mfma_f32_16x16x32_bf16 v[28:31], v[184:187], v[200:203], v[28:31]
	v_mfma_f32_16x16x32_bf16 v[24:27], v[188:191], v[196:199], v[24:27]
	v_mfma_f32_16x16x32_bf16 v[24:27], v[192:195], v[200:203], v[24:27]
	v_mfma_f32_16x16x32_bf16 v[20:23], v[180:183], v[208:211], v[20:23]
	v_mfma_f32_16x16x32_bf16 v[20:23], v[184:187], v[214:217], v[20:23]
	v_mfma_f32_16x16x32_bf16 v[16:19], v[188:191], v[208:211], v[16:19]
	v_mfma_f32_16x16x32_bf16 v[16:19], v[192:195], v[214:217], v[16:19]
	v_mfma_f32_16x16x32_bf16 v[12:15], v[180:183], v[230:233], v[12:15]
	v_mfma_f32_16x16x32_bf16 v[12:15], v[184:187], v[234:237], v[12:15]
	v_mfma_f32_16x16x32_bf16 v[8:11], v[188:191], v[230:233], v[8:11]
	v_mfma_f32_16x16x32_bf16 v[8:11], v[192:195], v[234:237], v[8:11]
	v_mfma_f32_16x16x32_bf16 v[4:7], v[180:183], v[238:241], v[4:7]
	v_mfma_f32_16x16x32_bf16 v[4:7], v[184:187], v[242:245], v[4:7]
	v_mfma_f32_16x16x32_bf16 v[0:3], v[188:191], v[238:241], v[0:3]
	v_mfma_f32_16x16x32_bf16 v[0:3], v[192:195], v[242:245], v[0:3]
	s_setprio 0
	s_barrier
	s_add_i32 s83, 0, 0x18000
	v_add_u32_e32 v155, s83, v150
	s_add_i32 s89, 0, 0x1c000
	ds_read_b128 v[100:103], v155
	ds_read_b128 v[168:171], v155 offset:1024
	ds_read_b128 v[172:175], v155 offset:2048
	ds_read_b128 v[176:179], v155 offset:3072
	v_add_u32_e32 v155, s89, v150
	ds_read_b128 v[180:183], v155
	ds_read_b128 v[184:187], v155 offset:1024
	ds_read_b128 v[188:191], v155 offset:2048
	ds_read_b128 v[192:195], v155 offset:3072
	s_add_u32 s76, s76, 0x40000
	s_addc_u32 s77, s77, 0
	s_mov_b32 m0, s8
	v_lshl_add_u64 v[206:207], s[76:77], 0, v[136:137]
	ds_read_b128 v[196:199], v154 offset:32768
	ds_read_b128 v[200:203], v154 offset:33792
	ds_read_b128 v[208:211], v154 offset:34816
	ds_read_b128 v[214:217], v154 offset:35840
	ds_read_b128 v[230:233], v154 offset:36864
	ds_read_b128 v[234:237], v154 offset:37888
	ds_read_b128 v[238:241], v154 offset:38912
	ds_read_b128 v[242:245], v154 offset:39936
	global_load_lds_dwordx4 v[206:207], off
	v_lshl_add_u64 v[206:207], s[76:77], 0, v[138:139]
	s_mov_b32 m0, s9
	s_nop 0
	global_load_lds_dwordx4 v[206:207], off
	s_waitcnt vmcnt(8)
	s_waitcnt lgkmcnt(0)
	s_barrier
	s_setprio 1
	s_waitcnt lgkmcnt(0)
	v_mfma_f32_16x16x32_bf16 v[132:135], v[100:103], v[196:199], v[132:135]
	v_mfma_f32_16x16x32_bf16 v[132:135], v[168:171], v[200:203], v[132:135]
	v_mfma_f32_16x16x32_bf16 v[128:131], v[172:175], v[196:199], v[128:131]
	v_mfma_f32_16x16x32_bf16 v[128:131], v[176:179], v[200:203], v[128:131]
	v_mfma_f32_16x16x32_bf16 v[124:127], v[100:103], v[208:211], v[124:127]
	v_mfma_f32_16x16x32_bf16 v[124:127], v[168:171], v[214:217], v[124:127]
	v_mfma_f32_16x16x32_bf16 v[120:123], v[172:175], v[208:211], v[120:123]
	v_mfma_f32_16x16x32_bf16 v[120:123], v[176:179], v[214:217], v[120:123]
	v_mfma_f32_16x16x32_bf16 v[116:119], v[100:103], v[230:233], v[116:119]
	v_mfma_f32_16x16x32_bf16 v[116:119], v[168:171], v[234:237], v[116:119]
	v_mfma_f32_16x16x32_bf16 v[112:115], v[172:175], v[230:233], v[112:115]
	v_mfma_f32_16x16x32_bf16 v[112:115], v[176:179], v[234:237], v[112:115]
	v_mfma_f32_16x16x32_bf16 v[108:111], v[100:103], v[238:241], v[108:111]
	v_mfma_f32_16x16x32_bf16 v[108:111], v[168:171], v[242:245], v[108:111]
	v_mfma_f32_16x16x32_bf16 v[104:107], v[172:175], v[238:241], v[104:107]
	v_mfma_f32_16x16x32_bf16 v[104:107], v[176:179], v[242:245], v[104:107]
	s_setprio 0
	s_setprio 1
	v_mfma_f32_16x16x32_bf16 v[68:71], v[180:183], v[196:199], v[68:71]
	v_mfma_f32_16x16x32_bf16 v[68:71], v[184:187], v[200:203], v[68:71]
	v_mfma_f32_16x16x32_bf16 v[56:59], v[188:191], v[196:199], v[56:59]
	v_mfma_f32_16x16x32_bf16 v[56:59], v[192:195], v[200:203], v[56:59]
	v_mfma_f32_16x16x32_bf16 v[52:55], v[180:183], v[208:211], v[52:55]
	v_mfma_f32_16x16x32_bf16 v[52:55], v[184:187], v[214:217], v[52:55]
	v_mfma_f32_16x16x32_bf16 v[48:51], v[188:191], v[208:211], v[48:51]
	v_mfma_f32_16x16x32_bf16 v[48:51], v[192:195], v[214:217], v[48:51]
	v_mfma_f32_16x16x32_bf16 v[44:47], v[180:183], v[230:233], v[44:47]
	v_mfma_f32_16x16x32_bf16 v[44:47], v[184:187], v[234:237], v[44:47]
	v_mfma_f32_16x16x32_bf16 v[40:43], v[188:191], v[230:233], v[40:43]
	v_mfma_f32_16x16x32_bf16 v[40:43], v[192:195], v[234:237], v[40:43]
	v_mfma_f32_16x16x32_bf16 v[36:39], v[180:183], v[238:241], v[36:39]
	v_mfma_f32_16x16x32_bf16 v[36:39], v[184:187], v[242:245], v[36:39]
	v_mfma_f32_16x16x32_bf16 v[32:35], v[188:191], v[238:241], v[32:35]
	v_mfma_f32_16x16x32_bf16 v[32:35], v[192:195], v[242:245], v[32:35]
	s_setprio 0
	s_barrier
; #define PG8_STAGE(bufoff, gbase, voff) do { _Pragma("unroll") for (int _i = 0; _i < 2; ++_i) \
;         __builtin_amdgcn_global_load_lds((const unsigned*)((const char*)(gbase) + (voff)[_i]), (LAS unsigned*)(lds + (bufoff) + ldsw + _i * 8192), 16, 0, 0); } while (0)
; #define PG8_LDA(dst, b, h) do { _Pragma("unroll") for (int m = 0; m < 4; ++m) _Pragma("unroll") for (int k = 0; k < 2; ++k) dst[m][k] = *(const LAS bf16x8*)(lds + PG8_SA(b, h) + aoff + m * 2048 + k * 1024); } while (0)
; #define PG8_MMA(ai, bj, At, Bt) do { __builtin_amdgcn_s_setprio(1); _Pragma("unroll") for (int m = 0; m < 4; ++m) _Pragma("unroll") for (int n = 0; n < 2; ++n) _Pragma("unroll") for (int k = 0; k < 2; ++k) \
;         acc[ai][bj][m][n] = __builtin_amdgcn_mfma_f32_16x16x32_bf16(Bt[n][k], At[m][k], acc[ai][bj][m][n], 0, 0, 0); __builtin_amdgcn_s_setprio(0); } while (0)
; #define PG8_WAIT_V(n) asm volatile("s_waitcnt vmcnt(" #n ")" ::: "memory")
; #define PG8_WAIT_L(n) asm volatile("s_waitcnt lgkmcnt(" #n ")" ::: "memory")
; #define PG8_BAR __builtin_amdgcn_s_barrier()
; #define PG8_SCHED __builtin_amdgcn_sched_barrier(0)
;     ...
;         for (int t = 0; t < nt; t += 2) {
;     ...
;             PG8_LDA(At, 1, 1); PG8_STAGE(PG8_SB(1, 0), b3, voffB); PG8_STAGE(PG8_SB(1, 1), b3 + hB, voffB); PG8_STAGE(PG8_SA(1, 0), a3, voffA);
;             PG8_WAIT_V(8); PG8_WAIT_L(0); PG8_BAR; PG8_MMA(1, 0, At, B0); PG8_MMA(1, 1, At, B1); PG8_BAR; PG8_SCHED;
	s_add_i32 s76, s83, s5
	v_lshl_add_u64 v[146:147], v[146:147], 0, s[38:39]
	s_mov_b32 m0, s76
	ds_read_b128 v[196:199], v154 offset:49152
	ds_read_b128 v[200:203], v154 offset:50176
	ds_read_b128 v[208:211], v154 offset:51200
	ds_read_b128 v[214:217], v154 offset:52224
	ds_read_b128 v[230:233], v154 offset:53248
	ds_read_b128 v[234:237], v154 offset:54272
	ds_read_b128 v[238:241], v154 offset:55296
	ds_read_b128 v[242:245], v154 offset:56320
	global_load_lds_dwordx4 v[146:147], off
	s_add_i32 m0, s76, 0x2000
	s_add_u32 s74, s74, 0x40080
	v_lshl_add_u64 v[146:147], v[204:205], 0, s[38:39]
	s_addc_u32 s75, s75, 0
	s_add_i32 s76, s89, s5
	global_load_lds_dwordx4 v[146:147], off
	v_lshl_add_u64 v[146:147], s[74:75], 0, v[156:157]
	s_mov_b32 m0, s76
	s_nop 0
	global_load_lds_dwordx4 v[146:147], off
	v_lshl_add_u64 v[146:147], s[74:75], 0, v[140:141]
	s_add_i32 m0, s76, 0x2000
	s_nop 0
	global_load_lds_dwordx4 v[146:147], off
	v_lshl_add_u64 v[146:147], s[72:73], 0, v[136:137]
	s_mov_b32 m0, s42
	s_nop 0
	global_load_lds_dwordx4 v[146:147], off
	v_lshl_add_u64 v[146:147], s[72:73], 0, v[138:139]
	s_mov_b32 m0, s43
	s_nop 0
	global_load_lds_dwordx4 v[146:147], off
	s_waitcnt vmcnt(8)
	s_waitcnt lgkmcnt(0)
	s_barrier
	s_setprio 1
	s_waitcnt lgkmcnt(0)
	v_mfma_f32_16x16x32_bf16 v[92:95], v[100:103], v[196:199], v[92:95]
	v_mfma_f32_16x16x32_bf16 v[92:95], v[168:171], v[200:203], v[92:95]
	v_mfma_f32_16x16x32_bf16 v[88:91], v[172:175], v[196:199], v[88:91]
	v_mfma_f32_16x16x32_bf16 v[88:91], v[176:179], v[200:203], v[88:91]
	v_mfma_f32_16x16x32_bf16 v[84:87], v[100:103], v[208:211], v[84:87]
	v_mfma_f32_16x16x32_bf16 v[84:87], v[168:171], v[214:217], v[84:87]
	v_mfma_f32_16x16x32_bf16 v[80:83], v[172:175], v[208:211], v[80:83]
	v_mfma_f32_16x16x32_bf16 v[80:83], v[176:179], v[214:217], v[80:83]
	v_mfma_f32_16x16x32_bf16 v[76:79], v[100:103], v[230:233], v[76:79]
	v_mfma_f32_16x16x32_bf16 v[76:79], v[168:171], v[234:237], v[76:79]
	v_mfma_f32_16x16x32_bf16 v[72:75], v[172:175], v[230:233], v[72:75]
	v_mfma_f32_16x16x32_bf16 v[72:75], v[176:179], v[234:237], v[72:75]
	v_mfma_f32_16x16x32_bf16 v[64:67], v[100:103], v[238:241], v[64:67]
	v_mfma_f32_16x16x32_bf16 v[64:67], v[168:171], v[242:245], v[64:67]
	v_mfma_f32_16x16x32_bf16 v[60:63], v[172:175], v[238:241], v[60:63]
	v_mfma_f32_16x16x32_bf16 v[60:63], v[176:179], v[242:245], v[60:63]
	s_setprio 0
	s_setprio 1
	v_mfma_f32_16x16x32_bf16 v[28:31], v[180:183], v[196:199], v[28:31]
	v_mfma_f32_16x16x32_bf16 v[28:31], v[184:187], v[200:203], v[28:31]
	v_mfma_f32_16x16x32_bf16 v[24:27], v[188:191], v[196:199], v[24:27]
	v_mfma_f32_16x16x32_bf16 v[24:27], v[192:195], v[200:203], v[24:27]
	v_mfma_f32_16x16x32_bf16 v[20:23], v[180:183], v[208:211], v[20:23]
	v_mfma_f32_16x16x32_bf16 v[20:23], v[184:187], v[214:217], v[20:23]
	v_mfma_f32_16x16x32_bf16 v[16:19], v[188:191], v[208:211], v[16:19]
	v_mfma_f32_16x16x32_bf16 v[16:19], v[192:195], v[214:217], v[16:19]
	v_mfma_f32_16x16x32_bf16 v[12:15], v[180:183], v[230:233], v[12:15]
	v_mfma_f32_16x16x32_bf16 v[12:15], v[184:187], v[234:237], v[12:15]
	v_mfma_f32_16x16x32_bf16 v[8:11], v[188:191], v[230:233], v[8:11]
	v_mfma_f32_16x16x32_bf16 v[8:11], v[192:195], v[234:237], v[8:11]
	v_mfma_f32_16x16x32_bf16 v[4:7], v[180:183], v[238:241], v[4:7]
	v_mfma_f32_16x16x32_bf16 v[4:7], v[184:187], v[242:245], v[4:7]
	v_mfma_f32_16x16x32_bf16 v[0:3], v[188:191], v[238:241], v[0:3]
	v_mfma_f32_16x16x32_bf16 v[0:3], v[192:195], v[242:245], v[0:3]
	s_setprio 0
	s_barrier
	s_add_i32 s82, s82, 2
	s_add_u32 s52, s52, 0x100
	s_addc_u32 s53, s53, 0
	s_cmp_gt_u32 s82, 13
	s_cbranch_scc0 .LBB0_191
	s_and_b64 vcc, exec, s[14:15]
	s_cbranch_vccz .LBB0_194
	s_barrier

; #define PG8_STAGE(bufoff, gbase, voff) do { _Pragma("unroll") for (int _i = 0; _i < 2; ++_i) \
;         __builtin_amdgcn_global_load_lds((const unsigned*)((const char*)(gbase) + (voff)[_i]), (LAS unsigned*)(lds + (bufoff) + ldsw + _i * 8192), 16, 0, 0); } while (0)
; #define PG8_LDA(dst, b, h) do { _Pragma("unroll") for (int m = 0; m < 4; ++m) _Pragma("unroll") for (int k = 0; k < 2; ++k) dst[m][k] = *(const LAS bf16x8*)(lds + PG8_SA(b, h) + aoff + m * 2048 + k * 1024); } while (0)
; #define PG8_LDB(dst, b, h) do { _Pragma("unroll") for (int n = 0; n < 2; ++n) _Pragma("unroll") for (int k = 0; k < 2; ++k) dst[n][k] = *(const LAS bf16x8*)(lds + PG8_SB(b, h) + boff + n * 2048 + k * 1024); } while (0)
; #define PG8_MMA(ai, bj, At, Bt) do { __builtin_amdgcn_s_setprio(1); _Pragma("unroll") for (int m = 0; m < 4; ++m) _Pragma("unroll") for (int n = 0; n < 2; ++n) _Pragma("unroll") for (int k = 0; k < 2; ++k) \
;         acc[ai][bj][m][n] = __builtin_amdgcn_mfma_f32_16x16x32_bf16(Bt[n][k], At[m][k], acc[ai][bj][m][n], 0, 0, 0); __builtin_amdgcn_s_setprio(0); } while (0)
; #define PG8_WAIT_V(n) asm volatile("s_waitcnt vmcnt(" #n ")" ::: "memory")
; #define PG8_WAIT_L(n) asm volatile("s_waitcnt lgkmcnt(" #n ")" ::: "memory")
; #define PG8_BAR __builtin_amdgcn_s_barrier()
; #define PG8_SCHED __builtin_amdgcn_sched_barrier(0)
;     ...
;             const bool last = (t == nt - 2);
;             const char* a1 = PG8_ATILE(cA, cA2, t + 1);
;             const char* a2 = last ? nA : PG8_ATILE(cA, cA2, t + 2); const char* b2 = last ? nB : cB + (size_t)(t + 2) * 128;
;             const char* a3 = last ? nA + kA1 : PG8_ATILE(cA, cA2, t + 3); const char* b3 = b2 + kB1;
;             if constexpr (SP2) {
;             PG8_LDB(B0, 0, 0); PG8_LDB(B1, 0, 1); PG8_SCHED; PG8_LDA(At, 0, 0); PG8_STAGE(PG8_SA(1, 1), a1 + hA, voffA);
;             PG8_WAIT_V(8); PG8_WAIT_L(0); PG8_BAR; PG8_MMA(0, 0, At, B0); PG8_MMA(0, 1, At, B1); PG8_BAR; PG8_SCHED;
;             PG8_LDA(At, 0, 1); PG8_STAGE(PG8_SB(0, 0), b2, voffB); PG8_STAGE(PG8_SB(0, 1), b2 + hB, voffB); PG8_STAGE(PG8_SA(0, 0), a2, voffA);
;             PG8_WAIT_V(8); PG8_WAIT_L(0); PG8_BAR; PG8_MMA(1, 0, At, B0); PG8_MMA(1, 1, At, B1); PG8_BAR; PG8_SCHED;
.LBB0_271:
	s_add_u32 s31, s52, s90
	s_addc_u32 s36, s53, s91
	s_add_u32 s45, s31, 0x100
	s_addc_u32 s54, s36, 0
	s_add_u32 s55, s8, s90
	s_addc_u32 s74, s9, s91
	s_add_u32 s31, s31, 0x180
	s_addc_u32 s36, s36, 0
	s_add_i32 s82, 0, 0x10000
	s_add_i32 s83, 0, 0x14000
	v_add_u32_e32 v144, s82, v231
	v_add_u32_e32 v156, s83, v231
	ds_read_b128 v[132:135], v144
	ds_read_b128 v[136:139], v144 offset:1024
	ds_read_b128 v[140:143], v144 offset:2048
	ds_read_b128 v[144:147], v144 offset:3072
	ds_read_b128 v[148:151], v156
	ds_read_b128 v[152:155], v156 offset:1024
	ds_read_b128 v[182:185], v156 offset:2048
	ds_read_b128 v[186:189], v156 offset:3072
	s_cmpk_eq_i32 s90, 0x700
	s_cselect_b32 s73, s7, s36
	s_cselect_b32 s72, s6, s31
	s_cselect_b32 s75, s4, s74
	s_cselect_b32 s74, s5, s55
	s_cselect_b32 s77, s1, s54
	s_cselect_b32 s76, s3, s45
	v_lshl_add_u64 v[206:207], v[128:129], 0, s[90:91]
	s_add_i32 m0, s80, 0xc000
	ds_read_b128 v[190:193], v233
	ds_read_b128 v[194:197], v233 offset:1024
	ds_read_b128 v[198:201], v233 offset:2048
	ds_read_b128 v[202:205], v233 offset:3072
	ds_read_b128 v[208:211], v233 offset:4096
	ds_read_b128 v[214:217], v233 offset:5120
	ds_read_b128 v[234:237], v233 offset:6144
	ds_read_b128 v[238:241], v233 offset:7168
	global_load_lds_dwordx4 v[206:207], off
	v_lshl_add_u64 v[206:207], v[130:131], 0, s[90:91]
	s_add_i32 m0, s80, 0xe000
	s_nop 0
	global_load_lds_dwordx4 v[206:207], off
	s_waitcnt vmcnt(8)
	s_waitcnt lgkmcnt(0)
	s_barrier
	s_setprio 1
	s_waitcnt lgkmcnt(0)
	v_mfma_f32_16x16x32_bf16 v[124:127], v[132:135], v[190:193], v[124:127]
	v_mfma_f32_16x16x32_bf16 v[124:127], v[136:139], v[194:197], v[124:127]
	v_mfma_f32_16x16x32_bf16 v[120:123], v[140:143], v[190:193], v[120:123]
	v_mfma_f32_16x16x32_bf16 v[120:123], v[144:147], v[194:197], v[120:123]
	v_mfma_f32_16x16x32_bf16 v[108:111], v[132:135], v[198:201], v[108:111]
	v_mfma_f32_16x16x32_bf16 v[108:111], v[136:139], v[202:205], v[108:111]
	v_mfma_f32_16x16x32_bf16 v[104:107], v[140:143], v[198:201], v[104:107]
	v_mfma_f32_16x16x32_bf16 v[104:107], v[144:147], v[202:205], v[104:107]
	v_mfma_f32_16x16x32_bf16 v[92:95], v[132:135], v[208:211], v[92:95]
	v_mfma_f32_16x16x32_bf16 v[92:95], v[136:139], v[214:217], v[92:95]
	v_mfma_f32_16x16x32_bf16 v[88:91], v[140:143], v[208:211], v[88:91]
	v_mfma_f32_16x16x32_bf16 v[88:91], v[144:147], v[214:217], v[88:91]
	v_mfma_f32_16x16x32_bf16 v[76:79], v[132:135], v[234:237], v[76:79]
	v_mfma_f32_16x16x32_bf16 v[76:79], v[136:139], v[238:241], v[76:79]
	v_mfma_f32_16x16x32_bf16 v[72:75], v[140:143], v[234:237], v[72:75]
	v_mfma_f32_16x16x32_bf16 v[72:75], v[144:147], v[238:241], v[72:75]
	s_setprio 0
	s_setprio 1
	v_mfma_f32_16x16x32_bf16 v[116:119], v[148:151], v[190:193], v[116:119]
	v_mfma_f32_16x16x32_bf16 v[116:119], v[152:155], v[194:197], v[116:119]
	v_mfma_f32_16x16x32_bf16 v[112:115], v[182:185], v[190:193], v[112:115]
	v_mfma_f32_16x16x32_bf16 v[112:115], v[186:189], v[194:197], v[112:115]
	v_mfma_f32_16x16x32_bf16 v[100:103], v[148:151], v[198:201], v[100:103]
	v_mfma_f32_16x16x32_bf16 v[100:103], v[152:155], v[202:205], v[100:103]
	v_mfma_f32_16x16x32_bf16 v[96:99], v[182:185], v[198:201], v[96:99]
	v_mfma_f32_16x16x32_bf16 v[96:99], v[186:189], v[202:205], v[96:99]
	v_mfma_f32_16x16x32_bf16 v[84:87], v[148:151], v[208:211], v[84:87]
	v_mfma_f32_16x16x32_bf16 v[84:87], v[152:155], v[214:217], v[84:87]
	v_mfma_f32_16x16x32_bf16 v[80:83], v[182:185], v[208:211], v[80:83]
	v_mfma_f32_16x16x32_bf16 v[80:83], v[186:189], v[214:217], v[80:83]
	v_mfma_f32_16x16x32_bf16 v[68:71], v[148:151], v[234:237], v[68:71]
	v_mfma_f32_16x16x32_bf16 v[68:71], v[152:155], v[238:241], v[68:71]
	v_mfma_f32_16x16x32_bf16 v[64:67], v[182:185], v[234:237], v[64:67]
	v_mfma_f32_16x16x32_bf16 v[64:67], v[186:189], v[238:241], v[64:67]
	s_setprio 0
	s_barrier
	s_add_i32 s31, s82, s79
	v_lshl_add_u64 v[206:207], s[74:75], 0, v[170:171]
	s_mov_b32 m0, s31
	ds_read_b128 v[190:193], v233 offset:16384
	ds_read_b128 v[194:197], v233 offset:17408
	ds_read_b128 v[198:201], v233 offset:18432
	ds_read_b128 v[202:205], v233 offset:19456
	ds_read_b128 v[208:211], v233 offset:20480
	ds_read_b128 v[214:217], v233 offset:21504
	ds_read_b128 v[234:237], v233 offset:22528
	ds_read_b128 v[238:241], v233 offset:23552
	global_load_lds_dwordx4 v[206:207], off
	s_add_i32 m0, s31, 0x2000
	s_add_u32 s54, s74, 0x40000
	v_lshl_add_u64 v[242:243], s[74:75], 0, v[174:175]
	s_addc_u32 s55, s75, 0
	s_add_i32 s31, s83, s79
	global_load_lds_dwordx4 v[242:243], off
	v_lshl_add_u64 v[244:245], s[54:55], 0, v[170:171]
	s_mov_b32 m0, s31
	s_nop 0
	global_load_lds_dwordx4 v[244:245], off
	v_lshl_add_u64 v[244:245], s[54:55], 0, v[174:175]
	s_add_i32 m0, s31, 0x2000
	s_nop 0
	global_load_lds_dwordx4 v[244:245], off
	v_lshl_add_u64 v[244:245], s[76:77], 0, v[168:169]
	s_mov_b32 m0, s80
	s_nop 0
	global_load_lds_dwordx4 v[244:245], off
	v_lshl_add_u64 v[244:245], s[76:77], 0, v[172:173]
	s_mov_b32 m0, s81
	s_nop 0
	global_load_lds_dwordx4 v[244:245], off
	s_waitcnt vmcnt(8)
	s_waitcnt lgkmcnt(0)
	s_barrier
; #define PG8_STAGE(bufoff, gbase, voff) do { _Pragma("unroll") for (int _i = 0; _i < 2; ++_i) \
;         __builtin_amdgcn_global_load_lds((const unsigned*)((const char*)(gbase) + (voff)[_i]), (LAS unsigned*)(lds + (bufoff) + ldsw + _i * 8192), 16, 0, 0); } while (0)
; #define PG8_LDA(dst, b, h) do { _Pragma("unroll") for (int m = 0; m < 4; ++m) _Pragma("unroll") for (int k = 0; k < 2; ++k) dst[m][k] = *(const LAS bf16x8*)(lds + PG8_SA(b, h) + aoff + m * 2048 + k * 1024); } while (0)
; #define PG8_LDB(dst, b, h) do { _Pragma("unroll") for (int n = 0; n < 2; ++n) _Pragma("unroll") for (int k = 0; k < 2; ++k) dst[n][k] = *(const LAS bf16x8*)(lds + PG8_SB(b, h) + boff + n * 2048 + k * 1024); } while (0)
; #define PG8_MMA(ai, bj, At, Bt) do { __builtin_amdgcn_s_setprio(1); _Pragma("unroll") for (int m = 0; m < 4; ++m) _Pragma("unroll") for (int n = 0; n < 2; ++n) _Pragma("unroll") for (int k = 0; k < 2; ++k) \
;         acc[ai][bj][m][n] = __builtin_amdgcn_mfma_f32_16x16x32_bf16(Bt[n][k], At[m][k], acc[ai][bj][m][n], 0, 0, 0); __builtin_amdgcn_s_setprio(0); } while (0)
; #define PG8_WAIT_V(n) asm volatile("s_waitcnt vmcnt(" #n ")" ::: "memory")
; #define PG8_WAIT_L(n) asm volatile("s_waitcnt lgkmcnt(" #n ")" ::: "memory")
; #define PG8_BAR __builtin_amdgcn_s_barrier()
; #define PG8_SCHED __builtin_amdgcn_sched_barrier(0)
;     ...
;             PG8_WAIT_V(8); PG8_WAIT_L(0); PG8_BAR; PG8_MMA(1, 0, At, B0); PG8_MMA(1, 1, At, B1); PG8_BAR; PG8_SCHED;
;             PG8_LDB(B0, 1, 0); PG8_LDB(B1, 1, 1); PG8_SCHED; PG8_LDA(At, 1, 0); PG8_STAGE(PG8_SA(0, 1), a2 + hA, voffA);
;             PG8_WAIT_V(8); PG8_WAIT_L(0); PG8_BAR; PG8_MMA(0, 0, At, B0); PG8_MMA(0, 1, At, B1); PG8_BAR; PG8_SCHED;
	s_setprio 1
	s_waitcnt lgkmcnt(0)
	v_mfma_f32_16x16x32_bf16 v[60:63], v[132:135], v[190:193], v[60:63]
	v_mfma_f32_16x16x32_bf16 v[60:63], v[136:139], v[194:197], v[60:63]
	v_mfma_f32_16x16x32_bf16 v[56:59], v[140:143], v[190:193], v[56:59]
	v_mfma_f32_16x16x32_bf16 v[56:59], v[144:147], v[194:197], v[56:59]
	v_mfma_f32_16x16x32_bf16 v[44:47], v[132:135], v[198:201], v[44:47]
	v_mfma_f32_16x16x32_bf16 v[44:47], v[136:139], v[202:205], v[44:47]
	v_mfma_f32_16x16x32_bf16 v[40:43], v[140:143], v[198:201], v[40:43]
	v_mfma_f32_16x16x32_bf16 v[40:43], v[144:147], v[202:205], v[40:43]
	v_mfma_f32_16x16x32_bf16 v[28:31], v[132:135], v[208:211], v[28:31]
	v_mfma_f32_16x16x32_bf16 v[28:31], v[136:139], v[214:217], v[28:31]
	v_mfma_f32_16x16x32_bf16 v[24:27], v[140:143], v[208:211], v[24:27]
	v_mfma_f32_16x16x32_bf16 v[24:27], v[144:147], v[214:217], v[24:27]
	v_mfma_f32_16x16x32_bf16 v[12:15], v[132:135], v[234:237], v[12:15]
	v_mfma_f32_16x16x32_bf16 v[12:15], v[136:139], v[238:241], v[12:15]
	v_mfma_f32_16x16x32_bf16 v[8:11], v[140:143], v[234:237], v[8:11]
	v_mfma_f32_16x16x32_bf16 v[8:11], v[144:147], v[238:241], v[8:11]
	s_setprio 0
	s_setprio 1
	v_mfma_f32_16x16x32_bf16 v[52:55], v[148:151], v[190:193], v[52:55]
	v_mfma_f32_16x16x32_bf16 v[52:55], v[152:155], v[194:197], v[52:55]
	v_mfma_f32_16x16x32_bf16 v[48:51], v[182:185], v[190:193], v[48:51]
	v_mfma_f32_16x16x32_bf16 v[48:51], v[186:189], v[194:197], v[48:51]
	v_mfma_f32_16x16x32_bf16 v[36:39], v[148:151], v[198:201], v[36:39]
	v_mfma_f32_16x16x32_bf16 v[36:39], v[152:155], v[202:205], v[36:39]
	v_mfma_f32_16x16x32_bf16 v[32:35], v[182:185], v[198:201], v[32:35]
	v_mfma_f32_16x16x32_bf16 v[32:35], v[186:189], v[202:205], v[32:35]
	v_mfma_f32_16x16x32_bf16 v[20:23], v[148:151], v[208:211], v[20:23]
	v_mfma_f32_16x16x32_bf16 v[20:23], v[152:155], v[214:217], v[20:23]
	v_mfma_f32_16x16x32_bf16 v[16:19], v[182:185], v[208:211], v[16:19]
	v_mfma_f32_16x16x32_bf16 v[16:19], v[186:189], v[214:217], v[16:19]
	v_mfma_f32_16x16x32_bf16 v[4:7], v[148:151], v[234:237], v[4:7]
	v_mfma_f32_16x16x32_bf16 v[4:7], v[152:155], v[238:241], v[4:7]
	v_mfma_f32_16x16x32_bf16 v[0:3], v[182:185], v[234:237], v[0:3]
	v_mfma_f32_16x16x32_bf16 v[0:3], v[186:189], v[238:241], v[0:3]
	s_setprio 0
	s_barrier
	s_add_i32 s31, 0, 0x18000
	s_add_i32 s36, 0, 0x1c000
	v_add_u32_e32 v144, s31, v231
	v_add_u32_e32 v156, s36, v231
	ds_read_b128 v[132:135], v144
	ds_read_b128 v[136:139], v144 offset:1024
	ds_read_b128 v[140:143], v144 offset:2048
	ds_read_b128 v[144:147], v144 offset:3072
	ds_read_b128 v[148:151], v156
	ds_read_b128 v[152:155], v156 offset:1024
	ds_read_b128 v[182:185], v156 offset:2048
	ds_read_b128 v[186:189], v156 offset:3072
	s_add_u32 s54, s76, 0x40000
	s_addc_u32 s55, s77, 0
	s_mov_b32 m0, s89
	v_lshl_add_u64 v[244:245], s[54:55], 0, v[168:169]
	ds_read_b128 v[190:193], v233 offset:32768
	ds_read_b128 v[194:197], v233 offset:33792
	ds_read_b128 v[198:201], v233 offset:34816
	ds_read_b128 v[202:205], v233 offset:35840
	ds_read_b128 v[208:211], v233 offset:36864
	ds_read_b128 v[214:217], v233 offset:37888
	ds_read_b128 v[234:237], v233 offset:38912
	ds_read_b128 v[238:241], v233 offset:39936
	global_load_lds_dwordx4 v[244:245], off
	v_lshl_add_u64 v[244:245], s[54:55], 0, v[172:173]
	s_mov_b32 m0, s92
	s_nop 0
	global_load_lds_dwordx4 v[244:245], off
	s_waitcnt vmcnt(8)
	s_waitcnt lgkmcnt(0)
	s_barrier
	s_setprio 1
	s_waitcnt lgkmcnt(0)
	v_mfma_f32_16x16x32_bf16 v[124:127], v[132:135], v[190:193], v[124:127]
	v_mfma_f32_16x16x32_bf16 v[124:127], v[136:139], v[194:197], v[124:127]
	v_mfma_f32_16x16x32_bf16 v[120:123], v[140:143], v[190:193], v[120:123]
	v_mfma_f32_16x16x32_bf16 v[120:123], v[144:147], v[194:197], v[120:123]
	v_mfma_f32_16x16x32_bf16 v[108:111], v[132:135], v[198:201], v[108:111]
	v_mfma_f32_16x16x32_bf16 v[108:111], v[136:139], v[202:205], v[108:111]
	v_mfma_f32_16x16x32_bf16 v[104:107], v[140:143], v[198:201], v[104:107]
	v_mfma_f32_16x16x32_bf16 v[104:107], v[144:147], v[202:205], v[104:107]
	v_mfma_f32_16x16x32_bf16 v[92:95], v[132:135], v[208:211], v[92:95]
	v_mfma_f32_16x16x32_bf16 v[92:95], v[136:139], v[214:217], v[92:95]
	v_mfma_f32_16x16x32_bf16 v[88:91], v[140:143], v[208:211], v[88:91]
	v_mfma_f32_16x16x32_bf16 v[88:91], v[144:147], v[214:217], v[88:91]
	v_mfma_f32_16x16x32_bf16 v[76:79], v[132:135], v[234:237], v[76:79]
	v_mfma_f32_16x16x32_bf16 v[76:79], v[136:139], v[238:241], v[76:79]
	v_mfma_f32_16x16x32_bf16 v[72:75], v[140:143], v[234:237], v[72:75]
	v_mfma_f32_16x16x32_bf16 v[72:75], v[144:147], v[238:241], v[72:75]
	s_setprio 0
	s_setprio 1
	v_mfma_f32_16x16x32_bf16 v[116:119], v[148:151], v[190:193], v[116:119]
	v_mfma_f32_16x16x32_bf16 v[116:119], v[152:155], v[194:197], v[116:119]
	v_mfma_f32_16x16x32_bf16 v[112:115], v[182:185], v[190:193], v[112:115]
	v_mfma_f32_16x16x32_bf16 v[112:115], v[186:189], v[194:197], v[112:115]
	v_mfma_f32_16x16x32_bf16 v[100:103], v[148:151], v[198:201], v[100:103]
	v_mfma_f32_16x16x32_bf16 v[100:103], v[152:155], v[202:205], v[100:103]
	v_mfma_f32_16x16x32_bf16 v[96:99], v[182:185], v[198:201], v[96:99]
	v_mfma_f32_16x16x32_bf16 v[96:99], v[186:189], v[202:205], v[96:99]
	v_mfma_f32_16x16x32_bf16 v[84:87], v[148:151], v[208:211], v[84:87]
	v_mfma_f32_16x16x32_bf16 v[84:87], v[152:155], v[214:217], v[84:87]
	v_mfma_f32_16x16x32_bf16 v[80:83], v[182:185], v[208:211], v[80:83]
	v_mfma_f32_16x16x32_bf16 v[80:83], v[186:189], v[214:217], v[80:83]
	v_mfma_f32_16x16x32_bf16 v[68:71], v[148:151], v[234:237], v[68:71]
	v_mfma_f32_16x16x32_bf16 v[68:71], v[152:155], v[238:241], v[68:71]
	v_mfma_f32_16x16x32_bf16 v[64:67], v[182:185], v[234:237], v[64:67]
	v_mfma_f32_16x16x32_bf16 v[64:67], v[186:189], v[238:241], v[64:67]
	s_setprio 0
	s_barrier
; #define PG8_STAGE(bufoff, gbase, voff) do { _Pragma("unroll") for (int _i = 0; _i < 2; ++_i) \
;         __builtin_amdgcn_global_load_lds((const unsigned*)((const char*)(gbase) + (voff)[_i]), (LAS unsigned*)(lds + (bufoff) + ldsw + _i * 8192), 16, 0, 0); } while (0)
; #define PG8_LDA(dst, b, h) do { _Pragma("unroll") for (int m = 0; m < 4; ++m) _Pragma("unroll") for (int k = 0; k < 2; ++k) dst[m][k] = *(const LAS bf16x8*)(lds + PG8_SA(b, h) + aoff + m * 2048 + k * 1024); } while (0)
; #define PG8_MMA(ai, bj, At, Bt) do { __builtin_amdgcn_s_setprio(1); _Pragma("unroll") for (int m = 0; m < 4; ++m) _Pragma("unroll") for (int n = 0; n < 2; ++n) _Pragma("unroll") for (int k = 0; k < 2; ++k) \
;         acc[ai][bj][m][n] = __builtin_amdgcn_mfma_f32_16x16x32_bf16(Bt[n][k], At[m][k], acc[ai][bj][m][n], 0, 0, 0); __builtin_amdgcn_s_setprio(0); } while (0)
; #define PG8_WAIT_V(n) asm volatile("s_waitcnt vmcnt(" #n ")" ::: "memory")
; #define PG8_WAIT_L(n) asm volatile("s_waitcnt lgkmcnt(" #n ")" ::: "memory")
; #define PG8_BAR __builtin_amdgcn_s_barrier()
; #define PG8_SCHED __builtin_amdgcn_sched_barrier(0)
;     ...
;         for (int t = 0; t < nt; t += 2) {
;     ...
;             PG8_LDA(At, 1, 1); PG8_STAGE(PG8_SB(1, 0), b3, voffB); PG8_STAGE(PG8_SB(1, 1), b3 + hB, voffB); PG8_STAGE(PG8_SA(1, 0), a3, voffA);
;             PG8_WAIT_V(8); PG8_WAIT_L(0); PG8_BAR; PG8_MMA(1, 0, At, B0); PG8_MMA(1, 1, At, B1); PG8_BAR; PG8_SCHED;
	s_add_i32 s31, s31, s79
	v_lshl_add_u64 v[206:207], v[206:207], 0, s[38:39]
	s_mov_b32 m0, s31
	ds_read_b128 v[190:193], v233 offset:49152
	ds_read_b128 v[194:197], v233 offset:50176
	ds_read_b128 v[198:201], v233 offset:51200
	ds_read_b128 v[202:205], v233 offset:52224
	ds_read_b128 v[208:211], v233 offset:53248
	ds_read_b128 v[214:217], v233 offset:54272
	ds_read_b128 v[234:237], v233 offset:55296
	ds_read_b128 v[238:241], v233 offset:56320
	global_load_lds_dwordx4 v[206:207], off
	s_add_i32 m0, s31, 0x2000
	s_add_u32 s54, s74, 0x40080
	v_lshl_add_u64 v[206:207], v[242:243], 0, s[38:39]
	s_addc_u32 s55, s75, 0
	s_add_i32 s31, s36, s79
	global_load_lds_dwordx4 v[206:207], off
	v_lshl_add_u64 v[206:207], s[54:55], 0, v[170:171]
	s_mov_b32 m0, s31
	s_nop 0
	global_load_lds_dwordx4 v[206:207], off
	v_lshl_add_u64 v[206:207], s[54:55], 0, v[174:175]
	s_add_i32 m0, s31, 0x2000
	s_nop 0
	global_load_lds_dwordx4 v[206:207], off
	v_lshl_add_u64 v[206:207], s[72:73], 0, v[168:169]
	s_mov_b32 m0, s95
	s_nop 0
	global_load_lds_dwordx4 v[206:207], off
	v_lshl_add_u64 v[206:207], s[72:73], 0, v[172:173]
	s_mov_b32 m0, s42
	s_nop 0
	global_load_lds_dwordx4 v[206:207], off
	s_waitcnt vmcnt(8)
	s_waitcnt lgkmcnt(0)
	s_barrier
	s_setprio 1
	s_waitcnt lgkmcnt(0)
	v_mfma_f32_16x16x32_bf16 v[60:63], v[132:135], v[190:193], v[60:63]
	v_mfma_f32_16x16x32_bf16 v[60:63], v[136:139], v[194:197], v[60:63]
	v_mfma_f32_16x16x32_bf16 v[56:59], v[140:143], v[190:193], v[56:59]
	v_mfma_f32_16x16x32_bf16 v[56:59], v[144:147], v[194:197], v[56:59]
	v_mfma_f32_16x16x32_bf16 v[44:47], v[132:135], v[198:201], v[44:47]
	v_mfma_f32_16x16x32_bf16 v[44:47], v[136:139], v[202:205], v[44:47]
	v_mfma_f32_16x16x32_bf16 v[40:43], v[140:143], v[198:201], v[40:43]
	v_mfma_f32_16x16x32_bf16 v[40:43], v[144:147], v[202:205], v[40:43]
	v_mfma_f32_16x16x32_bf16 v[28:31], v[132:135], v[208:211], v[28:31]
	v_mfma_f32_16x16x32_bf16 v[28:31], v[136:139], v[214:217], v[28:31]
	v_mfma_f32_16x16x32_bf16 v[24:27], v[140:143], v[208:211], v[24:27]
	v_mfma_f32_16x16x32_bf16 v[24:27], v[144:147], v[214:217], v[24:27]
	v_mfma_f32_16x16x32_bf16 v[12:15], v[132:135], v[234:237], v[12:15]
	v_mfma_f32_16x16x32_bf16 v[12:15], v[136:139], v[238:241], v[12:15]
	v_mfma_f32_16x16x32_bf16 v[8:11], v[140:143], v[234:237], v[8:11]
	v_mfma_f32_16x16x32_bf16 v[8:11], v[144:147], v[238:241], v[8:11]
	s_setprio 0
	s_setprio 1
	v_mfma_f32_16x16x32_bf16 v[52:55], v[148:151], v[190:193], v[52:55]
	v_mfma_f32_16x16x32_bf16 v[52:55], v[152:155], v[194:197], v[52:55]
	v_mfma_f32_16x16x32_bf16 v[48:51], v[182:185], v[190:193], v[48:51]
	v_mfma_f32_16x16x32_bf16 v[48:51], v[186:189], v[194:197], v[48:51]
	v_mfma_f32_16x16x32_bf16 v[36:39], v[148:151], v[198:201], v[36:39]
	v_mfma_f32_16x16x32_bf16 v[36:39], v[152:155], v[202:205], v[36:39]
	v_mfma_f32_16x16x32_bf16 v[32:35], v[182:185], v[198:201], v[32:35]
	v_mfma_f32_16x16x32_bf16 v[32:35], v[186:189], v[202:205], v[32:35]
	v_mfma_f32_16x16x32_bf16 v[20:23], v[148:151], v[208:211], v[20:23]
	v_mfma_f32_16x16x32_bf16 v[20:23], v[152:155], v[214:217], v[20:23]
	v_mfma_f32_16x16x32_bf16 v[16:19], v[182:185], v[208:211], v[16:19]
	v_mfma_f32_16x16x32_bf16 v[16:19], v[186:189], v[214:217], v[16:19]
	v_mfma_f32_16x16x32_bf16 v[4:7], v[148:151], v[234:237], v[4:7]
	v_mfma_f32_16x16x32_bf16 v[4:7], v[152:155], v[238:241], v[4:7]
	v_mfma_f32_16x16x32_bf16 v[0:3], v[182:185], v[234:237], v[0:3]
	v_mfma_f32_16x16x32_bf16 v[0:3], v[186:189], v[238:241], v[0:3]
	s_setprio 0
	s_barrier
	s_add_i32 s13, s13, 2
	s_add_u32 s90, s90, 0x100
	s_addc_u32 s91, s91, 0
	s_cmp_gt_u32 s13, 13
	s_cbranch_scc0 .LBB0_271
	s_and_b64 vcc, exec, s[28:29]
	s_cbranch_vccz .LBB0_274
	s_barrier

; #define PG8_STAGE(bufoff, gbase, voff) do { _Pragma("unroll") for (int _i = 0; _i < 2; ++_i) \
;         __builtin_amdgcn_global_load_lds((const unsigned*)((const char*)(gbase) + (voff)[_i]), (LAS unsigned*)(lds + (bufoff) + ldsw + _i * 8192), 16, 0, 0); } while (0)
; #define PG8_LDA(dst, b, h) do { _Pragma("unroll") for (int m = 0; m < 4; ++m) _Pragma("unroll") for (int k = 0; k < 2; ++k) dst[m][k] = *(const LAS bf16x8*)(lds + PG8_SA(b, h) + aoff + m * 2048 + k * 1024); } while (0)
; #define PG8_LDB(dst, b, h) do { _Pragma("unroll") for (int n = 0; n < 2; ++n) _Pragma("unroll") for (int k = 0; k < 2; ++k) dst[n][k] = *(const LAS bf16x8*)(lds + PG8_SB(b, h) + boff + n * 2048 + k * 1024); } while (0)
; #define PG8_MMA(ai, bj, At, Bt) do { __builtin_amdgcn_s_setprio(1); _Pragma("unroll") for (int m = 0; m < 4; ++m) _Pragma("unroll") for (int n = 0; n < 2; ++n) _Pragma("unroll") for (int k = 0; k < 2; ++k) \
;         acc[ai][bj][m][n] = __builtin_amdgcn_mfma_f32_16x16x32_bf16(Bt[n][k], At[m][k], acc[ai][bj][m][n], 0, 0, 0); __builtin_amdgcn_s_setprio(0); } while (0)
; #define PG8_WAIT_V(n) asm volatile("s_waitcnt vmcnt(" #n ")" ::: "memory")
; #define PG8_WAIT_L(n) asm volatile("s_waitcnt lgkmcnt(" #n ")" ::: "memory")
; #define PG8_BAR __builtin_amdgcn_s_barrier()
; #define PG8_SCHED __builtin_amdgcn_sched_barrier(0)
;     ...
;             const bool last = (t == nt - 2);
;             const char* a1 = PG8_ATILE(cA, cA2, t + 1);
;             const char* a2 = last ? nA : PG8_ATILE(cA, cA2, t + 2); const char* b2 = last ? nB : cB + (size_t)(t + 2) * 128;
;             const char* a3 = last ? nA + kA1 : PG8_ATILE(cA, cA2, t + 3); const char* b3 = b2 + kB1;
;             if constexpr (SP2) {
;             PG8_LDB(B0, 0, 0); PG8_LDB(B1, 0, 1); PG8_SCHED; PG8_LDA(At, 0, 0); PG8_STAGE(PG8_SA(1, 1), a1 + hA, voffA);
;             PG8_WAIT_V(8); PG8_WAIT_L(0); PG8_BAR; PG8_MMA(0, 0, At, B0); PG8_MMA(0, 1, At, B1); PG8_BAR; PG8_SCHED;
;             PG8_LDA(At, 0, 1); PG8_STAGE(PG8_SB(0, 0), b2, voffB); PG8_STAGE(PG8_SB(0, 1), b2 + hB, voffB); PG8_STAGE(PG8_SA(0, 0), a2, voffA);
;             PG8_WAIT_V(8); PG8_WAIT_L(0); PG8_BAR; PG8_MMA(1, 0, At, B0); PG8_MMA(1, 1, At, B1); PG8_BAR; PG8_SCHED;
.LBB0_299:
	s_add_u32 s72, s44, s52
	s_addc_u32 s73, s45, s53
	s_add_u32 s98, s72, 0x40080
	s_addc_u32 s99, s73, 0
	s_add_u32 s76, s72, 0x100
	s_addc_u32 s77, s73, 0
	s_add_u32 s74, s79, s52
	s_addc_u32 s75, s80, s53
	s_add_u32 s72, s72, 0x180
	s_addc_u32 s73, s73, 0
	s_add_i32 s82, 0, 0x10000
	s_add_i32 s89, 0, 0x14000
	v_add_u32_e32 v144, s82, v193
	v_add_u32_e32 v184, s89, v193
	ds_read_b128 v[132:135], v144
	ds_read_b128 v[136:139], v144 offset:1024
	ds_read_b128 v[140:143], v144 offset:2048
	ds_read_b128 v[144:147], v144 offset:3072
	ds_read_b128 v[148:151], v184
	ds_read_b128 v[176:179], v184 offset:1024
	ds_read_b128 v[180:183], v184 offset:2048
	ds_read_b128 v[184:187], v184 offset:3072
	s_cmpk_eq_i32 s52, 0x700
	s_cselect_b32 s73, s78, s73
	s_cselect_b32 s72, s55, s72
	s_cselect_b32 s75, s27, s75
	s_cselect_b32 s74, s54, s74
	s_cselect_b32 s77, s3, s77
	s_cselect_b32 s76, s29, s76
	s_add_i32 m0, s6, 0xc000
	ds_read_b128 v[188:191], v198
	ds_read_b128 v[200:203], v198 offset:1024
	ds_read_b128 v[208:211], v198 offset:2048
	ds_read_b128 v[214:217], v198 offset:3072
	ds_read_b128 v[230:233], v198 offset:4096
	ds_read_b128 v[234:237], v198 offset:5120
	ds_read_b128 v[238:241], v198 offset:6144
	ds_read_b128 v[242:245], v198 offset:7168
	global_load_lds_dwordx4 v172, s[98:99]
	s_add_i32 m0, s6, 0xe000
	s_nop 0
	global_load_lds_dwordx4 v174, s[98:99]
	s_waitcnt vmcnt(8)
	s_waitcnt lgkmcnt(0)
	s_barrier
	s_setprio 1
	s_waitcnt lgkmcnt(0)
	v_mfma_f32_16x16x32_bf16 v[124:127], v[132:135], v[188:191], v[124:127]
	v_mfma_f32_16x16x32_bf16 v[124:127], v[136:139], v[200:203], v[124:127]
	v_mfma_f32_16x16x32_bf16 v[120:123], v[140:143], v[188:191], v[120:123]
	v_mfma_f32_16x16x32_bf16 v[120:123], v[144:147], v[200:203], v[120:123]
	v_mfma_f32_16x16x32_bf16 v[108:111], v[132:135], v[208:211], v[108:111]
	v_mfma_f32_16x16x32_bf16 v[108:111], v[136:139], v[214:217], v[108:111]
	v_mfma_f32_16x16x32_bf16 v[104:107], v[140:143], v[208:211], v[104:107]
	v_mfma_f32_16x16x32_bf16 v[104:107], v[144:147], v[214:217], v[104:107]
	v_mfma_f32_16x16x32_bf16 v[92:95], v[132:135], v[230:233], v[92:95]
	v_mfma_f32_16x16x32_bf16 v[92:95], v[136:139], v[234:237], v[92:95]
	v_mfma_f32_16x16x32_bf16 v[88:91], v[140:143], v[230:233], v[88:91]
	v_mfma_f32_16x16x32_bf16 v[88:91], v[144:147], v[234:237], v[88:91]
	v_mfma_f32_16x16x32_bf16 v[76:79], v[132:135], v[238:241], v[76:79]
	v_mfma_f32_16x16x32_bf16 v[76:79], v[136:139], v[242:245], v[76:79]
	v_mfma_f32_16x16x32_bf16 v[72:75], v[140:143], v[238:241], v[72:75]
	v_mfma_f32_16x16x32_bf16 v[72:75], v[144:147], v[242:245], v[72:75]
	s_setprio 0
	s_setprio 1
	v_mfma_f32_16x16x32_bf16 v[116:119], v[148:151], v[188:191], v[116:119]
	v_mfma_f32_16x16x32_bf16 v[116:119], v[176:179], v[200:203], v[116:119]
	v_mfma_f32_16x16x32_bf16 v[112:115], v[180:183], v[188:191], v[112:115]
	v_mfma_f32_16x16x32_bf16 v[112:115], v[184:187], v[200:203], v[112:115]
	v_mfma_f32_16x16x32_bf16 v[100:103], v[148:151], v[208:211], v[100:103]
	v_mfma_f32_16x16x32_bf16 v[100:103], v[176:179], v[214:217], v[100:103]
	v_mfma_f32_16x16x32_bf16 v[96:99], v[180:183], v[208:211], v[96:99]
	v_mfma_f32_16x16x32_bf16 v[96:99], v[184:187], v[214:217], v[96:99]
	v_mfma_f32_16x16x32_bf16 v[84:87], v[148:151], v[230:233], v[84:87]
	v_mfma_f32_16x16x32_bf16 v[84:87], v[176:179], v[234:237], v[84:87]
	v_mfma_f32_16x16x32_bf16 v[80:83], v[180:183], v[230:233], v[80:83]
	v_mfma_f32_16x16x32_bf16 v[80:83], v[184:187], v[234:237], v[80:83]
	v_mfma_f32_16x16x32_bf16 v[68:71], v[148:151], v[238:241], v[68:71]
	v_mfma_f32_16x16x32_bf16 v[68:71], v[176:179], v[242:245], v[68:71]
	v_mfma_f32_16x16x32_bf16 v[64:67], v[180:183], v[238:241], v[64:67]
	v_mfma_f32_16x16x32_bf16 v[64:67], v[184:187], v[242:245], v[64:67]
	s_setprio 0
	s_barrier
	s_add_i32 s82, s82, s5
	s_mov_b32 m0, s82
	ds_read_b128 v[188:191], v198 offset:16384
	ds_read_b128 v[200:203], v198 offset:17408
	ds_read_b128 v[208:211], v198 offset:18432
	ds_read_b128 v[214:217], v198 offset:19456
	ds_read_b128 v[230:233], v198 offset:20480
	ds_read_b128 v[234:237], v198 offset:21504
	ds_read_b128 v[238:241], v198 offset:22528
	ds_read_b128 v[242:245], v198 offset:23552
	global_load_lds_dwordx4 v156, s[74:75]
	s_add_i32 m0, s82, 0x2000
	s_add_u32 s82, s74, 0x40000
	s_addc_u32 s83, s75, 0
	s_add_i32 s89, s89, s5
	global_load_lds_dwordx4 v168, s[74:75]
	s_mov_b32 m0, s89
	s_nop 0
	global_load_lds_dwordx4 v156, s[82:83]
	s_add_i32 m0, s89, 0x2000
	s_nop 0
	global_load_lds_dwordx4 v168, s[82:83]
	s_mov_b32 m0, s6
	s_nop 0
	global_load_lds_dwordx4 v152, s[76:77]
	s_mov_b32 m0, s7
	s_nop 0
	global_load_lds_dwordx4 v154, s[76:77]
	s_waitcnt vmcnt(8)
	s_waitcnt lgkmcnt(0)
	s_barrier
; #define PG8_STAGE(bufoff, gbase, voff) do { _Pragma("unroll") for (int _i = 0; _i < 2; ++_i) \
;         __builtin_amdgcn_global_load_lds((const unsigned*)((const char*)(gbase) + (voff)[_i]), (LAS unsigned*)(lds + (bufoff) + ldsw + _i * 8192), 16, 0, 0); } while (0)
; #define PG8_LDA(dst, b, h) do { _Pragma("unroll") for (int m = 0; m < 4; ++m) _Pragma("unroll") for (int k = 0; k < 2; ++k) dst[m][k] = *(const LAS bf16x8*)(lds + PG8_SA(b, h) + aoff + m * 2048 + k * 1024); } while (0)
; #define PG8_LDB(dst, b, h) do { _Pragma("unroll") for (int n = 0; n < 2; ++n) _Pragma("unroll") for (int k = 0; k < 2; ++k) dst[n][k] = *(const LAS bf16x8*)(lds + PG8_SB(b, h) + boff + n * 2048 + k * 1024); } while (0)
; #define PG8_MMA(ai, bj, At, Bt) do { __builtin_amdgcn_s_setprio(1); _Pragma("unroll") for (int m = 0; m < 4; ++m) _Pragma("unroll") for (int n = 0; n < 2; ++n) _Pragma("unroll") for (int k = 0; k < 2; ++k) \
;         acc[ai][bj][m][n] = __builtin_amdgcn_mfma_f32_16x16x32_bf16(Bt[n][k], At[m][k], acc[ai][bj][m][n], 0, 0, 0); __builtin_amdgcn_s_setprio(0); } while (0)
; #define PG8_WAIT_V(n) asm volatile("s_waitcnt vmcnt(" #n ")" ::: "memory")
; #define PG8_WAIT_L(n) asm volatile("s_waitcnt lgkmcnt(" #n ")" ::: "memory")
; #define PG8_BAR __builtin_amdgcn_s_barrier()
; #define PG8_SCHED __builtin_amdgcn_sched_barrier(0)
;     ...
;             PG8_WAIT_V(8); PG8_WAIT_L(0); PG8_BAR; PG8_MMA(1, 0, At, B0); PG8_MMA(1, 1, At, B1); PG8_BAR; PG8_SCHED;
;             PG8_LDB(B0, 1, 0); PG8_LDB(B1, 1, 1); PG8_SCHED; PG8_LDA(At, 1, 0); PG8_STAGE(PG8_SA(0, 1), a2 + hA, voffA);
;             PG8_WAIT_V(8); PG8_WAIT_L(0); PG8_BAR; PG8_MMA(0, 0, At, B0); PG8_MMA(0, 1, At, B1); PG8_BAR; PG8_SCHED;
	s_setprio 1
	s_waitcnt lgkmcnt(0)
	v_mfma_f32_16x16x32_bf16 v[60:63], v[132:135], v[188:191], v[60:63]
	v_mfma_f32_16x16x32_bf16 v[60:63], v[136:139], v[200:203], v[60:63]
	v_mfma_f32_16x16x32_bf16 v[56:59], v[140:143], v[188:191], v[56:59]
	v_mfma_f32_16x16x32_bf16 v[56:59], v[144:147], v[200:203], v[56:59]
	v_mfma_f32_16x16x32_bf16 v[44:47], v[132:135], v[208:211], v[44:47]
	v_mfma_f32_16x16x32_bf16 v[44:47], v[136:139], v[214:217], v[44:47]
	v_mfma_f32_16x16x32_bf16 v[40:43], v[140:143], v[208:211], v[40:43]
	v_mfma_f32_16x16x32_bf16 v[40:43], v[144:147], v[214:217], v[40:43]
	v_mfma_f32_16x16x32_bf16 v[28:31], v[132:135], v[230:233], v[28:31]
	v_mfma_f32_16x16x32_bf16 v[28:31], v[136:139], v[234:237], v[28:31]
	v_mfma_f32_16x16x32_bf16 v[24:27], v[140:143], v[230:233], v[24:27]
	v_mfma_f32_16x16x32_bf16 v[24:27], v[144:147], v[234:237], v[24:27]
	v_mfma_f32_16x16x32_bf16 v[12:15], v[132:135], v[238:241], v[12:15]
	v_mfma_f32_16x16x32_bf16 v[12:15], v[136:139], v[242:245], v[12:15]
	v_mfma_f32_16x16x32_bf16 v[8:11], v[140:143], v[238:241], v[8:11]
	v_mfma_f32_16x16x32_bf16 v[8:11], v[144:147], v[242:245], v[8:11]
	s_setprio 0
	s_setprio 1
	v_mfma_f32_16x16x32_bf16 v[52:55], v[148:151], v[188:191], v[52:55]
	v_mfma_f32_16x16x32_bf16 v[52:55], v[176:179], v[200:203], v[52:55]
	v_mfma_f32_16x16x32_bf16 v[48:51], v[180:183], v[188:191], v[48:51]
	v_mfma_f32_16x16x32_bf16 v[48:51], v[184:187], v[200:203], v[48:51]
	v_mfma_f32_16x16x32_bf16 v[36:39], v[148:151], v[208:211], v[36:39]
	v_mfma_f32_16x16x32_bf16 v[36:39], v[176:179], v[214:217], v[36:39]
	v_mfma_f32_16x16x32_bf16 v[32:35], v[180:183], v[208:211], v[32:35]
	v_mfma_f32_16x16x32_bf16 v[32:35], v[184:187], v[214:217], v[32:35]
	v_mfma_f32_16x16x32_bf16 v[20:23], v[148:151], v[230:233], v[20:23]
	v_mfma_f32_16x16x32_bf16 v[20:23], v[176:179], v[234:237], v[20:23]
	v_mfma_f32_16x16x32_bf16 v[16:19], v[180:183], v[230:233], v[16:19]
	v_mfma_f32_16x16x32_bf16 v[16:19], v[184:187], v[234:237], v[16:19]
	v_mfma_f32_16x16x32_bf16 v[4:7], v[148:151], v[238:241], v[4:7]
	v_mfma_f32_16x16x32_bf16 v[4:7], v[176:179], v[242:245], v[4:7]
	v_mfma_f32_16x16x32_bf16 v[0:3], v[180:183], v[238:241], v[0:3]
	v_mfma_f32_16x16x32_bf16 v[0:3], v[184:187], v[242:245], v[0:3]
	s_setprio 0
	s_barrier
	s_add_i32 s82, 0, 0x18000
	s_add_i32 s83, 0, 0x1c000
	v_add_u32_e32 v144, s82, v193
	v_add_u32_e32 v184, s83, v193
	ds_read_b128 v[132:135], v144
	ds_read_b128 v[136:139], v144 offset:1024
	ds_read_b128 v[140:143], v144 offset:2048
	ds_read_b128 v[144:147], v144 offset:3072
	ds_read_b128 v[148:151], v184
	ds_read_b128 v[176:179], v184 offset:1024
	ds_read_b128 v[180:183], v184 offset:2048
	ds_read_b128 v[184:187], v184 offset:3072
	s_add_u32 s76, s76, 0x40000
	s_addc_u32 s77, s77, 0
	s_mov_b32 m0, s8
	ds_read_b128 v[188:191], v198 offset:32768
	ds_read_b128 v[200:203], v198 offset:33792
	ds_read_b128 v[208:211], v198 offset:34816
	ds_read_b128 v[214:217], v198 offset:35840
	ds_read_b128 v[230:233], v198 offset:36864
	ds_read_b128 v[234:237], v198 offset:37888
	ds_read_b128 v[238:241], v198 offset:38912
	ds_read_b128 v[242:245], v198 offset:39936
	global_load_lds_dwordx4 v152, s[76:77]
	s_mov_b32 m0, s9
	s_nop 0
	global_load_lds_dwordx4 v154, s[76:77]
	s_waitcnt vmcnt(8)
	s_waitcnt lgkmcnt(0)
	s_barrier
	s_setprio 1
	s_waitcnt lgkmcnt(0)
	v_mfma_f32_16x16x32_bf16 v[124:127], v[132:135], v[188:191], v[124:127]
	v_mfma_f32_16x16x32_bf16 v[124:127], v[136:139], v[200:203], v[124:127]
	v_mfma_f32_16x16x32_bf16 v[120:123], v[140:143], v[188:191], v[120:123]
	v_mfma_f32_16x16x32_bf16 v[120:123], v[144:147], v[200:203], v[120:123]
	v_mfma_f32_16x16x32_bf16 v[108:111], v[132:135], v[208:211], v[108:111]
	v_mfma_f32_16x16x32_bf16 v[108:111], v[136:139], v[214:217], v[108:111]
	v_mfma_f32_16x16x32_bf16 v[104:107], v[140:143], v[208:211], v[104:107]
	v_mfma_f32_16x16x32_bf16 v[104:107], v[144:147], v[214:217], v[104:107]
	v_mfma_f32_16x16x32_bf16 v[92:95], v[132:135], v[230:233], v[92:95]
	v_mfma_f32_16x16x32_bf16 v[92:95], v[136:139], v[234:237], v[92:95]
	v_mfma_f32_16x16x32_bf16 v[88:91], v[140:143], v[230:233], v[88:91]
	v_mfma_f32_16x16x32_bf16 v[88:91], v[144:147], v[234:237], v[88:91]
	v_mfma_f32_16x16x32_bf16 v[76:79], v[132:135], v[238:241], v[76:79]
	v_mfma_f32_16x16x32_bf16 v[76:79], v[136:139], v[242:245], v[76:79]
	v_mfma_f32_16x16x32_bf16 v[72:75], v[140:143], v[238:241], v[72:75]
	v_mfma_f32_16x16x32_bf16 v[72:75], v[144:147], v[242:245], v[72:75]
	s_setprio 0
	s_setprio 1
	v_mfma_f32_16x16x32_bf16 v[116:119], v[148:151], v[188:191], v[116:119]
	v_mfma_f32_16x16x32_bf16 v[116:119], v[176:179], v[200:203], v[116:119]
	v_mfma_f32_16x16x32_bf16 v[112:115], v[180:183], v[188:191], v[112:115]
	v_mfma_f32_16x16x32_bf16 v[112:115], v[184:187], v[200:203], v[112:115]
	v_mfma_f32_16x16x32_bf16 v[100:103], v[148:151], v[208:211], v[100:103]
	v_mfma_f32_16x16x32_bf16 v[100:103], v[176:179], v[214:217], v[100:103]
	v_mfma_f32_16x16x32_bf16 v[96:99], v[180:183], v[208:211], v[96:99]
	v_mfma_f32_16x16x32_bf16 v[96:99], v[184:187], v[214:217], v[96:99]
	v_mfma_f32_16x16x32_bf16 v[84:87], v[148:151], v[230:233], v[84:87]
	v_mfma_f32_16x16x32_bf16 v[84:87], v[176:179], v[234:237], v[84:87]
	v_mfma_f32_16x16x32_bf16 v[80:83], v[180:183], v[230:233], v[80:83]
	v_mfma_f32_16x16x32_bf16 v[80:83], v[184:187], v[234:237], v[80:83]
	v_mfma_f32_16x16x32_bf16 v[68:71], v[148:151], v[238:241], v[68:71]
	v_mfma_f32_16x16x32_bf16 v[68:71], v[176:179], v[242:245], v[68:71]
	v_mfma_f32_16x16x32_bf16 v[64:67], v[180:183], v[238:241], v[64:67]
	v_mfma_f32_16x16x32_bf16 v[64:67], v[184:187], v[242:245], v[64:67]
	s_setprio 0
	s_barrier
; #define PG8_STAGE(bufoff, gbase, voff) do { _Pragma("unroll") for (int _i = 0; _i < 2; ++_i) \
;         __builtin_amdgcn_global_load_lds((const unsigned*)((const char*)(gbase) + (voff)[_i]), (LAS unsigned*)(lds + (bufoff) + ldsw + _i * 8192), 16, 0, 0); } while (0)
; #define PG8_LDA(dst, b, h) do { _Pragma("unroll") for (int m = 0; m < 4; ++m) _Pragma("unroll") for (int k = 0; k < 2; ++k) dst[m][k] = *(const LAS bf16x8*)(lds + PG8_SA(b, h) + aoff + m * 2048 + k * 1024); } while (0)
; #define PG8_MMA(ai, bj, At, Bt) do { __builtin_amdgcn_s_setprio(1); _Pragma("unroll") for (int m = 0; m < 4; ++m) _Pragma("unroll") for (int n = 0; n < 2; ++n) _Pragma("unroll") for (int k = 0; k < 2; ++k) \
;         acc[ai][bj][m][n] = __builtin_amdgcn_mfma_f32_16x16x32_bf16(Bt[n][k], At[m][k], acc[ai][bj][m][n], 0, 0, 0); __builtin_amdgcn_s_setprio(0); } while (0)
; #define PG8_WAIT_V(n) asm volatile("s_waitcnt vmcnt(" #n ")" ::: "memory")
; #define PG8_WAIT_L(n) asm volatile("s_waitcnt lgkmcnt(" #n ")" ::: "memory")
; #define PG8_BAR __builtin_amdgcn_s_barrier()
; #define PG8_SCHED __builtin_amdgcn_sched_barrier(0)
;     ...
;         for (int t = 0; t < nt; t += 2) {
;     ...
;             PG8_LDA(At, 1, 1); PG8_STAGE(PG8_SB(1, 0), b3, voffB); PG8_STAGE(PG8_SB(1, 1), b3 + hB, voffB); PG8_STAGE(PG8_SA(1, 0), a3, voffA);
;             PG8_WAIT_V(8); PG8_WAIT_L(0); PG8_BAR; PG8_MMA(1, 0, At, B0); PG8_MMA(1, 1, At, B1); PG8_BAR; PG8_SCHED;
	s_add_i32 s76, s82, s5
	s_add_u32 s100, s74, s38
	s_addc_u32 s101, s75, s39
	s_mov_b32 m0, s76
	ds_read_b128 v[188:191], v198 offset:49152
	ds_read_b128 v[200:203], v198 offset:50176
	ds_read_b128 v[208:211], v198 offset:51200
	ds_read_b128 v[214:217], v198 offset:52224
	ds_read_b128 v[230:233], v198 offset:53248
	ds_read_b128 v[234:237], v198 offset:54272
	ds_read_b128 v[238:241], v198 offset:55296
	ds_read_b128 v[242:245], v198 offset:56320
	global_load_lds_dwordx4 v156, s[100:101]
	s_add_i32 m0, s76, 0x2000
	s_add_u32 s74, s74, 0x40080
	s_addc_u32 s75, s75, 0
	s_add_i32 s76, s83, s5
	global_load_lds_dwordx4 v168, s[100:101]
	s_mov_b32 m0, s76
	s_nop 0
	global_load_lds_dwordx4 v156, s[74:75]
	s_add_i32 m0, s76, 0x2000
	s_nop 0
	global_load_lds_dwordx4 v168, s[74:75]
	s_mov_b32 m0, s36
	s_nop 0
	global_load_lds_dwordx4 v152, s[72:73]
	s_mov_b32 m0, s42
	s_nop 0
	global_load_lds_dwordx4 v154, s[72:73]
	s_waitcnt vmcnt(8)
	s_waitcnt lgkmcnt(0)
	s_barrier
	s_setprio 1
	s_waitcnt lgkmcnt(0)
	v_mfma_f32_16x16x32_bf16 v[60:63], v[132:135], v[188:191], v[60:63]
	v_mfma_f32_16x16x32_bf16 v[60:63], v[136:139], v[200:203], v[60:63]
	v_mfma_f32_16x16x32_bf16 v[56:59], v[140:143], v[188:191], v[56:59]
	v_mfma_f32_16x16x32_bf16 v[56:59], v[144:147], v[200:203], v[56:59]
	v_mfma_f32_16x16x32_bf16 v[44:47], v[132:135], v[208:211], v[44:47]
	v_mfma_f32_16x16x32_bf16 v[44:47], v[136:139], v[214:217], v[44:47]
	v_mfma_f32_16x16x32_bf16 v[40:43], v[140:143], v[208:211], v[40:43]
	v_mfma_f32_16x16x32_bf16 v[40:43], v[144:147], v[214:217], v[40:43]
	v_mfma_f32_16x16x32_bf16 v[28:31], v[132:135], v[230:233], v[28:31]
	v_mfma_f32_16x16x32_bf16 v[28:31], v[136:139], v[234:237], v[28:31]
	v_mfma_f32_16x16x32_bf16 v[24:27], v[140:143], v[230:233], v[24:27]
	v_mfma_f32_16x16x32_bf16 v[24:27], v[144:147], v[234:237], v[24:27]
	v_mfma_f32_16x16x32_bf16 v[12:15], v[132:135], v[238:241], v[12:15]
	v_mfma_f32_16x16x32_bf16 v[12:15], v[136:139], v[242:245], v[12:15]
	v_mfma_f32_16x16x32_bf16 v[8:11], v[140:143], v[238:241], v[8:11]
	v_mfma_f32_16x16x32_bf16 v[8:11], v[144:147], v[242:245], v[8:11]
	s_setprio 0
	s_setprio 1
	v_mfma_f32_16x16x32_bf16 v[52:55], v[148:151], v[188:191], v[52:55]
	v_mfma_f32_16x16x32_bf16 v[52:55], v[176:179], v[200:203], v[52:55]
	v_mfma_f32_16x16x32_bf16 v[48:51], v[180:183], v[188:191], v[48:51]
	v_mfma_f32_16x16x32_bf16 v[48:51], v[184:187], v[200:203], v[48:51]
	v_mfma_f32_16x16x32_bf16 v[36:39], v[148:151], v[208:211], v[36:39]
	v_mfma_f32_16x16x32_bf16 v[36:39], v[176:179], v[214:217], v[36:39]
	v_mfma_f32_16x16x32_bf16 v[32:35], v[180:183], v[208:211], v[32:35]
	v_mfma_f32_16x16x32_bf16 v[32:35], v[184:187], v[214:217], v[32:35]
	v_mfma_f32_16x16x32_bf16 v[20:23], v[148:151], v[230:233], v[20:23]
	v_mfma_f32_16x16x32_bf16 v[20:23], v[176:179], v[234:237], v[20:23]
	v_mfma_f32_16x16x32_bf16 v[16:19], v[180:183], v[230:233], v[16:19]
	v_mfma_f32_16x16x32_bf16 v[16:19], v[184:187], v[234:237], v[16:19]
	v_mfma_f32_16x16x32_bf16 v[4:7], v[148:151], v[238:241], v[4:7]
	v_mfma_f32_16x16x32_bf16 v[4:7], v[176:179], v[242:245], v[4:7]
	v_mfma_f32_16x16x32_bf16 v[0:3], v[180:183], v[238:241], v[0:3]
	v_mfma_f32_16x16x32_bf16 v[0:3], v[184:187], v[242:245], v[0:3]
	s_setprio 0
	s_barrier
	s_add_i32 s81, s81, 2
	s_add_u32 s52, s52, 0x100
	s_addc_u32 s53, s53, 0
	s_cmp_gt_u32 s81, 13
	s_cbranch_scc0 .LBB0_299
	s_and_b64 vcc, exec, s[16:17]
	s_cbranch_vccz .LBB0_302
	s_barrier

; #define PG8_STAGE(bufoff, gbase, voff) do { _Pragma("unroll") for (int _i = 0; _i < 2; ++_i) \
;         __builtin_amdgcn_global_load_lds((const unsigned*)((const char*)(gbase) + (voff)[_i]), (LAS unsigned*)(lds + (bufoff) + ldsw + _i * 8192), 16, 0, 0); } while (0)
; #define PG8_LDA(dst, b, h) do { _Pragma("unroll") for (int m = 0; m < 4; ++m) _Pragma("unroll") for (int k = 0; k < 2; ++k) dst[m][k] = *(const LAS bf16x8*)(lds + PG8_SA(b, h) + aoff + m * 2048 + k * 1024); } while (0)
; #define PG8_LDB(dst, b, h) do { _Pragma("unroll") for (int n = 0; n < 2; ++n) _Pragma("unroll") for (int k = 0; k < 2; ++k) dst[n][k] = *(const LAS bf16x8*)(lds + PG8_SB(b, h) + boff + n * 2048 + k * 1024); } while (0)
; #define PG8_MMA(ai, bj, At, Bt) do { __builtin_amdgcn_s_setprio(1); _Pragma("unroll") for (int m = 0; m < 4; ++m) _Pragma("unroll") for (int n = 0; n < 2; ++n) _Pragma("unroll") for (int k = 0; k < 2; ++k) \
;         acc[ai][bj][m][n] = __builtin_amdgcn_mfma_f32_16x16x32_bf16(Bt[n][k], At[m][k], acc[ai][bj][m][n], 0, 0, 0); __builtin_amdgcn_s_setprio(0); } while (0)
; #define PG8_WAIT_V(n) asm volatile("s_waitcnt vmcnt(" #n ")" ::: "memory")
; #define PG8_WAIT_L(n) asm volatile("s_waitcnt lgkmcnt(" #n ")" ::: "memory")
; #define PG8_BAR __builtin_amdgcn_s_barrier()
; #define PG8_SCHED __builtin_amdgcn_sched_barrier(0)
;     ...
;             const bool last = (t == nt - 2);
;             const char* a1 = PG8_ATILE(cA, cA2, t + 1);
;             const char* a2 = last ? nA : PG8_ATILE(cA, cA2, t + 2); const char* b2 = last ? nB : cB + (size_t)(t + 2) * 128;
;             const char* a3 = last ? nA + kA1 : PG8_ATILE(cA, cA2, t + 3); const char* b3 = b2 + kB1;
;             if constexpr (SP2) {
;             PG8_LDB(B0, 0, 0); PG8_LDB(B1, 0, 1); PG8_SCHED; PG8_LDA(At, 0, 0); PG8_STAGE(PG8_SA(1, 1), a1 + hA, voffA);
;             PG8_WAIT_V(8); PG8_WAIT_L(0); PG8_BAR; PG8_MMA(0, 0, At, B0); PG8_MMA(0, 1, At, B1); PG8_BAR; PG8_SCHED;
;             PG8_LDA(At, 0, 1); PG8_STAGE(PG8_SB(0, 0), b2, voffB); PG8_STAGE(PG8_SB(0, 1), b2 + hB, voffB); PG8_STAGE(PG8_SA(0, 0), a2, voffA);
;             PG8_WAIT_V(8); PG8_WAIT_L(0); PG8_BAR; PG8_MMA(1, 0, At, B0); PG8_MMA(1, 1, At, B1); PG8_BAR; PG8_SCHED;
.LBB0_364:
	s_add_i32 s6, s74, 2
	s_add_u32 s26, s92, vcc_lo
	s_addc_u32 s27, s93, vcc_hi
	s_add_u32 s98, s26, 0x80
	s_addc_u32 s99, s27, 0
	s_add_u32 s76, s26, 0x100
	s_addc_u32 s77, s27, 0
	s_add_u32 s9, s94, vcc_lo
	s_addc_u32 s8, s95, vcc_hi
	s_add_u32 s26, s26, 0x180
	s_addc_u32 s27, s27, 0
	s_add_i32 s50, 0, 0x10000
	s_add_i32 s51, 0, 0x14000
	v_add_u32_e32 v154, s50, v168
	ds_read_b128 v[132:135], v154
	ds_read_b128 v[146:149], v154 offset:1024
	ds_read_b128 v[150:153], v154 offset:2048
	ds_read_b128 v[172:175], v154 offset:3072
	v_add_u32_e32 v154, s51, v168
	ds_read_b128 v[176:179], v154
	ds_read_b128 v[180:183], v154 offset:1024
	ds_read_b128 v[184:187], v154 offset:2048
	ds_read_b128 v[188:191], v154 offset:3072
	s_cmp_eq_u32 s5, s74
	s_cselect_b32 s74, s97, s26
	s_cselect_b32 s75, s79, s27
	s_cselect_b32 s27, s45, s8
	s_cselect_b32 s26, s96, s9
	s_cselect_b32 s77, s43, s77
	s_cselect_b32 s76, s82, s76
	s_add_i32 m0, s83, 0xc000
	ds_read_b128 v[192:195], v170
	ds_read_b128 v[196:199], v170 offset:1024
	ds_read_b128 v[200:203], v170 offset:2048
	ds_read_b128 v[208:211], v170 offset:3072
	ds_read_b128 v[214:217], v170 offset:4096
	ds_read_b128 v[230:233], v170 offset:5120
	ds_read_b128 v[234:237], v170 offset:6144
	ds_read_b128 v[238:241], v170 offset:7168
	global_load_lds_dwordx4 v144, s[98:99]
	s_add_i32 m0, s83, 0xe000
	s_nop 0
	global_load_lds_dwordx4 v142, s[98:99]
	s_waitcnt vmcnt(8)
	s_waitcnt lgkmcnt(0)
	s_barrier
	s_setprio 1
	s_waitcnt lgkmcnt(0)
	v_mfma_f32_16x16x32_bf16 v[124:127], v[132:135], v[192:195], v[124:127]
	v_mfma_f32_16x16x32_bf16 v[124:127], v[146:149], v[196:199], v[124:127]
	v_mfma_f32_16x16x32_bf16 v[120:123], v[150:153], v[192:195], v[120:123]
	v_mfma_f32_16x16x32_bf16 v[120:123], v[172:175], v[196:199], v[120:123]
	v_mfma_f32_16x16x32_bf16 v[108:111], v[132:135], v[200:203], v[108:111]
	v_mfma_f32_16x16x32_bf16 v[108:111], v[146:149], v[208:211], v[108:111]
	v_mfma_f32_16x16x32_bf16 v[104:107], v[150:153], v[200:203], v[104:107]
	v_mfma_f32_16x16x32_bf16 v[104:107], v[172:175], v[208:211], v[104:107]
	v_mfma_f32_16x16x32_bf16 v[92:95], v[132:135], v[214:217], v[92:95]
	v_mfma_f32_16x16x32_bf16 v[92:95], v[146:149], v[230:233], v[92:95]
	v_mfma_f32_16x16x32_bf16 v[88:91], v[150:153], v[214:217], v[88:91]
	v_mfma_f32_16x16x32_bf16 v[88:91], v[172:175], v[230:233], v[88:91]
	v_mfma_f32_16x16x32_bf16 v[76:79], v[132:135], v[234:237], v[76:79]
	v_mfma_f32_16x16x32_bf16 v[76:79], v[146:149], v[238:241], v[76:79]
	v_mfma_f32_16x16x32_bf16 v[72:75], v[150:153], v[234:237], v[72:75]
	v_mfma_f32_16x16x32_bf16 v[72:75], v[172:175], v[238:241], v[72:75]
	s_setprio 0
	s_setprio 1
	v_mfma_f32_16x16x32_bf16 v[116:119], v[176:179], v[192:195], v[116:119]
	v_mfma_f32_16x16x32_bf16 v[116:119], v[180:183], v[196:199], v[116:119]
	v_mfma_f32_16x16x32_bf16 v[112:115], v[184:187], v[192:195], v[112:115]
	v_mfma_f32_16x16x32_bf16 v[112:115], v[188:191], v[196:199], v[112:115]
	v_mfma_f32_16x16x32_bf16 v[100:103], v[176:179], v[200:203], v[100:103]
	v_mfma_f32_16x16x32_bf16 v[100:103], v[180:183], v[208:211], v[100:103]
	v_mfma_f32_16x16x32_bf16 v[96:99], v[184:187], v[200:203], v[96:99]
	v_mfma_f32_16x16x32_bf16 v[96:99], v[188:191], v[208:211], v[96:99]
	v_mfma_f32_16x16x32_bf16 v[84:87], v[176:179], v[214:217], v[84:87]
	v_mfma_f32_16x16x32_bf16 v[84:87], v[180:183], v[230:233], v[84:87]
	v_mfma_f32_16x16x32_bf16 v[80:83], v[184:187], v[214:217], v[80:83]
	v_mfma_f32_16x16x32_bf16 v[80:83], v[188:191], v[230:233], v[80:83]
	v_mfma_f32_16x16x32_bf16 v[68:71], v[176:179], v[234:237], v[68:71]
	v_mfma_f32_16x16x32_bf16 v[68:71], v[180:183], v[238:241], v[68:71]
	v_mfma_f32_16x16x32_bf16 v[64:67], v[184:187], v[234:237], v[64:67]
	v_mfma_f32_16x16x32_bf16 v[64:67], v[188:191], v[238:241], v[64:67]
	s_setprio 0
	s_barrier
	s_add_i32 s8, s50, s81
	s_mov_b32 m0, s8
	ds_read_b128 v[192:195], v170 offset:16384
	ds_read_b128 v[196:199], v170 offset:17408
	ds_read_b128 v[200:203], v170 offset:18432
	ds_read_b128 v[208:211], v170 offset:19456
	ds_read_b128 v[214:217], v170 offset:20480
	ds_read_b128 v[230:233], v170 offset:21504
	ds_read_b128 v[234:237], v170 offset:22528
	ds_read_b128 v[238:241], v170 offset:23552
	global_load_lds_dwordx4 v156, s[26:27]
	s_add_i32 m0, s8, 0x2000
	s_mov_b64 s[100:101], s[26:27]
	s_add_u32 s26, s26, s16
	s_addc_u32 s27, s27, 0
	s_add_i32 s8, s51, s81
	global_load_lds_dwordx4 v140, s[100:101]
	s_mov_b32 m0, s8
	s_nop 0
	global_load_lds_dwordx4 v156, s[26:27]
	s_add_i32 m0, s8, 0x2000
	s_nop 0
	global_load_lds_dwordx4 v140, s[26:27]
	s_mov_b32 m0, s83
	s_nop 0
	global_load_lds_dwordx4 v136, s[76:77]
	s_mov_b32 m0, s2
	s_nop 0
	global_load_lds_dwordx4 v138, s[76:77]
	s_waitcnt vmcnt(8)
	s_waitcnt lgkmcnt(0)
	s_barrier
; #define PG8_STAGE(bufoff, gbase, voff) do { _Pragma("unroll") for (int _i = 0; _i < 2; ++_i) \
;         __builtin_amdgcn_global_load_lds((const unsigned*)((const char*)(gbase) + (voff)[_i]), (LAS unsigned*)(lds + (bufoff) + ldsw + _i * 8192), 16, 0, 0); } while (0)
; #define PG8_LDA(dst, b, h) do { _Pragma("unroll") for (int m = 0; m < 4; ++m) _Pragma("unroll") for (int k = 0; k < 2; ++k) dst[m][k] = *(const LAS bf16x8*)(lds + PG8_SA(b, h) + aoff + m * 2048 + k * 1024); } while (0)
; #define PG8_LDB(dst, b, h) do { _Pragma("unroll") for (int n = 0; n < 2; ++n) _Pragma("unroll") for (int k = 0; k < 2; ++k) dst[n][k] = *(const LAS bf16x8*)(lds + PG8_SB(b, h) + boff + n * 2048 + k * 1024); } while (0)
; #define PG8_MMA(ai, bj, At, Bt) do { __builtin_amdgcn_s_setprio(1); _Pragma("unroll") for (int m = 0; m < 4; ++m) _Pragma("unroll") for (int n = 0; n < 2; ++n) _Pragma("unroll") for (int k = 0; k < 2; ++k) \
;         acc[ai][bj][m][n] = __builtin_amdgcn_mfma_f32_16x16x32_bf16(Bt[n][k], At[m][k], acc[ai][bj][m][n], 0, 0, 0); __builtin_amdgcn_s_setprio(0); } while (0)
; #define PG8_WAIT_V(n) asm volatile("s_waitcnt vmcnt(" #n ")" ::: "memory")
; #define PG8_WAIT_L(n) asm volatile("s_waitcnt lgkmcnt(" #n ")" ::: "memory")
; #define PG8_BAR __builtin_amdgcn_s_barrier()
; #define PG8_SCHED __builtin_amdgcn_sched_barrier(0)
;     ...
;             PG8_WAIT_V(8); PG8_WAIT_L(0); PG8_BAR; PG8_MMA(1, 0, At, B0); PG8_MMA(1, 1, At, B1); PG8_BAR; PG8_SCHED;
;             PG8_LDB(B0, 1, 0); PG8_LDB(B1, 1, 1); PG8_SCHED; PG8_LDA(At, 1, 0); PG8_STAGE(PG8_SA(0, 1), a2 + hA, voffA);
;             PG8_WAIT_V(8); PG8_WAIT_L(0); PG8_BAR; PG8_MMA(0, 0, At, B0); PG8_MMA(0, 1, At, B1); PG8_BAR; PG8_SCHED;
	s_setprio 1
	s_waitcnt lgkmcnt(0)
	v_mfma_f32_16x16x32_bf16 v[60:63], v[132:135], v[192:195], v[60:63]
	v_mfma_f32_16x16x32_bf16 v[60:63], v[146:149], v[196:199], v[60:63]
	v_mfma_f32_16x16x32_bf16 v[56:59], v[150:153], v[192:195], v[56:59]
	v_mfma_f32_16x16x32_bf16 v[56:59], v[172:175], v[196:199], v[56:59]
	v_mfma_f32_16x16x32_bf16 v[44:47], v[132:135], v[200:203], v[44:47]
	v_mfma_f32_16x16x32_bf16 v[44:47], v[146:149], v[208:211], v[44:47]
	v_mfma_f32_16x16x32_bf16 v[40:43], v[150:153], v[200:203], v[40:43]
	v_mfma_f32_16x16x32_bf16 v[40:43], v[172:175], v[208:211], v[40:43]
	v_mfma_f32_16x16x32_bf16 v[28:31], v[132:135], v[214:217], v[28:31]
	v_mfma_f32_16x16x32_bf16 v[28:31], v[146:149], v[230:233], v[28:31]
	v_mfma_f32_16x16x32_bf16 v[24:27], v[150:153], v[214:217], v[24:27]
	v_mfma_f32_16x16x32_bf16 v[24:27], v[172:175], v[230:233], v[24:27]
	v_mfma_f32_16x16x32_bf16 v[12:15], v[132:135], v[234:237], v[12:15]
	v_mfma_f32_16x16x32_bf16 v[12:15], v[146:149], v[238:241], v[12:15]
	v_mfma_f32_16x16x32_bf16 v[8:11], v[150:153], v[234:237], v[8:11]
	v_mfma_f32_16x16x32_bf16 v[8:11], v[172:175], v[238:241], v[8:11]
	s_setprio 0
	s_setprio 1
	v_mfma_f32_16x16x32_bf16 v[52:55], v[176:179], v[192:195], v[52:55]
	v_mfma_f32_16x16x32_bf16 v[52:55], v[180:183], v[196:199], v[52:55]
	v_mfma_f32_16x16x32_bf16 v[48:51], v[184:187], v[192:195], v[48:51]
	v_mfma_f32_16x16x32_bf16 v[48:51], v[188:191], v[196:199], v[48:51]
	v_mfma_f32_16x16x32_bf16 v[36:39], v[176:179], v[200:203], v[36:39]
	v_mfma_f32_16x16x32_bf16 v[36:39], v[180:183], v[208:211], v[36:39]
	v_mfma_f32_16x16x32_bf16 v[32:35], v[184:187], v[200:203], v[32:35]
	v_mfma_f32_16x16x32_bf16 v[32:35], v[188:191], v[208:211], v[32:35]
	v_mfma_f32_16x16x32_bf16 v[20:23], v[176:179], v[214:217], v[20:23]
	v_mfma_f32_16x16x32_bf16 v[20:23], v[180:183], v[230:233], v[20:23]
	v_mfma_f32_16x16x32_bf16 v[16:19], v[184:187], v[214:217], v[16:19]
	v_mfma_f32_16x16x32_bf16 v[16:19], v[188:191], v[230:233], v[16:19]
	v_mfma_f32_16x16x32_bf16 v[4:7], v[176:179], v[234:237], v[4:7]
	v_mfma_f32_16x16x32_bf16 v[4:7], v[180:183], v[238:241], v[4:7]
	v_mfma_f32_16x16x32_bf16 v[0:3], v[184:187], v[234:237], v[0:3]
	v_mfma_f32_16x16x32_bf16 v[0:3], v[188:191], v[238:241], v[0:3]
	s_setprio 0
	s_barrier
	s_add_i32 s8, 0, 0x18000
	v_add_u32_e32 v171, s8, v168
	s_add_i32 s9, 0, 0x1c000
	ds_read_b128 v[132:135], v171
	ds_read_b128 v[146:149], v171 offset:1024
	ds_read_b128 v[150:153], v171 offset:2048
	ds_read_b128 v[172:175], v171 offset:3072
	v_add_u32_e32 v171, s9, v168
	ds_read_b128 v[176:179], v171
	ds_read_b128 v[180:183], v171 offset:1024
	ds_read_b128 v[184:187], v171 offset:2048
	ds_read_b128 v[188:191], v171 offset:3072
	s_add_u32 s26, s76, s16
	s_addc_u32 s27, s77, 0
	s_mov_b32 m0, s3
	ds_read_b128 v[192:195], v170 offset:32768
	ds_read_b128 v[196:199], v170 offset:33792
	ds_read_b128 v[200:203], v170 offset:34816
	ds_read_b128 v[208:211], v170 offset:35840
	ds_read_b128 v[214:217], v170 offset:36864
	ds_read_b128 v[230:233], v170 offset:37888
	ds_read_b128 v[234:237], v170 offset:38912
	ds_read_b128 v[238:241], v170 offset:39936
	global_load_lds_dwordx4 v136, s[26:27]
	s_mov_b32 m0, s0
	s_nop 0
	global_load_lds_dwordx4 v138, s[26:27]
	s_waitcnt vmcnt(8)
	s_waitcnt lgkmcnt(0)
	s_barrier
	s_setprio 1
	s_waitcnt lgkmcnt(0)
	v_mfma_f32_16x16x32_bf16 v[124:127], v[132:135], v[192:195], v[124:127]
	v_mfma_f32_16x16x32_bf16 v[124:127], v[146:149], v[196:199], v[124:127]
	v_mfma_f32_16x16x32_bf16 v[120:123], v[150:153], v[192:195], v[120:123]
	v_mfma_f32_16x16x32_bf16 v[120:123], v[172:175], v[196:199], v[120:123]
	v_mfma_f32_16x16x32_bf16 v[108:111], v[132:135], v[200:203], v[108:111]
	v_mfma_f32_16x16x32_bf16 v[108:111], v[146:149], v[208:211], v[108:111]
	v_mfma_f32_16x16x32_bf16 v[104:107], v[150:153], v[200:203], v[104:107]
	v_mfma_f32_16x16x32_bf16 v[104:107], v[172:175], v[208:211], v[104:107]
	v_mfma_f32_16x16x32_bf16 v[92:95], v[132:135], v[214:217], v[92:95]
	v_mfma_f32_16x16x32_bf16 v[92:95], v[146:149], v[230:233], v[92:95]
	v_mfma_f32_16x16x32_bf16 v[88:91], v[150:153], v[214:217], v[88:91]
	v_mfma_f32_16x16x32_bf16 v[88:91], v[172:175], v[230:233], v[88:91]
	v_mfma_f32_16x16x32_bf16 v[76:79], v[132:135], v[234:237], v[76:79]
	v_mfma_f32_16x16x32_bf16 v[76:79], v[146:149], v[238:241], v[76:79]
	v_mfma_f32_16x16x32_bf16 v[72:75], v[150:153], v[234:237], v[72:75]
	v_mfma_f32_16x16x32_bf16 v[72:75], v[172:175], v[238:241], v[72:75]
	s_setprio 0
	s_setprio 1
	v_mfma_f32_16x16x32_bf16 v[116:119], v[176:179], v[192:195], v[116:119]
	v_mfma_f32_16x16x32_bf16 v[116:119], v[180:183], v[196:199], v[116:119]
	v_mfma_f32_16x16x32_bf16 v[112:115], v[184:187], v[192:195], v[112:115]
	v_mfma_f32_16x16x32_bf16 v[112:115], v[188:191], v[196:199], v[112:115]
	v_mfma_f32_16x16x32_bf16 v[100:103], v[176:179], v[200:203], v[100:103]
	v_mfma_f32_16x16x32_bf16 v[100:103], v[180:183], v[208:211], v[100:103]
	v_mfma_f32_16x16x32_bf16 v[96:99], v[184:187], v[200:203], v[96:99]
	v_mfma_f32_16x16x32_bf16 v[96:99], v[188:191], v[208:211], v[96:99]
	v_mfma_f32_16x16x32_bf16 v[84:87], v[176:179], v[214:217], v[84:87]
	v_mfma_f32_16x16x32_bf16 v[84:87], v[180:183], v[230:233], v[84:87]
	v_mfma_f32_16x16x32_bf16 v[80:83], v[184:187], v[214:217], v[80:83]
	v_mfma_f32_16x16x32_bf16 v[80:83], v[188:191], v[230:233], v[80:83]
	v_mfma_f32_16x16x32_bf16 v[68:71], v[176:179], v[234:237], v[68:71]
	v_mfma_f32_16x16x32_bf16 v[68:71], v[180:183], v[238:241], v[68:71]
	v_mfma_f32_16x16x32_bf16 v[64:67], v[184:187], v[234:237], v[64:67]
	v_mfma_f32_16x16x32_bf16 v[64:67], v[188:191], v[238:241], v[64:67]
	s_setprio 0
	s_barrier
; #define PG8_STAGE(bufoff, gbase, voff) do { _Pragma("unroll") for (int _i = 0; _i < 2; ++_i) \
;         __builtin_amdgcn_global_load_lds((const unsigned*)((const char*)(gbase) + (voff)[_i]), (LAS unsigned*)(lds + (bufoff) + ldsw + _i * 8192), 16, 0, 0); } while (0)
; #define PG8_LDA(dst, b, h) do { _Pragma("unroll") for (int m = 0; m < 4; ++m) _Pragma("unroll") for (int k = 0; k < 2; ++k) dst[m][k] = *(const LAS bf16x8*)(lds + PG8_SA(b, h) + aoff + m * 2048 + k * 1024); } while (0)
; #define PG8_MMA(ai, bj, At, Bt) do { __builtin_amdgcn_s_setprio(1); _Pragma("unroll") for (int m = 0; m < 4; ++m) _Pragma("unroll") for (int n = 0; n < 2; ++n) _Pragma("unroll") for (int k = 0; k < 2; ++k) \
;         acc[ai][bj][m][n] = __builtin_amdgcn_mfma_f32_16x16x32_bf16(Bt[n][k], At[m][k], acc[ai][bj][m][n], 0, 0, 0); __builtin_amdgcn_s_setprio(0); } while (0)
; #define PG8_WAIT_V(n) asm volatile("s_waitcnt vmcnt(" #n ")" ::: "memory")
; #define PG8_WAIT_L(n) asm volatile("s_waitcnt lgkmcnt(" #n ")" ::: "memory")
; #define PG8_BAR __builtin_amdgcn_s_barrier()
; #define PG8_SCHED __builtin_amdgcn_sched_barrier(0)
;     ...
;             PG8_LDA(At, 1, 1); PG8_STAGE(PG8_SB(1, 0), b3, voffB); PG8_STAGE(PG8_SB(1, 1), b3 + hB, voffB); PG8_STAGE(PG8_SA(1, 0), a3, voffA);
;             PG8_WAIT_V(8); PG8_WAIT_L(0); PG8_BAR; PG8_MMA(1, 0, At, B0); PG8_MMA(1, 1, At, B1); PG8_BAR; PG8_SCHED;
;     ...
;         }
;         if constexpr (ALIGN_EPI) { if (wr == 0) PG8_BAR; }
	s_add_i32 s8, s8, s81
	s_add_u32 s98, s100, s38
	s_addc_u32 s99, s101, s39
	s_add_u32 s100, s98, s16
	s_addc_u32 s101, s99, 0
	s_mov_b32 m0, s8
	ds_read_b128 v[192:195], v170 offset:49152
	ds_read_b128 v[196:199], v170 offset:50176
	ds_read_b128 v[200:203], v170 offset:51200
	ds_read_b128 v[208:211], v170 offset:52224
	ds_read_b128 v[214:217], v170 offset:53248
	ds_read_b128 v[230:233], v170 offset:54272
	ds_read_b128 v[234:237], v170 offset:55296
	ds_read_b128 v[238:241], v170 offset:56320
	global_load_lds_dwordx4 v156, s[98:99]
	s_add_i32 m0, s8, 0x2000
	s_add_i32 s8, s9, s81
	global_load_lds_dwordx4 v140, s[98:99]
	s_mov_b32 m0, s8
	s_nop 0
	global_load_lds_dwordx4 v156, s[100:101]
	s_add_i32 m0, s8, 0x2000
	s_nop 0
	global_load_lds_dwordx4 v140, s[100:101]
	s_mov_b32 m0, s1
	s_nop 0
	global_load_lds_dwordx4 v136, s[74:75]
	s_mov_b32 m0, s54
	s_nop 0
	global_load_lds_dwordx4 v138, s[74:75]
	s_waitcnt vmcnt(8)
	s_waitcnt lgkmcnt(0)
	s_barrier
	s_setprio 1
	s_waitcnt lgkmcnt(0)
	v_mfma_f32_16x16x32_bf16 v[60:63], v[132:135], v[192:195], v[60:63]
	v_mfma_f32_16x16x32_bf16 v[60:63], v[146:149], v[196:199], v[60:63]
	v_mfma_f32_16x16x32_bf16 v[56:59], v[150:153], v[192:195], v[56:59]
	v_mfma_f32_16x16x32_bf16 v[56:59], v[172:175], v[196:199], v[56:59]
	v_mfma_f32_16x16x32_bf16 v[44:47], v[132:135], v[200:203], v[44:47]
	v_mfma_f32_16x16x32_bf16 v[44:47], v[146:149], v[208:211], v[44:47]
	v_mfma_f32_16x16x32_bf16 v[40:43], v[150:153], v[200:203], v[40:43]
	v_mfma_f32_16x16x32_bf16 v[40:43], v[172:175], v[208:211], v[40:43]
	v_mfma_f32_16x16x32_bf16 v[28:31], v[132:135], v[214:217], v[28:31]
	v_mfma_f32_16x16x32_bf16 v[28:31], v[146:149], v[230:233], v[28:31]
	v_mfma_f32_16x16x32_bf16 v[24:27], v[150:153], v[214:217], v[24:27]
	v_mfma_f32_16x16x32_bf16 v[24:27], v[172:175], v[230:233], v[24:27]
	v_mfma_f32_16x16x32_bf16 v[12:15], v[132:135], v[234:237], v[12:15]
	v_mfma_f32_16x16x32_bf16 v[12:15], v[146:149], v[238:241], v[12:15]
	v_mfma_f32_16x16x32_bf16 v[8:11], v[150:153], v[234:237], v[8:11]
	v_mfma_f32_16x16x32_bf16 v[8:11], v[172:175], v[238:241], v[8:11]
	s_setprio 0
	s_setprio 1
	v_mfma_f32_16x16x32_bf16 v[52:55], v[176:179], v[192:195], v[52:55]
	v_mfma_f32_16x16x32_bf16 v[52:55], v[180:183], v[196:199], v[52:55]
	v_mfma_f32_16x16x32_bf16 v[48:51], v[184:187], v[192:195], v[48:51]
	v_mfma_f32_16x16x32_bf16 v[48:51], v[188:191], v[196:199], v[48:51]
	v_mfma_f32_16x16x32_bf16 v[36:39], v[176:179], v[200:203], v[36:39]
	v_mfma_f32_16x16x32_bf16 v[36:39], v[180:183], v[208:211], v[36:39]
	v_mfma_f32_16x16x32_bf16 v[32:35], v[184:187], v[200:203], v[32:35]
	v_mfma_f32_16x16x32_bf16 v[32:35], v[188:191], v[208:211], v[32:35]
	v_mfma_f32_16x16x32_bf16 v[20:23], v[176:179], v[214:217], v[20:23]
	v_mfma_f32_16x16x32_bf16 v[20:23], v[180:183], v[230:233], v[20:23]
	v_mfma_f32_16x16x32_bf16 v[16:19], v[184:187], v[214:217], v[16:19]
	v_mfma_f32_16x16x32_bf16 v[16:19], v[188:191], v[230:233], v[16:19]
	v_mfma_f32_16x16x32_bf16 v[4:7], v[176:179], v[234:237], v[4:7]
	v_mfma_f32_16x16x32_bf16 v[4:7], v[180:183], v[238:241], v[4:7]
	v_mfma_f32_16x16x32_bf16 v[0:3], v[184:187], v[234:237], v[0:3]
	v_mfma_f32_16x16x32_bf16 v[0:3], v[188:191], v[238:241], v[0:3]
	s_setprio 0
	s_barrier
	s_add_u32 vcc_lo, vcc_lo, 0x100
	s_addc_u32 vcc_hi, vcc_hi, 0
	s_cmp_ge_u32 s6, s4
	s_mov_b32 s74, s6
	s_cbranch_scc0 .LBB0_364
	s_and_b64 vcc, exec, s[30:31]
	s_cbranch_vccz .LBB0_367
	s_barrier

; #define PG8_STAGE(bufoff, gbase, voff) do { _Pragma("unroll") for (int _i = 0; _i < 2; ++_i) \
;         __builtin_amdgcn_global_load_lds((const unsigned*)((const char*)(gbase) + (voff)[_i]), (LAS unsigned*)(lds + (bufoff) + ldsw + _i * 8192), 16, 0, 0); } while (0)
; #define PG8_LDA(dst, b, h) do { _Pragma("unroll") for (int m = 0; m < 4; ++m) _Pragma("unroll") for (int k = 0; k < 2; ++k) dst[m][k] = *(const LAS bf16x8*)(lds + PG8_SA(b, h) + aoff + m * 2048 + k * 1024); } while (0)
; #define PG8_LDB(dst, b, h) do { _Pragma("unroll") for (int n = 0; n < 2; ++n) _Pragma("unroll") for (int k = 0; k < 2; ++k) dst[n][k] = *(const LAS bf16x8*)(lds + PG8_SB(b, h) + boff + n * 2048 + k * 1024); } while (0)
; #define PG8_MMA(ai, bj, At, Bt) do { __builtin_amdgcn_s_setprio(1); _Pragma("unroll") for (int m = 0; m < 4; ++m) _Pragma("unroll") for (int n = 0; n < 2; ++n) _Pragma("unroll") for (int k = 0; k < 2; ++k) \
;         acc[ai][bj][m][n] = __builtin_amdgcn_mfma_f32_16x16x32_bf16(Bt[n][k], At[m][k], acc[ai][bj][m][n], 0, 0, 0); __builtin_amdgcn_s_setprio(0); } while (0)
; #define PG8_WAIT_V(n) asm volatile("s_waitcnt vmcnt(" #n ")" ::: "memory")
; #define PG8_WAIT_L(n) asm volatile("s_waitcnt lgkmcnt(" #n ")" ::: "memory")
; #define PG8_BAR __builtin_amdgcn_s_barrier()
; #define PG8_SCHED __builtin_amdgcn_sched_barrier(0)
;     ...
;             const bool last = (t == nt - 2);
;             const char* a1 = PG8_ATILE(cA, cA2, t + 1);
;             const char* a2 = last ? nA : PG8_ATILE(cA, cA2, t + 2); const char* b2 = last ? nB : cB + (size_t)(t + 2) * 128;
;             const char* a3 = last ? nA + kA1 : PG8_ATILE(cA, cA2, t + 3); const char* b3 = b2 + kB1;
;             if constexpr (SP2) {
;             PG8_LDB(B0, 0, 0); PG8_LDB(B1, 0, 1); PG8_SCHED; PG8_LDA(At, 0, 0); PG8_STAGE(PG8_SA(1, 1), a1 + hA, voffA);
;             PG8_WAIT_V(8); PG8_WAIT_L(0); PG8_BAR; PG8_MMA(0, 0, At, B0); PG8_MMA(0, 1, At, B1); PG8_BAR; PG8_SCHED;
;             PG8_LDA(At, 0, 1); PG8_STAGE(PG8_SB(0, 0), b2, voffB); PG8_STAGE(PG8_SB(0, 1), b2 + hB, voffB); PG8_STAGE(PG8_SA(0, 0), a2, voffA);
;             PG8_WAIT_V(8); PG8_WAIT_L(0); PG8_BAR; PG8_MMA(1, 0, At, B0); PG8_MMA(1, 1, At, B1); PG8_BAR; PG8_SCHED;
.LBB0_406:
	s_add_u32 s42, s30, s34
	s_addc_u32 s43, s31, s35
	s_add_u32 s48, s42, 0x100
	s_addc_u32 s49, s43, 0
	s_add_u32 s44, s74, s34
	s_addc_u32 s45, s75, s35
	s_add_u32 s42, s42, 0x180
	s_addc_u32 s43, s43, 0
	s_add_i32 s77, 0, 0x10000
	s_add_i32 s80, 0, 0x14000
	v_add_u32_e32 v144, s77, v179
	v_add_u32_e32 v178, s80, v179
	ds_read_b128 v[132:135], v144
	ds_read_b128 v[136:139], v144 offset:1024
	ds_read_b128 v[140:143], v144 offset:2048
	ds_read_b128 v[144:147], v144 offset:3072
	ds_read_b128 v[148:151], v178
	ds_read_b128 v[186:189], v178 offset:1024
	ds_read_b128 v[190:193], v178 offset:2048
	ds_read_b128 v[194:197], v178 offset:3072
	s_cmpk_eq_i32 s34, 0x700
	s_cselect_b32 s43, s73, s43
	s_cselect_b32 s42, s72, s42
	s_cselect_b32 s45, s17, s45
	s_cselect_b32 s44, s55, s44
	s_cselect_b32 s49, s3, s49
	s_cselect_b32 s48, s25, s48
	v_lshl_add_u64 v[182:183], v[128:129], 0, s[34:35]
	s_add_i32 m0, s6, 0xc000
	ds_read_b128 v[208:211], v181
	ds_read_b128 v[230:233], v181 offset:1024
	ds_read_b128 v[234:237], v181 offset:2048
	ds_read_b128 v[238:241], v181 offset:3072
	ds_read_b128 v[242:245], v181 offset:4096
	ds_read_b128 v[246:249], v181 offset:5120
	ds_read_b128 v[214:217], v181 offset:6144
	ds_read_b128 v[198:201], v181 offset:7168
	global_load_lds_dwordx4 v[182:183], off
	v_lshl_add_u64 v[182:183], v[130:131], 0, s[34:35]
	s_add_i32 m0, s6, 0xe000
	s_nop 0
	global_load_lds_dwordx4 v[182:183], off
	s_waitcnt vmcnt(8)
	s_waitcnt lgkmcnt(0)
	s_barrier
	s_setprio 1
	s_waitcnt lgkmcnt(0)
	v_mfma_f32_16x16x32_bf16 v[124:127], v[132:135], v[208:211], v[124:127]
	v_mfma_f32_16x16x32_bf16 v[124:127], v[136:139], v[230:233], v[124:127]
	v_mfma_f32_16x16x32_bf16 v[120:123], v[140:143], v[208:211], v[120:123]
	v_mfma_f32_16x16x32_bf16 v[120:123], v[144:147], v[230:233], v[120:123]
	v_mfma_f32_16x16x32_bf16 v[108:111], v[132:135], v[234:237], v[108:111]
	v_mfma_f32_16x16x32_bf16 v[108:111], v[136:139], v[238:241], v[108:111]
	v_mfma_f32_16x16x32_bf16 v[104:107], v[140:143], v[234:237], v[104:107]
	v_mfma_f32_16x16x32_bf16 v[104:107], v[144:147], v[238:241], v[104:107]
	v_mfma_f32_16x16x32_bf16 v[92:95], v[132:135], v[242:245], v[92:95]
	v_mfma_f32_16x16x32_bf16 v[92:95], v[136:139], v[246:249], v[92:95]
	v_mfma_f32_16x16x32_bf16 v[88:91], v[140:143], v[242:245], v[88:91]
	v_mfma_f32_16x16x32_bf16 v[88:91], v[144:147], v[246:249], v[88:91]
	v_mfma_f32_16x16x32_bf16 v[76:79], v[132:135], v[214:217], v[76:79]
	v_mfma_f32_16x16x32_bf16 v[76:79], v[136:139], v[198:201], v[76:79]
	v_mfma_f32_16x16x32_bf16 v[72:75], v[140:143], v[214:217], v[72:75]
	v_mfma_f32_16x16x32_bf16 v[72:75], v[144:147], v[198:201], v[72:75]
	s_setprio 0
	s_setprio 1
	v_mfma_f32_16x16x32_bf16 v[116:119], v[148:151], v[208:211], v[116:119]
	v_mfma_f32_16x16x32_bf16 v[116:119], v[186:189], v[230:233], v[116:119]
	v_mfma_f32_16x16x32_bf16 v[112:115], v[190:193], v[208:211], v[112:115]
	v_mfma_f32_16x16x32_bf16 v[112:115], v[194:197], v[230:233], v[112:115]
	v_mfma_f32_16x16x32_bf16 v[100:103], v[148:151], v[234:237], v[100:103]
	v_mfma_f32_16x16x32_bf16 v[100:103], v[186:189], v[238:241], v[100:103]
	v_mfma_f32_16x16x32_bf16 v[96:99], v[190:193], v[234:237], v[96:99]
	v_mfma_f32_16x16x32_bf16 v[96:99], v[194:197], v[238:241], v[96:99]
	v_mfma_f32_16x16x32_bf16 v[84:87], v[148:151], v[242:245], v[84:87]
	v_mfma_f32_16x16x32_bf16 v[84:87], v[186:189], v[246:249], v[84:87]
	v_mfma_f32_16x16x32_bf16 v[80:83], v[190:193], v[242:245], v[80:83]
	v_mfma_f32_16x16x32_bf16 v[80:83], v[194:197], v[246:249], v[80:83]
	v_mfma_f32_16x16x32_bf16 v[68:71], v[148:151], v[214:217], v[68:71]
	v_mfma_f32_16x16x32_bf16 v[68:71], v[186:189], v[198:201], v[68:71]
	v_mfma_f32_16x16x32_bf16 v[64:67], v[190:193], v[214:217], v[64:67]
	v_mfma_f32_16x16x32_bf16 v[64:67], v[194:197], v[198:201], v[64:67]
	s_setprio 0
	s_barrier
	s_add_i32 s77, s77, s5
	v_lshl_add_u64 v[182:183], s[44:45], 0, v[156:157]
	s_mov_b32 m0, s77
	ds_read_b128 v[198:201], v181 offset:16384
	ds_read_b128 v[208:211], v181 offset:17408
	ds_read_b128 v[214:217], v181 offset:18432
	ds_read_b128 v[230:233], v181 offset:19456
	ds_read_b128 v[234:237], v181 offset:20480
	ds_read_b128 v[238:241], v181 offset:21504
	ds_read_b128 v[242:245], v181 offset:22528
	ds_read_b128 v[246:249], v181 offset:23552
	global_load_lds_dwordx4 v[182:183], off
	s_add_i32 m0, s77, 0x2000
	s_add_u32 s78, s44, 0x40000
	v_lshl_add_u64 v[202:203], s[44:45], 0, v[168:169]
	s_addc_u32 s79, s45, 0
	s_add_i32 s77, s80, s5
	global_load_lds_dwordx4 v[202:203], off
	v_lshl_add_u64 v[204:205], s[78:79], 0, v[156:157]
	s_mov_b32 m0, s77
	s_nop 0
	global_load_lds_dwordx4 v[204:205], off
	v_lshl_add_u64 v[204:205], s[78:79], 0, v[168:169]
	s_add_i32 m0, s77, 0x2000
	s_nop 0
	global_load_lds_dwordx4 v[204:205], off
	v_lshl_add_u64 v[204:205], s[48:49], 0, v[152:153]
	s_mov_b32 m0, s6
	s_nop 0
	global_load_lds_dwordx4 v[204:205], off
	v_lshl_add_u64 v[204:205], s[48:49], 0, v[154:155]
	s_mov_b32 m0, s7
	s_nop 0
	global_load_lds_dwordx4 v[204:205], off
	s_waitcnt vmcnt(8)
	s_waitcnt lgkmcnt(0)
	s_barrier
; #define PG8_STAGE(bufoff, gbase, voff) do { _Pragma("unroll") for (int _i = 0; _i < 2; ++_i) \
;         __builtin_amdgcn_global_load_lds((const unsigned*)((const char*)(gbase) + (voff)[_i]), (LAS unsigned*)(lds + (bufoff) + ldsw + _i * 8192), 16, 0, 0); } while (0)
; #define PG8_LDA(dst, b, h) do { _Pragma("unroll") for (int m = 0; m < 4; ++m) _Pragma("unroll") for (int k = 0; k < 2; ++k) dst[m][k] = *(const LAS bf16x8*)(lds + PG8_SA(b, h) + aoff + m * 2048 + k * 1024); } while (0)
; #define PG8_LDB(dst, b, h) do { _Pragma("unroll") for (int n = 0; n < 2; ++n) _Pragma("unroll") for (int k = 0; k < 2; ++k) dst[n][k] = *(const LAS bf16x8*)(lds + PG8_SB(b, h) + boff + n * 2048 + k * 1024); } while (0)
; #define PG8_MMA(ai, bj, At, Bt) do { __builtin_amdgcn_s_setprio(1); _Pragma("unroll") for (int m = 0; m < 4; ++m) _Pragma("unroll") for (int n = 0; n < 2; ++n) _Pragma("unroll") for (int k = 0; k < 2; ++k) \
;         acc[ai][bj][m][n] = __builtin_amdgcn_mfma_f32_16x16x32_bf16(Bt[n][k], At[m][k], acc[ai][bj][m][n], 0, 0, 0); __builtin_amdgcn_s_setprio(0); } while (0)
; #define PG8_WAIT_V(n) asm volatile("s_waitcnt vmcnt(" #n ")" ::: "memory")
; #define PG8_WAIT_L(n) asm volatile("s_waitcnt lgkmcnt(" #n ")" ::: "memory")
; #define PG8_BAR __builtin_amdgcn_s_barrier()
; #define PG8_SCHED __builtin_amdgcn_sched_barrier(0)
;     ...
;             PG8_WAIT_V(8); PG8_WAIT_L(0); PG8_BAR; PG8_MMA(1, 0, At, B0); PG8_MMA(1, 1, At, B1); PG8_BAR; PG8_SCHED;
;             PG8_LDB(B0, 1, 0); PG8_LDB(B1, 1, 1); PG8_SCHED; PG8_LDA(At, 1, 0); PG8_STAGE(PG8_SA(0, 1), a2 + hA, voffA);
;             PG8_WAIT_V(8); PG8_WAIT_L(0); PG8_BAR; PG8_MMA(0, 0, At, B0); PG8_MMA(0, 1, At, B1); PG8_BAR; PG8_SCHED;
	s_setprio 1
	s_waitcnt lgkmcnt(0)
	v_mfma_f32_16x16x32_bf16 v[60:63], v[132:135], v[198:201], v[60:63]
	v_mfma_f32_16x16x32_bf16 v[60:63], v[136:139], v[208:211], v[60:63]
	v_mfma_f32_16x16x32_bf16 v[56:59], v[140:143], v[198:201], v[56:59]
	v_mfma_f32_16x16x32_bf16 v[56:59], v[144:147], v[208:211], v[56:59]
	v_mfma_f32_16x16x32_bf16 v[44:47], v[132:135], v[214:217], v[44:47]
	v_mfma_f32_16x16x32_bf16 v[44:47], v[136:139], v[230:233], v[44:47]
	v_mfma_f32_16x16x32_bf16 v[40:43], v[140:143], v[214:217], v[40:43]
	v_mfma_f32_16x16x32_bf16 v[40:43], v[144:147], v[230:233], v[40:43]
	v_mfma_f32_16x16x32_bf16 v[28:31], v[132:135], v[234:237], v[28:31]
	v_mfma_f32_16x16x32_bf16 v[28:31], v[136:139], v[238:241], v[28:31]
	v_mfma_f32_16x16x32_bf16 v[24:27], v[140:143], v[234:237], v[24:27]
	v_mfma_f32_16x16x32_bf16 v[24:27], v[144:147], v[238:241], v[24:27]
	v_mfma_f32_16x16x32_bf16 v[12:15], v[132:135], v[242:245], v[12:15]
	v_mfma_f32_16x16x32_bf16 v[12:15], v[136:139], v[246:249], v[12:15]
	v_mfma_f32_16x16x32_bf16 v[8:11], v[140:143], v[242:245], v[8:11]
	v_mfma_f32_16x16x32_bf16 v[8:11], v[144:147], v[246:249], v[8:11]
	s_setprio 0
	s_setprio 1
	v_mfma_f32_16x16x32_bf16 v[52:55], v[148:151], v[198:201], v[52:55]
	v_mfma_f32_16x16x32_bf16 v[52:55], v[186:189], v[208:211], v[52:55]
	v_mfma_f32_16x16x32_bf16 v[48:51], v[190:193], v[198:201], v[48:51]
	v_mfma_f32_16x16x32_bf16 v[48:51], v[194:197], v[208:211], v[48:51]
	v_mfma_f32_16x16x32_bf16 v[36:39], v[148:151], v[214:217], v[36:39]
	v_mfma_f32_16x16x32_bf16 v[36:39], v[186:189], v[230:233], v[36:39]
	v_mfma_f32_16x16x32_bf16 v[32:35], v[190:193], v[214:217], v[32:35]
	v_mfma_f32_16x16x32_bf16 v[32:35], v[194:197], v[230:233], v[32:35]
	v_mfma_f32_16x16x32_bf16 v[20:23], v[148:151], v[234:237], v[20:23]
	v_mfma_f32_16x16x32_bf16 v[20:23], v[186:189], v[238:241], v[20:23]
	v_mfma_f32_16x16x32_bf16 v[16:19], v[190:193], v[234:237], v[16:19]
	v_mfma_f32_16x16x32_bf16 v[16:19], v[194:197], v[238:241], v[16:19]
	v_mfma_f32_16x16x32_bf16 v[4:7], v[148:151], v[242:245], v[4:7]
	v_mfma_f32_16x16x32_bf16 v[4:7], v[186:189], v[246:249], v[4:7]
	v_mfma_f32_16x16x32_bf16 v[0:3], v[190:193], v[242:245], v[0:3]
	v_mfma_f32_16x16x32_bf16 v[0:3], v[194:197], v[246:249], v[0:3]
	s_setprio 0
	s_barrier
	s_add_i32 s77, 0, 0x18000
	s_add_i32 s78, 0, 0x1c000
	v_add_u32_e32 v144, s77, v179
	v_add_u32_e32 v178, s78, v179
	ds_read_b128 v[132:135], v144
	ds_read_b128 v[136:139], v144 offset:1024
	ds_read_b128 v[140:143], v144 offset:2048
	ds_read_b128 v[144:147], v144 offset:3072
	ds_read_b128 v[148:151], v178
	ds_read_b128 v[186:189], v178 offset:1024
	ds_read_b128 v[190:193], v178 offset:2048
	ds_read_b128 v[194:197], v178 offset:3072
	s_add_u32 s48, s48, 0x40000
	s_addc_u32 s49, s49, 0
	s_mov_b32 m0, s8
	v_lshl_add_u64 v[204:205], s[48:49], 0, v[152:153]
	ds_read_b128 v[198:201], v181 offset:32768
	ds_read_b128 v[208:211], v181 offset:33792
	ds_read_b128 v[214:217], v181 offset:34816
	ds_read_b128 v[230:233], v181 offset:35840
	ds_read_b128 v[234:237], v181 offset:36864
	ds_read_b128 v[238:241], v181 offset:37888
	ds_read_b128 v[242:245], v181 offset:38912
	ds_read_b128 v[246:249], v181 offset:39936
	global_load_lds_dwordx4 v[204:205], off
	v_lshl_add_u64 v[204:205], s[48:49], 0, v[154:155]
	s_mov_b32 m0, s9
	s_nop 0
	global_load_lds_dwordx4 v[204:205], off
	s_waitcnt vmcnt(8)
	s_waitcnt lgkmcnt(0)
	s_barrier
	s_setprio 1
	s_waitcnt lgkmcnt(0)
	v_mfma_f32_16x16x32_bf16 v[124:127], v[132:135], v[198:201], v[124:127]
	v_mfma_f32_16x16x32_bf16 v[124:127], v[136:139], v[208:211], v[124:127]
	v_mfma_f32_16x16x32_bf16 v[120:123], v[140:143], v[198:201], v[120:123]
	v_mfma_f32_16x16x32_bf16 v[120:123], v[144:147], v[208:211], v[120:123]
	v_mfma_f32_16x16x32_bf16 v[108:111], v[132:135], v[214:217], v[108:111]
	v_mfma_f32_16x16x32_bf16 v[108:111], v[136:139], v[230:233], v[108:111]
	v_mfma_f32_16x16x32_bf16 v[104:107], v[140:143], v[214:217], v[104:107]
	v_mfma_f32_16x16x32_bf16 v[104:107], v[144:147], v[230:233], v[104:107]
	v_mfma_f32_16x16x32_bf16 v[92:95], v[132:135], v[234:237], v[92:95]
	v_mfma_f32_16x16x32_bf16 v[92:95], v[136:139], v[238:241], v[92:95]
	v_mfma_f32_16x16x32_bf16 v[88:91], v[140:143], v[234:237], v[88:91]
	v_mfma_f32_16x16x32_bf16 v[88:91], v[144:147], v[238:241], v[88:91]
	v_mfma_f32_16x16x32_bf16 v[76:79], v[132:135], v[242:245], v[76:79]
	v_mfma_f32_16x16x32_bf16 v[76:79], v[136:139], v[246:249], v[76:79]
	v_mfma_f32_16x16x32_bf16 v[72:75], v[140:143], v[242:245], v[72:75]
	v_mfma_f32_16x16x32_bf16 v[72:75], v[144:147], v[246:249], v[72:75]
	s_setprio 0
	s_setprio 1
	v_mfma_f32_16x16x32_bf16 v[116:119], v[148:151], v[198:201], v[116:119]
	v_mfma_f32_16x16x32_bf16 v[116:119], v[186:189], v[208:211], v[116:119]
	v_mfma_f32_16x16x32_bf16 v[112:115], v[190:193], v[198:201], v[112:115]
	v_mfma_f32_16x16x32_bf16 v[112:115], v[194:197], v[208:211], v[112:115]
	v_mfma_f32_16x16x32_bf16 v[100:103], v[148:151], v[214:217], v[100:103]
	v_mfma_f32_16x16x32_bf16 v[100:103], v[186:189], v[230:233], v[100:103]
	v_mfma_f32_16x16x32_bf16 v[96:99], v[190:193], v[214:217], v[96:99]
	v_mfma_f32_16x16x32_bf16 v[96:99], v[194:197], v[230:233], v[96:99]
	v_mfma_f32_16x16x32_bf16 v[84:87], v[148:151], v[234:237], v[84:87]
	v_mfma_f32_16x16x32_bf16 v[84:87], v[186:189], v[238:241], v[84:87]
	v_mfma_f32_16x16x32_bf16 v[80:83], v[190:193], v[234:237], v[80:83]
	v_mfma_f32_16x16x32_bf16 v[80:83], v[194:197], v[238:241], v[80:83]
	v_mfma_f32_16x16x32_bf16 v[68:71], v[148:151], v[242:245], v[68:71]
	v_mfma_f32_16x16x32_bf16 v[68:71], v[186:189], v[246:249], v[68:71]
	v_mfma_f32_16x16x32_bf16 v[64:67], v[190:193], v[242:245], v[64:67]
	v_mfma_f32_16x16x32_bf16 v[64:67], v[194:197], v[246:249], v[64:67]
	s_setprio 0
	s_barrier
; #define PG8_STAGE(bufoff, gbase, voff) do { _Pragma("unroll") for (int _i = 0; _i < 2; ++_i) \
;         __builtin_amdgcn_global_load_lds((const unsigned*)((const char*)(gbase) + (voff)[_i]), (LAS unsigned*)(lds + (bufoff) + ldsw + _i * 8192), 16, 0, 0); } while (0)
; #define PG8_LDA(dst, b, h) do { _Pragma("unroll") for (int m = 0; m < 4; ++m) _Pragma("unroll") for (int k = 0; k < 2; ++k) dst[m][k] = *(const LAS bf16x8*)(lds + PG8_SA(b, h) + aoff + m * 2048 + k * 1024); } while (0)
; #define PG8_MMA(ai, bj, At, Bt) do { __builtin_amdgcn_s_setprio(1); _Pragma("unroll") for (int m = 0; m < 4; ++m) _Pragma("unroll") for (int n = 0; n < 2; ++n) _Pragma("unroll") for (int k = 0; k < 2; ++k) \
;         acc[ai][bj][m][n] = __builtin_amdgcn_mfma_f32_16x16x32_bf16(Bt[n][k], At[m][k], acc[ai][bj][m][n], 0, 0, 0); __builtin_amdgcn_s_setprio(0); } while (0)
; #define PG8_WAIT_V(n) asm volatile("s_waitcnt vmcnt(" #n ")" ::: "memory")
; #define PG8_WAIT_L(n) asm volatile("s_waitcnt lgkmcnt(" #n ")" ::: "memory")
; #define PG8_BAR __builtin_amdgcn_s_barrier()
; #define PG8_SCHED __builtin_amdgcn_sched_barrier(0)
;     ...
;             PG8_LDA(At, 1, 1); PG8_STAGE(PG8_SB(1, 0), b3, voffB); PG8_STAGE(PG8_SB(1, 1), b3 + hB, voffB); PG8_STAGE(PG8_SA(1, 0), a3, voffA);
;             PG8_WAIT_V(8); PG8_WAIT_L(0); PG8_BAR; PG8_MMA(1, 0, At, B0); PG8_MMA(1, 1, At, B1); PG8_BAR; PG8_SCHED;
;     ...
;         }
;         if constexpr (ALIGN_EPI) { if (wr == 0) PG8_BAR; }
	s_add_i32 s48, s77, s5
	v_lshl_add_u64 v[182:183], v[182:183], 0, s[38:39]
	s_mov_b32 m0, s48
	ds_read_b128 v[198:201], v181 offset:49152
	ds_read_b128 v[208:211], v181 offset:50176
	ds_read_b128 v[214:217], v181 offset:51200
	ds_read_b128 v[230:233], v181 offset:52224
	ds_read_b128 v[234:237], v181 offset:53248
	ds_read_b128 v[238:241], v181 offset:54272
	ds_read_b128 v[242:245], v181 offset:55296
	ds_read_b128 v[246:249], v181 offset:56320
	global_load_lds_dwordx4 v[182:183], off
	s_add_i32 m0, s48, 0x2000
	s_add_u32 s44, s44, 0x40080
	v_lshl_add_u64 v[182:183], v[202:203], 0, s[38:39]
	s_addc_u32 s45, s45, 0
	s_add_i32 s48, s78, s5
	global_load_lds_dwordx4 v[182:183], off
	v_lshl_add_u64 v[182:183], s[44:45], 0, v[156:157]
	s_mov_b32 m0, s48
	s_nop 0
	global_load_lds_dwordx4 v[182:183], off
	v_lshl_add_u64 v[182:183], s[44:45], 0, v[168:169]
	s_add_i32 m0, s48, 0x2000
	s_nop 0
	global_load_lds_dwordx4 v[182:183], off
	v_lshl_add_u64 v[182:183], s[42:43], 0, v[152:153]
	s_mov_b32 m0, s50
	s_nop 0
	global_load_lds_dwordx4 v[182:183], off
	v_lshl_add_u64 v[182:183], s[42:43], 0, v[154:155]
	s_mov_b32 m0, s51
	s_nop 0
	global_load_lds_dwordx4 v[182:183], off
	s_waitcnt vmcnt(8)
	s_waitcnt lgkmcnt(0)
	s_barrier
	s_setprio 1
	s_waitcnt lgkmcnt(0)
	v_mfma_f32_16x16x32_bf16 v[60:63], v[132:135], v[198:201], v[60:63]
	v_mfma_f32_16x16x32_bf16 v[60:63], v[136:139], v[208:211], v[60:63]
	v_mfma_f32_16x16x32_bf16 v[56:59], v[140:143], v[198:201], v[56:59]
	v_mfma_f32_16x16x32_bf16 v[56:59], v[144:147], v[208:211], v[56:59]
	v_mfma_f32_16x16x32_bf16 v[44:47], v[132:135], v[214:217], v[44:47]
	v_mfma_f32_16x16x32_bf16 v[44:47], v[136:139], v[230:233], v[44:47]
	v_mfma_f32_16x16x32_bf16 v[40:43], v[140:143], v[214:217], v[40:43]
	v_mfma_f32_16x16x32_bf16 v[40:43], v[144:147], v[230:233], v[40:43]
	v_mfma_f32_16x16x32_bf16 v[28:31], v[132:135], v[234:237], v[28:31]
	v_mfma_f32_16x16x32_bf16 v[28:31], v[136:139], v[238:241], v[28:31]
	v_mfma_f32_16x16x32_bf16 v[24:27], v[140:143], v[234:237], v[24:27]
	v_mfma_f32_16x16x32_bf16 v[24:27], v[144:147], v[238:241], v[24:27]
	v_mfma_f32_16x16x32_bf16 v[12:15], v[132:135], v[242:245], v[12:15]
	v_mfma_f32_16x16x32_bf16 v[12:15], v[136:139], v[246:249], v[12:15]
	v_mfma_f32_16x16x32_bf16 v[8:11], v[140:143], v[242:245], v[8:11]
	v_mfma_f32_16x16x32_bf16 v[8:11], v[144:147], v[246:249], v[8:11]
	s_setprio 0
	s_setprio 1
	v_mfma_f32_16x16x32_bf16 v[52:55], v[148:151], v[198:201], v[52:55]
	v_mfma_f32_16x16x32_bf16 v[52:55], v[186:189], v[208:211], v[52:55]
	v_mfma_f32_16x16x32_bf16 v[48:51], v[190:193], v[198:201], v[48:51]
	v_mfma_f32_16x16x32_bf16 v[48:51], v[194:197], v[208:211], v[48:51]
	v_mfma_f32_16x16x32_bf16 v[36:39], v[148:151], v[214:217], v[36:39]
	v_mfma_f32_16x16x32_bf16 v[36:39], v[186:189], v[230:233], v[36:39]
	v_mfma_f32_16x16x32_bf16 v[32:35], v[190:193], v[214:217], v[32:35]
	v_mfma_f32_16x16x32_bf16 v[32:35], v[194:197], v[230:233], v[32:35]
	v_mfma_f32_16x16x32_bf16 v[20:23], v[148:151], v[234:237], v[20:23]
	v_mfma_f32_16x16x32_bf16 v[20:23], v[186:189], v[238:241], v[20:23]
	v_mfma_f32_16x16x32_bf16 v[16:19], v[190:193], v[234:237], v[16:19]
	v_mfma_f32_16x16x32_bf16 v[16:19], v[194:197], v[238:241], v[16:19]
	v_mfma_f32_16x16x32_bf16 v[4:7], v[148:151], v[242:245], v[4:7]
	v_mfma_f32_16x16x32_bf16 v[4:7], v[186:189], v[246:249], v[4:7]
	v_mfma_f32_16x16x32_bf16 v[0:3], v[190:193], v[242:245], v[0:3]
	v_mfma_f32_16x16x32_bf16 v[0:3], v[194:197], v[246:249], v[0:3]
	s_setprio 0
	s_barrier
	s_add_i32 s76, s76, 2
	s_add_u32 s34, s34, 0x100
	s_addc_u32 s35, s35, 0
	s_cmp_gt_u32 s76, 13
	s_cbranch_scc0 .LBB0_406
	s_and_b64 vcc, exec, s[14:15]
	s_cbranch_vccz .LBB0_409
	s_barrier
